# stacked: resid epilogue gamma/beta via DPP table and fewer waits, SGU loads hoisted, saddr LDS-DMA in two GEMM loops
# speedup vs baseline: 1.0091x; 1.0091x over previous
; #define LAS __attribute__((address_space(3)))
; __device__ __forceinline__ unsigned cvt_pk_bf16(float lo, float hi) { f32x2 v = {lo, hi}; bf16x2_t b = __builtin_convertvector(v, bf16x2_t); return __builtin_bit_cast(unsigned, b); }
; __device__ __forceinline__ float bf_lo(unsigned w) { return __uint_as_float(w << 16); }
; __device__ __forceinline__ float bf_hi(unsigned w) { return __uint_as_float(w & 0xffff0000u); }
; __device__ __forceinline__ void sgu_chunk(const Ctx& C, const Args& a, int l, int n) {
;     ...
;     for (int g = 0; g < 8; ++g) {
; #pragma unroll
;         for (int j = 0; j < 4; ++j) { const int p = C.tid + 512 * j, r = p >> 4, c8 = (p & 15) * 8; const f32x2 st = stats[r];
;             const u32x4 w = *(const u32x4*)(VB + (R0 + r) * D + g * 128 + c8); const f32x4 g0 = *(const f32x4*)(gam + g * 128 + c8), g1 = *(const f32x4*)(gam + g * 128 + c8 + 4);
;             const f32x4 b0 = *(const f32x4*)(bet + g * 128 + c8), b1 = *(const f32x4*)(bet + g * 128 + c8 + 4);
;             u32x4 o; o.x = cvt_pk_bf16((bf_lo(w.x) - st.x) * st.y * g0[0] + b0[0], (bf_hi(w.x) - st.x) * st.y * g0[1] + b0[1]);
;             o.y = cvt_pk_bf16((bf_lo(w.y) - st.x) * st.y * g0[2] + b0[2], (bf_hi(w.y) - st.x) * st.y * g0[3] + b0[3]);
;             o.z = cvt_pk_bf16((bf_lo(w.z) - st.x) * st.y * g1[0] + b1[0], (bf_hi(w.z) - st.x) * st.y * g1[1] + b1[1]);
;             o.w = cvt_pk_bf16((bf_lo(w.w) - st.x) * st.y * g1[2] + b1[2], (bf_hi(w.w) - st.x) * st.y * g1[3] + b1[3]);
;             *(LAS u32x4*)(vimg + (c8 >> 5) * 8192 + r * 64 + (c8 & 31) * 2) = o; }
;         __syncthreads();
;         f32x16 acc[2];
; #pragma unroll
;         for (int r = 0; r < 16; ++r) { acc[0][r] = 0.f; acc[1][r] = 0.f; }
;         const bf16_t* wrow = SW + ((size_t)g * 128 + 32 * tb + r32) * 128 + 4 * hi;
; #pragma unroll
;         for (int kc = 0; kc < 8; ++kc) {
;             const u32x2 alo = *(const u32x2*)(wrow + 16 * kc), ahi = *(const u32x2*)(wrow + 16 * kc + 8);
.LBB0_154:
	v_lshl_add_u64 v[78:79], s[86:87], 0, v[56:57]
	global_load_dwordx2 v[206:207], v[78:79], off offset:-128
	global_load_dwordx2 v[208:209], v[78:79], off offset:-112
	global_load_dwordx2 v[210:211], v[78:79], off offset:-96
	global_load_dwordx2 v[212:213], v[78:79], off offset:-80
	global_load_dwordx2 v[214:215], v[78:79], off offset:-64
	global_load_dwordx2 v[216:217], v[78:79], off offset:-48
	global_load_dwordx2 v[218:219], v[78:79], off offset:-32
	global_load_dwordx2 v[220:221], v[78:79], off offset:-16
	global_load_dwordx2 v[232:233], v[78:79], off offset:0
	global_load_dwordx2 v[234:235], v[78:79], off offset:16
	global_load_dwordx2 v[236:237], v[78:79], off offset:32
	global_load_dwordx2 v[238:239], v[78:79], off offset:48
	global_load_dwordx2 v[240:241], v[78:79], off offset:64
	global_load_dwordx2 v[242:243], v[78:79], off offset:80
	global_load_dwordx2 v[244:245], v[78:79], off offset:96
	global_load_dwordx2 v[246:247], v[78:79], off offset:112
	v_lshl_add_u64 v[176:177], s[86:87], 0, v[62:63]
	global_load_dwordx4 v[164:167], v[176:177], off
	v_lshl_add_u64 v[176:177], s[86:87], 0, v[60:61]
	global_load_dwordx4 v[168:171], v[176:177], off
	v_lshl_add_u64 v[176:177], s[86:87], 0, v[58:59]
	global_load_dwordx4 v[172:175], v[176:177], off
	v_lshl_add_u64 v[0:1], s[86:87], 0, v[64:65]
	global_load_dwordx4 v[16:19], v[0:1], off
	v_lshl_add_u64 v[0:1], v[52:53], 0, s[44:45]
	v_lshl_add_u64 v[8:9], v[54:55], 0, s[44:45]
	ds_read_b64 v[20:21], v68
	global_load_dwordx4 v[4:7], v[0:1], off offset:-16
	s_nop 0
	global_load_dwordx4 v[0:3], v[0:1], off
	s_nop 0
	global_load_dwordx4 v[12:15], v[8:9], off offset:-16
	s_nop 0
	global_load_dwordx4 v[8:11], v[8:9], off
	s_add_u32 s18, s24, s44
	s_addc_u32 s19, s25, s45
	s_mov_b32 s12, 0x5c00000
	v_lshl_add_u64 v[64:65], v[64:65], 0, s[14:15]
	v_lshl_add_u64 v[56:57], v[56:57], 0, s[94:95]
	s_waitcnt vmcnt(4)
	v_lshlrev_b32_e32 v22, 16, v16
	v_and_b32_e32 v23, 0xffff0000, v16
	s_waitcnt lgkmcnt(0)
	v_pk_add_f32 v[22:23], v[22:23], v[20:21] op_sel_hi:[1,0] neg_lo:[0,1] neg_hi:[0,1]
	s_nop 0
	v_pk_mul_f32 v[22:23], v[20:21], v[22:23] op_sel:[1,0]
	s_waitcnt vmcnt(1)
	v_pk_fma_f32 v[22:23], v[4:5], v[22:23], v[12:13]
	s_nop 0
	v_cvt_pk_bf16_f32 v16, v22, v23
	v_lshlrev_b32_e32 v22, 16, v17
	v_and_b32_e32 v23, 0xffff0000, v17
	v_pk_add_f32 v[22:23], v[22:23], v[20:21] op_sel_hi:[1,0] neg_lo:[0,1] neg_hi:[0,1]
	s_nop 0
	v_pk_mul_f32 v[22:23], v[20:21], v[22:23] op_sel:[1,0]
	s_nop 0
	v_pk_fma_f32 v[22:23], v[6:7], v[22:23], v[14:15]
	s_nop 0
	v_cvt_pk_bf16_f32 v17, v22, v23
	v_lshlrev_b32_e32 v22, 16, v18
	v_and_b32_e32 v23, 0xffff0000, v18
	v_pk_add_f32 v[22:23], v[22:23], v[20:21] op_sel_hi:[1,0] neg_lo:[0,1] neg_hi:[0,1]
	s_nop 0
	v_pk_mul_f32 v[22:23], v[20:21], v[22:23] op_sel:[1,0]
	s_waitcnt vmcnt(0)
	v_pk_fma_f32 v[22:23], v[0:1], v[22:23], v[8:9]
	s_nop 0
	v_cvt_pk_bf16_f32 v18, v22, v23
	v_lshlrev_b32_e32 v22, 16, v19
	v_and_b32_e32 v23, 0xffff0000, v19
	v_pk_add_f32 v[22:23], v[22:23], v[20:21] op_sel_hi:[1,0] neg_lo:[0,1] neg_hi:[0,1]
	s_nop 0
	v_pk_mul_f32 v[20:21], v[20:21], v[22:23] op_sel:[1,0]
	s_nop 0
	v_pk_fma_f32 v[20:21], v[2:3], v[20:21], v[10:11]
	s_nop 0
	v_cvt_pk_bf16_f32 v19, v20, v21
	ds_write_b128 v72, v[16:19] offset:1024
	v_mov_b32_e32 v16, v164
	v_mov_b32_e32 v17, v165
	v_mov_b32_e32 v18, v166
	v_mov_b32_e32 v19, v167
	ds_read_b64 v[20:21], v69
	v_lshl_add_u64 v[62:63], v[62:63], 0, s[14:15]
	s_waitcnt vmcnt(0)
	v_lshlrev_b32_e32 v22, 16, v16
	v_and_b32_e32 v23, 0xffff0000, v16
	s_waitcnt lgkmcnt(0)
	v_pk_add_f32 v[22:23], v[22:23], v[20:21] op_sel_hi:[1,0] neg_lo:[0,1] neg_hi:[0,1]
	s_nop 0
	v_pk_mul_f32 v[22:23], v[20:21], v[22:23] op_sel:[1,0]
	s_nop 0
	v_pk_fma_f32 v[22:23], v[4:5], v[22:23], v[12:13]
	s_nop 0
	v_cvt_pk_bf16_f32 v16, v22, v23
	v_lshlrev_b32_e32 v22, 16, v17
	v_and_b32_e32 v23, 0xffff0000, v17
	v_pk_add_f32 v[22:23], v[22:23], v[20:21] op_sel_hi:[1,0] neg_lo:[0,1] neg_hi:[0,1]
	s_nop 0
	v_pk_mul_f32 v[22:23], v[20:21], v[22:23] op_sel:[1,0]
	s_nop 0
	v_pk_fma_f32 v[22:23], v[6:7], v[22:23], v[14:15]
	s_nop 0
	v_cvt_pk_bf16_f32 v17, v22, v23
	v_lshlrev_b32_e32 v22, 16, v18
	v_and_b32_e32 v23, 0xffff0000, v18
	v_pk_add_f32 v[22:23], v[22:23], v[20:21] op_sel_hi:[1,0] neg_lo:[0,1] neg_hi:[0,1]
	s_nop 0
	v_pk_mul_f32 v[22:23], v[20:21], v[22:23] op_sel:[1,0]
	s_nop 0
	v_pk_fma_f32 v[22:23], v[0:1], v[22:23], v[8:9]
	s_nop 0
	v_cvt_pk_bf16_f32 v18, v22, v23
	v_lshlrev_b32_e32 v22, 16, v19
	v_and_b32_e32 v23, 0xffff0000, v19
	v_pk_add_f32 v[22:23], v[22:23], v[20:21] op_sel_hi:[1,0] neg_lo:[0,1] neg_hi:[0,1]
	s_nop 0
	v_pk_mul_f32 v[20:21], v[20:21], v[22:23] op_sel:[1,0]
	s_nop 0
	v_pk_fma_f32 v[20:21], v[2:3], v[20:21], v[10:11]
	s_nop 0
	v_cvt_pk_bf16_f32 v19, v20, v21
	ds_write_b128 v73, v[16:19] offset:1024
	v_mov_b32_e32 v16, v168
	v_mov_b32_e32 v17, v169
	v_mov_b32_e32 v18, v170
	v_mov_b32_e32 v19, v171
	ds_read_b64 v[20:21], v70
	v_lshl_add_u64 v[60:61], v[60:61], 0, s[14:15]
	s_waitcnt vmcnt(0)
	v_lshlrev_b32_e32 v22, 16, v16
	v_and_b32_e32 v23, 0xffff0000, v16
	s_waitcnt lgkmcnt(0)
; #define LAS __attribute__((address_space(3)))
; __device__ __forceinline__ unsigned cvt_pk_bf16(float lo, float hi) { f32x2 v = {lo, hi}; bf16x2_t b = __builtin_convertvector(v, bf16x2_t); return __builtin_bit_cast(unsigned, b); }
; __device__ __forceinline__ float bf_lo(unsigned w) { return __uint_as_float(w << 16); }
; __device__ __forceinline__ float bf_hi(unsigned w) { return __uint_as_float(w & 0xffff0000u); }
; __device__ __forceinline__ void sgu_chunk(const Ctx& C, const Args& a, int l, int n) {
;     ...
;         for (int j = 0; j < 4; ++j) { const int p = C.tid + 512 * j, r = p >> 4, c8 = (p & 15) * 8; const f32x2 st = stats[r];
;             const u32x4 w = *(const u32x4*)(VB + (R0 + r) * D + g * 128 + c8); const f32x4 g0 = *(const f32x4*)(gam + g * 128 + c8), g1 = *(const f32x4*)(gam + g * 128 + c8 + 4);
;             const f32x4 b0 = *(const f32x4*)(bet + g * 128 + c8), b1 = *(const f32x4*)(bet + g * 128 + c8 + 4);
;             u32x4 o; o.x = cvt_pk_bf16((bf_lo(w.x) - st.x) * st.y * g0[0] + b0[0], (bf_hi(w.x) - st.x) * st.y * g0[1] + b0[1]);
;             o.y = cvt_pk_bf16((bf_lo(w.y) - st.x) * st.y * g0[2] + b0[2], (bf_hi(w.y) - st.x) * st.y * g0[3] + b0[3]);
;             o.z = cvt_pk_bf16((bf_lo(w.z) - st.x) * st.y * g1[0] + b1[0], (bf_hi(w.z) - st.x) * st.y * g1[1] + b1[1]);
;             o.w = cvt_pk_bf16((bf_lo(w.w) - st.x) * st.y * g1[2] + b1[2], (bf_hi(w.w) - st.x) * st.y * g1[3] + b1[3]);
;             *(LAS u32x4*)(vimg + (c8 >> 5) * 8192 + r * 64 + (c8 & 31) * 2) = o; }
;         __syncthreads();
;         f32x16 acc[2];
; #pragma unroll
;         for (int r = 0; r < 16; ++r) { acc[0][r] = 0.f; acc[1][r] = 0.f; }
;         const bf16_t* wrow = SW + ((size_t)g * 128 + 32 * tb + r32) * 128 + 4 * hi;
; #pragma unroll
;         for (int kc = 0; kc < 8; ++kc) {
;             const u32x2 alo = *(const u32x2*)(wrow + 16 * kc), ahi = *(const u32x2*)(wrow + 16 * kc + 8);
;             const bf16x8 af = __builtin_bit_cast(bf16x8, (u32x4){alo.x, alo.y, ahi.x, ahi.y});
; #pragma unroll
;             for (int j = 0; j < 2; ++j) { LAS const unsigned char* vp = vimg + (2 * ch + j) * 8192 + kc * 1024 + voff; const s16x4 lo = att::vtr(vp), hh = att::vtr(vp + 512);
;                 const bf16x8 vf = (bf16x8){lo[0], lo[1], lo[2], lo[3], hh[0], hh[1], hh[2], hh[3]}; acc[j] = ATT_MFMA(af, vf, acc[j]); }
;         }
	v_pk_add_f32 v[22:23], v[22:23], v[20:21] op_sel_hi:[1,0] neg_lo:[0,1] neg_hi:[0,1]
	s_nop 0
	v_pk_mul_f32 v[22:23], v[20:21], v[22:23] op_sel:[1,0]
	s_nop 0
	v_pk_fma_f32 v[22:23], v[4:5], v[22:23], v[12:13]
	s_nop 0
	v_cvt_pk_bf16_f32 v16, v22, v23
	v_lshlrev_b32_e32 v22, 16, v17
	v_and_b32_e32 v23, 0xffff0000, v17
	v_pk_add_f32 v[22:23], v[22:23], v[20:21] op_sel_hi:[1,0] neg_lo:[0,1] neg_hi:[0,1]
	s_nop 0
	v_pk_mul_f32 v[22:23], v[20:21], v[22:23] op_sel:[1,0]
	s_nop 0
	v_pk_fma_f32 v[22:23], v[6:7], v[22:23], v[14:15]
	s_nop 0
	v_cvt_pk_bf16_f32 v17, v22, v23
	v_lshlrev_b32_e32 v22, 16, v18
	v_and_b32_e32 v23, 0xffff0000, v18
	v_pk_add_f32 v[22:23], v[22:23], v[20:21] op_sel_hi:[1,0] neg_lo:[0,1] neg_hi:[0,1]
	s_nop 0
	v_pk_mul_f32 v[22:23], v[20:21], v[22:23] op_sel:[1,0]
	s_nop 0
	v_pk_fma_f32 v[22:23], v[0:1], v[22:23], v[8:9]
	s_nop 0
	v_cvt_pk_bf16_f32 v18, v22, v23
	v_lshlrev_b32_e32 v22, 16, v19
	v_and_b32_e32 v23, 0xffff0000, v19
	v_pk_add_f32 v[22:23], v[22:23], v[20:21] op_sel_hi:[1,0] neg_lo:[0,1] neg_hi:[0,1]
	s_nop 0
	v_pk_mul_f32 v[20:21], v[20:21], v[22:23] op_sel:[1,0]
	s_nop 0
	v_pk_fma_f32 v[20:21], v[2:3], v[20:21], v[10:11]
	s_nop 0
	v_cvt_pk_bf16_f32 v19, v20, v21
	ds_write_b128 v74, v[16:19] offset:1024
	v_mov_b32_e32 v16, v172
	v_mov_b32_e32 v17, v173
	v_mov_b32_e32 v18, v174
	v_mov_b32_e32 v19, v175
	ds_read_b64 v[20:21], v71
	v_lshl_add_u64 v[58:59], v[58:59], 0, s[14:15]
	s_waitcnt vmcnt(0)
	v_lshlrev_b32_e32 v22, 16, v16
	v_and_b32_e32 v23, 0xffff0000, v16
	s_waitcnt lgkmcnt(0)
	v_pk_add_f32 v[22:23], v[22:23], v[20:21] op_sel_hi:[1,0] neg_lo:[0,1] neg_hi:[0,1]
	s_nop 0
	v_pk_mul_f32 v[22:23], v[20:21], v[22:23] op_sel:[1,0]
	s_nop 0
	v_pk_fma_f32 v[4:5], v[4:5], v[22:23], v[12:13]
	v_lshlrev_b32_e32 v12, 16, v17
	v_and_b32_e32 v13, 0xffff0000, v17
	v_pk_add_f32 v[12:13], v[12:13], v[20:21] op_sel_hi:[1,0] neg_lo:[0,1] neg_hi:[0,1]
	v_cvt_pk_bf16_f32 v4, v4, v5
	v_pk_mul_f32 v[12:13], v[20:21], v[12:13] op_sel:[1,0]
	s_nop 0
	v_pk_fma_f32 v[6:7], v[6:7], v[12:13], v[14:15]
	s_nop 0
	v_cvt_pk_bf16_f32 v5, v6, v7
	v_lshlrev_b32_e32 v6, 16, v18
	v_and_b32_e32 v7, 0xffff0000, v18
	v_pk_add_f32 v[6:7], v[6:7], v[20:21] op_sel_hi:[1,0] neg_lo:[0,1] neg_hi:[0,1]
	s_nop 0
	v_pk_mul_f32 v[6:7], v[20:21], v[6:7] op_sel:[1,0]
	s_nop 0
	v_pk_fma_f32 v[0:1], v[0:1], v[6:7], v[8:9]
	s_nop 0
	v_cvt_pk_bf16_f32 v6, v0, v1
	v_lshlrev_b32_e32 v0, 16, v19
	v_and_b32_e32 v1, 0xffff0000, v19
	v_pk_add_f32 v[0:1], v[0:1], v[20:21] op_sel_hi:[1,0] neg_lo:[0,1] neg_hi:[0,1]
	s_nop 0
	v_pk_mul_f32 v[0:1], v[20:21], v[0:1] op_sel:[1,0]
	s_nop 0
	v_pk_fma_f32 v[0:1], v[2:3], v[0:1], v[10:11]
	s_nop 0
	v_cvt_pk_bf16_f32 v7, v0, v1
	ds_write_b128 v75, v[4:7] offset:1024
	s_waitcnt lgkmcnt(0)
	s_barrier
	ds_read_b64_tr_b16 v[4:5], v76 offset:1024
	ds_read_b64_tr_b16 v[6:7], v76 offset:1536
	s_waitcnt vmcnt(0) lgkmcnt(0)
	v_mfma_f32_32x32x16_bf16 v[16:31], v[206:209], v[4:7], 0
	ds_read_b64_tr_b16 v[4:5], v76 offset:9216
	ds_read_b64_tr_b16 v[6:7], v76 offset:9728
	ds_read_b64_tr_b16 v[36:37], v76 offset:2048
	ds_read_b64_tr_b16 v[38:39], v76 offset:2560
	s_waitcnt lgkmcnt(2)
	v_mfma_f32_32x32x16_bf16 v[0:15], v[206:209], v[4:7], 0
	s_waitcnt vmcnt(0) lgkmcnt(0)
	v_mfma_f32_32x32x16_bf16 v[16:31], v[210:213], v[36:39], v[16:31]
	ds_read_b64_tr_b16 v[36:37], v76 offset:10240
	ds_read_b64_tr_b16 v[38:39], v76 offset:10752
	s_waitcnt lgkmcnt(0)
	v_mfma_f32_32x32x16_bf16 v[0:15], v[210:213], v[36:39], v[0:15]
	ds_read_b64_tr_b16 v[36:37], v76 offset:3072
	ds_read_b64_tr_b16 v[38:39], v76 offset:3584
	s_waitcnt vmcnt(0) lgkmcnt(0)
	v_mfma_f32_32x32x16_bf16 v[16:31], v[214:217], v[36:39], v[16:31]
	ds_read_b64_tr_b16 v[36:37], v76 offset:11264
	ds_read_b64_tr_b16 v[38:39], v76 offset:11776
	s_waitcnt lgkmcnt(0)
	v_mfma_f32_32x32x16_bf16 v[0:15], v[214:217], v[36:39], v[0:15]
	ds_read_b64_tr_b16 v[36:37], v76 offset:4096
	ds_read_b64_tr_b16 v[38:39], v76 offset:4608
	s_waitcnt vmcnt(0) lgkmcnt(0)
	v_mfma_f32_32x32x16_bf16 v[16:31], v[218:221], v[36:39], v[16:31]
	ds_read_b64_tr_b16 v[36:37], v76 offset:12288
	ds_read_b64_tr_b16 v[38:39], v76 offset:12800
	s_waitcnt lgkmcnt(0)
	v_mfma_f32_32x32x16_bf16 v[0:15], v[218:221], v[36:39], v[0:15]
	ds_read_b64_tr_b16 v[36:37], v76 offset:5120
	ds_read_b64_tr_b16 v[38:39], v76 offset:5632
	s_waitcnt vmcnt(0) lgkmcnt(0)
	v_mfma_f32_32x32x16_bf16 v[16:31], v[232:235], v[36:39], v[16:31]
	ds_read_b64_tr_b16 v[36:37], v76 offset:13312
	ds_read_b64_tr_b16 v[38:39], v76 offset:13824
	s_waitcnt lgkmcnt(0)
	v_mfma_f32_32x32x16_bf16 v[0:15], v[232:235], v[36:39], v[0:15]
	ds_read_b64_tr_b16 v[36:37], v76 offset:6144
	ds_read_b64_tr_b16 v[38:39], v76 offset:6656
	s_waitcnt vmcnt(0) lgkmcnt(0)
	v_mfma_f32_32x32x16_bf16 v[16:31], v[236:239], v[36:39], v[16:31]
	ds_read_b64_tr_b16 v[36:37], v76 offset:14336
	ds_read_b64_tr_b16 v[38:39], v76 offset:14848
	s_waitcnt lgkmcnt(0)
	v_mfma_f32_32x32x16_bf16 v[0:15], v[236:239], v[36:39], v[0:15]
	ds_read_b64_tr_b16 v[36:37], v76 offset:7168
	ds_read_b64_tr_b16 v[38:39], v76 offset:7680
	s_waitcnt vmcnt(0) lgkmcnt(0)
	v_mfma_f32_32x32x16_bf16 v[16:31], v[240:243], v[36:39], v[16:31]
	ds_read_b64_tr_b16 v[36:37], v76 offset:15360
	ds_read_b64_tr_b16 v[38:39], v76 offset:15872
	s_waitcnt lgkmcnt(0)
	v_mfma_f32_32x32x16_bf16 v[0:15], v[240:243], v[36:39], v[0:15]
	ds_read_b64_tr_b16 v[36:37], v76 offset:8192
	ds_read_b64_tr_b16 v[38:39], v76 offset:8704
	s_waitcnt vmcnt(0) lgkmcnt(0)
	v_mfma_f32_32x32x16_bf16 v[16:31], v[244:247], v[36:39], v[16:31]
	ds_read_b64_tr_b16 v[36:37], v76 offset:16384
	ds_read_b64_tr_b16 v[38:39], v76 offset:16896
	s_waitcnt lgkmcnt(0)
; __device__ __forceinline__ unsigned cvt_pk_bf16(float lo, float hi) { f32x2 v = {lo, hi}; bf16x2_t b = __builtin_convertvector(v, bf16x2_t); return __builtin_bit_cast(unsigned, b); }
; __device__ __forceinline__ int crow(int r, int hi) { return (r & 3) + 8 * (r >> 2) + 4 * hi; }
; __device__ __forceinline__ void sgu_chunk(const Ctx& C, const Args& a, int l, int n) {
;     ...
;         int hi_e = hi, r32_e = r32; asm volatile("" : "+v"(hi_e), "+v"(r32_e));
;         const float* sbp = sb + g * 128 + 32 * tb + 4 * hi_e; bf16_t* hp = HC + (R0 + 32 * tb + 4 * hi_e) * 2048 + g * 128 + 64 * ch + r32_e;
;         bf16_t uu[16][2]; float bsv[16];
; #pragma unroll
;         for (int r = 0; r < 16; ++r) { bsv[r] = sbp[att::crow(r, 0)];
; #pragma unroll
;             for (int j = 0; j < 2; ++j) uu[r][j] = hp[att::crow(r, 0) * 2048 + 32 * j]; }
;         asm volatile("" ::: "memory");
; #pragma unroll
;         for (int r = 0; r < 16; ++r)
; #pragma unroll
;             for (int j = 0; j < 2; ++j) { const float u = __uint_as_float((unsigned)uu[r][j] << 16);
;                 hp[att::crow(r, 0) * 2048 + 32 * j] = (bf16_t)(cvt_pk_bf16(u * (acc[j][r] + bsv[r]), 0.f) & 0xffffu); }
	v_mfma_f32_32x32x16_bf16 v[0:15], v[244:247], v[36:39], v[0:15]
	v_mov_b32_e32 v32, v66
	v_mov_b32_e32 v33, v67
	s_nop 0
	v_lshlrev_b32_e32 v34, 2, v33
	v_ashrrev_i32_e32 v35, 31, v34
	v_lshl_add_u64 v[86:87], v[34:35], 2, s[18:19]
	v_lshl_add_u64 v[34:35], s[40:41], 0, v[34:35]
	v_ashrrev_i32_e32 v33, 31, v32
	v_lshlrev_b64 v[34:35], 12, v[34:35]
	s_add_u32 s18, s86, s46
	v_lshl_add_u64 v[32:33], v[32:33], 1, v[34:35]
	s_addc_u32 s19, s87, s47
	v_lshl_add_u64 v[88:89], s[18:19], 0, v[32:33]
	global_load_dwordx4 v[78:81], v[86:87], off
	global_load_dwordx4 v[82:85], v[86:87], off offset:32
	global_load_dwordx4 v[36:39], v[86:87], off offset:64
	global_load_dwordx4 v[32:35], v[86:87], off offset:96
	v_add_co_u32_e32 v86, vcc, s12, v88
	s_mov_b32 s12, 0x5c01000
	s_nop 0
	v_addc_co_u32_e32 v87, vcc, 0, v89, vcc
	v_add_co_u32_e32 v90, vcc, s12, v88
	s_mov_b32 s12, 0x5c02000
	s_nop 0
	v_addc_co_u32_e32 v91, vcc, 0, v89, vcc
	global_load_ushort v77, v[90:91], off offset:-4096
	global_load_ushort v118, v[86:87], off offset:64
	global_load_ushort v119, v[90:91], off
	global_load_ushort v120, v[90:91], off offset:64
	v_add_co_u32_e32 v92, vcc, s12, v88
	s_mov_b32 s12, 0x5c03000
	s_nop 0
	v_addc_co_u32_e32 v93, vcc, 0, v89, vcc
	v_add_co_u32_e32 v94, vcc, s12, v88
	s_mov_b32 s12, 0x5c08000
	s_nop 0
	v_addc_co_u32_e32 v95, vcc, 0, v89, vcc
	global_load_ushort v121, v[94:95], off offset:-4096
	global_load_ushort v122, v[92:93], off offset:64
	global_load_ushort v123, v[94:95], off
	global_load_ushort v124, v[94:95], off offset:64
	v_add_co_u32_e32 v96, vcc, s12, v88
	s_mov_b32 s12, 0x5c09000
	s_nop 0
	v_addc_co_u32_e32 v97, vcc, 0, v89, vcc
	v_add_co_u32_e32 v98, vcc, s12, v88
	s_mov_b32 s12, 0x5c0a000
	s_nop 0
	v_addc_co_u32_e32 v99, vcc, 0, v89, vcc
	global_load_ushort v125, v[98:99], off offset:-4096
	global_load_ushort v126, v[96:97], off offset:64
	global_load_ushort v127, v[98:99], off
	global_load_ushort v128, v[98:99], off offset:64
	v_add_co_u32_e32 v100, vcc, s12, v88
	s_mov_b32 s12, 0x5c0b000
	s_nop 0
	v_addc_co_u32_e32 v101, vcc, 0, v89, vcc
	v_add_co_u32_e32 v102, vcc, s12, v88
	s_mov_b32 s12, 0x5c10000
	s_nop 0
	v_addc_co_u32_e32 v103, vcc, 0, v89, vcc
	global_load_ushort v129, v[102:103], off offset:-4096
	global_load_ushort v130, v[100:101], off offset:64
	global_load_ushort v131, v[102:103], off
	global_load_ushort v132, v[102:103], off offset:64
	v_add_co_u32_e32 v104, vcc, s12, v88
	s_mov_b32 s12, 0x5c11000
	s_nop 0
	v_addc_co_u32_e32 v105, vcc, 0, v89, vcc
	v_add_co_u32_e32 v106, vcc, s12, v88
	s_mov_b32 s12, 0x5c12000
	s_nop 0
	v_addc_co_u32_e32 v107, vcc, 0, v89, vcc
	global_load_ushort v133, v[106:107], off offset:-4096
	global_load_ushort v134, v[104:105], off offset:64
	global_load_ushort v135, v[106:107], off
	global_load_ushort v136, v[106:107], off offset:64
	v_add_co_u32_e32 v108, vcc, s12, v88
	s_mov_b32 s12, 0x5c13000
	s_nop 0
	v_addc_co_u32_e32 v109, vcc, 0, v89, vcc
	v_add_co_u32_e32 v110, vcc, s12, v88
	s_mov_b32 s12, 0x5c18000
	s_nop 0
	v_addc_co_u32_e32 v111, vcc, 0, v89, vcc
	global_load_ushort v137, v[110:111], off offset:-4096
	global_load_ushort v138, v[108:109], off offset:64
	global_load_ushort v139, v[110:111], off
	global_load_ushort v140, v[110:111], off offset:64
	v_add_co_u32_e32 v112, vcc, s12, v88
	s_mov_b32 s12, 0x5c19000
	s_nop 0
	v_addc_co_u32_e32 v113, vcc, 0, v89, vcc
	v_add_co_u32_e32 v114, vcc, s12, v88
	s_mov_b32 s12, 0x5c1a000
	s_nop 0
	v_addc_co_u32_e32 v115, vcc, 0, v89, vcc
	global_load_ushort v141, v[114:115], off offset:-4096
	global_load_ushort v142, v[112:113], off offset:64
	global_load_ushort v143, v[114:115], off
	global_load_ushort v144, v[114:115], off offset:64
	v_add_co_u32_e32 v116, vcc, s12, v88
	s_mov_b32 s12, 0x5c1b000
	s_nop 0
	v_addc_co_u32_e32 v117, vcc, 0, v89, vcc
	s_waitcnt vmcnt(31)
	v_add_f32_e32 v16, v16, v78
	v_add_co_u32_e32 v88, vcc, s12, v88
	v_add_f32_e32 v0, v0, v78
	s_nop 0
	v_addc_co_u32_e32 v89, vcc, 0, v89, vcc
	s_waitcnt vmcnt(27)
	v_lshlrev_b32_e32 v77, 16, v77
	v_mul_f32_e32 v16, v16, v77
	v_cvt_pk_bf16_f32 v16, v16, s0
	global_load_ushort v145, v[88:89], off offset:-4096
	global_load_ushort v146, v[116:117], off offset:64
	global_load_ushort v147, v[88:89], off
	global_load_ushort v148, v[88:89], off offset:64
	global_store_short v[90:91], v16, off offset:-4096
	s_waitcnt vmcnt(31)
	v_lshlrev_b32_e32 v16, 16, v118
	v_mul_f32_e32 v0, v0, v16
	v_cvt_pk_bf16_f32 v0, v0, s0
	global_store_short v[86:87], v0, off offset:64
	s_waitcnt vmcnt(31)
	v_lshlrev_b32_e32 v0, 16, v119
	v_add_f32_e32 v16, v17, v79
	v_mul_f32_e32 v0, v16, v0
	v_cvt_pk_bf16_f32 v0, v0, s0
	global_store_short v[90:91], v0, off
	s_waitcnt vmcnt(31)
	v_lshlrev_b32_e32 v0, 16, v120
	v_add_f32_e32 v1, v1, v79
	v_mul_f32_e32 v0, v1, v0
	v_cvt_pk_bf16_f32 v0, v0, s0
	global_store_short v[90:91], v0, off offset:64
	s_waitcnt vmcnt(31)
	v_lshlrev_b32_e32 v0, 16, v121
	v_add_f32_e32 v1, v18, v80
	v_mul_f32_e32 v0, v1, v0
	v_cvt_pk_bf16_f32 v0, v0, s0
	global_store_short v[94:95], v0, off offset:-4096
	s_waitcnt vmcnt(31)
	v_lshlrev_b32_e32 v0, 16, v122
	v_add_f32_e32 v1, v2, v80
	v_mul_f32_e32 v0, v1, v0
	v_cvt_pk_bf16_f32 v0, v0, s0
	global_store_short v[92:93], v0, off offset:64
	s_waitcnt vmcnt(31)
; __device__ __forceinline__ unsigned cvt_pk_bf16(float lo, float hi) { f32x2 v = {lo, hi}; bf16x2_t b = __builtin_convertvector(v, bf16x2_t); return __builtin_bit_cast(unsigned, b); }
; __device__ __forceinline__ int crow(int r, int hi) { return (r & 3) + 8 * (r >> 2) + 4 * hi; }
; __device__ __forceinline__ void sgu_chunk(const Ctx& C, const Args& a, int l, int n) {
;     ...
; #pragma unroll
;         for (int r = 0; r < 16; ++r)
; #pragma unroll
;             for (int j = 0; j < 2; ++j) { const float u = __uint_as_float((unsigned)uu[r][j] << 16);
;                 hp[att::crow(r, 0) * 2048 + 32 * j] = (bf16_t)(cvt_pk_bf16(u * (acc[j][r] + bsv[r]), 0.f) & 0xffffu); }
;         __syncthreads();
;     }
; }
; __global__ void __launch_bounds__(512, 2) mk_fwd(Args a) {
;     ...
;                 for (int n = bx; n < 256; n += G) sgu_chunk(C, a, l, n);
	v_lshlrev_b32_e32 v0, 16, v123
	v_add_f32_e32 v1, v19, v81
	v_mul_f32_e32 v0, v1, v0
	v_cvt_pk_bf16_f32 v0, v0, s0
	global_store_short v[94:95], v0, off
	s_waitcnt vmcnt(31)
	v_lshlrev_b32_e32 v0, 16, v124
	v_add_f32_e32 v1, v3, v81
	v_mul_f32_e32 v0, v1, v0
	v_cvt_pk_bf16_f32 v0, v0, s0
	global_store_short v[94:95], v0, off offset:64
	s_waitcnt vmcnt(31)
	v_lshlrev_b32_e32 v0, 16, v125
	v_add_f32_e32 v1, v20, v82
	v_mul_f32_e32 v0, v1, v0
	v_cvt_pk_bf16_f32 v0, v0, s0
	global_store_short v[98:99], v0, off offset:-4096
	s_waitcnt vmcnt(31)
	v_lshlrev_b32_e32 v0, 16, v126
	v_add_f32_e32 v1, v4, v82
	v_mul_f32_e32 v0, v1, v0
	v_cvt_pk_bf16_f32 v0, v0, s0
	global_store_short v[96:97], v0, off offset:64
	s_waitcnt vmcnt(31)
	v_lshlrev_b32_e32 v0, 16, v127
	v_add_f32_e32 v1, v21, v83
	v_mul_f32_e32 v0, v1, v0
	v_cvt_pk_bf16_f32 v0, v0, s0
	global_store_short v[98:99], v0, off
	s_waitcnt vmcnt(31)
	v_lshlrev_b32_e32 v0, 16, v128
	v_add_f32_e32 v1, v5, v83
	v_mul_f32_e32 v0, v1, v0
	v_cvt_pk_bf16_f32 v0, v0, s0
	global_store_short v[98:99], v0, off offset:64
	s_waitcnt vmcnt(31)
	v_lshlrev_b32_e32 v0, 16, v129
	v_add_f32_e32 v1, v22, v84
	v_mul_f32_e32 v0, v1, v0
	v_cvt_pk_bf16_f32 v0, v0, s0
	global_store_short v[102:103], v0, off offset:-4096
	s_waitcnt vmcnt(31)
	v_lshlrev_b32_e32 v0, 16, v130
	v_add_f32_e32 v1, v6, v84
	v_mul_f32_e32 v0, v1, v0
	v_cvt_pk_bf16_f32 v0, v0, s0
	global_store_short v[100:101], v0, off offset:64
	s_waitcnt vmcnt(31)
	v_lshlrev_b32_e32 v0, 16, v131
	v_add_f32_e32 v1, v23, v85
	v_mul_f32_e32 v0, v1, v0
	v_cvt_pk_bf16_f32 v0, v0, s0
	global_store_short v[102:103], v0, off
	s_waitcnt vmcnt(31)
	v_lshlrev_b32_e32 v0, 16, v132
	v_add_f32_e32 v1, v7, v85
	v_mul_f32_e32 v0, v1, v0
	v_cvt_pk_bf16_f32 v0, v0, s0
	global_store_short v[102:103], v0, off offset:64
	s_waitcnt vmcnt(31)
	v_lshlrev_b32_e32 v0, 16, v133
	v_add_f32_e32 v1, v24, v36
	v_mul_f32_e32 v0, v1, v0
	v_cvt_pk_bf16_f32 v0, v0, s0
	global_store_short v[106:107], v0, off offset:-4096
	s_waitcnt vmcnt(31)
	v_lshlrev_b32_e32 v0, 16, v134
	v_add_f32_e32 v1, v8, v36
	v_mul_f32_e32 v0, v1, v0
	v_cvt_pk_bf16_f32 v0, v0, s0
	global_store_short v[104:105], v0, off offset:64
	s_waitcnt vmcnt(31)
	v_lshlrev_b32_e32 v0, 16, v135
	v_add_f32_e32 v1, v25, v37
	v_mul_f32_e32 v0, v1, v0
	v_cvt_pk_bf16_f32 v0, v0, s0
	global_store_short v[106:107], v0, off
	s_waitcnt vmcnt(31)
	v_lshlrev_b32_e32 v0, 16, v136
	v_add_f32_e32 v1, v9, v37
	v_mul_f32_e32 v0, v1, v0
	v_cvt_pk_bf16_f32 v0, v0, s0
	global_store_short v[106:107], v0, off offset:64
	s_waitcnt vmcnt(31)
	v_lshlrev_b32_e32 v0, 16, v137
	v_add_f32_e32 v1, v26, v38
	v_mul_f32_e32 v0, v1, v0
	v_cvt_pk_bf16_f32 v0, v0, s0
	global_store_short v[110:111], v0, off offset:-4096
	s_waitcnt vmcnt(31)
	v_lshlrev_b32_e32 v0, 16, v138
	v_add_f32_e32 v1, v10, v38
	v_mul_f32_e32 v0, v1, v0
	v_cvt_pk_bf16_f32 v0, v0, s0
	global_store_short v[108:109], v0, off offset:64
	s_waitcnt vmcnt(31)
	v_lshlrev_b32_e32 v0, 16, v139
	v_add_f32_e32 v1, v27, v39
	v_mul_f32_e32 v0, v1, v0
	v_cvt_pk_bf16_f32 v0, v0, s0
	global_store_short v[110:111], v0, off
	s_waitcnt vmcnt(31)
	v_lshlrev_b32_e32 v0, 16, v140
	v_add_f32_e32 v1, v11, v39
	v_mul_f32_e32 v0, v1, v0
	v_cvt_pk_bf16_f32 v0, v0, s0
	global_store_short v[110:111], v0, off offset:64
	s_waitcnt vmcnt(31)
	v_lshlrev_b32_e32 v0, 16, v141
	v_add_f32_e32 v1, v28, v32
	v_mul_f32_e32 v0, v1, v0
	v_cvt_pk_bf16_f32 v0, v0, s0
	global_store_short v[114:115], v0, off offset:-4096
	s_waitcnt vmcnt(31)
	v_lshlrev_b32_e32 v0, 16, v142
	v_add_f32_e32 v1, v12, v32
	v_mul_f32_e32 v0, v1, v0
	v_cvt_pk_bf16_f32 v0, v0, s0
	global_store_short v[112:113], v0, off offset:64
	s_waitcnt vmcnt(31)
	v_lshlrev_b32_e32 v0, 16, v143
	v_add_f32_e32 v1, v29, v33
	v_mul_f32_e32 v0, v1, v0
	v_cvt_pk_bf16_f32 v0, v0, s0
	global_store_short v[114:115], v0, off
	s_waitcnt vmcnt(31)
	v_lshlrev_b32_e32 v0, 16, v144
	v_add_f32_e32 v1, v13, v33
	v_mul_f32_e32 v0, v1, v0
	v_cvt_pk_bf16_f32 v0, v0, s0
	global_store_short v[114:115], v0, off offset:64
	s_waitcnt vmcnt(31)
	v_lshlrev_b32_e32 v0, 16, v145
	v_add_f32_e32 v1, v30, v34
	v_mul_f32_e32 v0, v1, v0
	v_cvt_pk_bf16_f32 v0, v0, s0
	global_store_short v[88:89], v0, off offset:-4096
	s_waitcnt vmcnt(31)
	v_lshlrev_b32_e32 v0, 16, v146
	v_add_f32_e32 v1, v14, v34
	v_mul_f32_e32 v0, v1, v0
	v_cvt_pk_bf16_f32 v0, v0, s0
	global_store_short v[116:117], v0, off offset:64
	s_waitcnt vmcnt(31)
	v_lshlrev_b32_e32 v0, 16, v147
	v_add_f32_e32 v1, v31, v35
	v_mul_f32_e32 v0, v1, v0
	s_add_u32 s44, s44, 0x200
	v_cvt_pk_bf16_f32 v0, v0, s0
	s_addc_u32 s45, s45, 0
	global_store_short v[88:89], v0, off
	s_waitcnt vmcnt(31)
	v_lshlrev_b32_e32 v0, 16, v148
	v_add_f32_e32 v1, v15, v35
	s_add_u32 s46, s46, 0x100
	v_mul_f32_e32 v0, v1, v0
	s_addc_u32 s47, s47, 0
	v_cvt_pk_bf16_f32 v0, v0, s0
	s_cmpk_lg_i32 s44, 0x1000
	global_store_short v[88:89], v0, off offset:64
	s_barrier
	s_cbranch_scc1 .LBB0_154
	s_add_i32 s29, s29, s88
	v_readlane_b32 s0, v249, 56
	v_readlane_b32 s12, v249, 50
	v_readlane_b32 s1, v249, 57
	s_add_u32 s40, s40, s0
	v_readlane_b32 s13, v249, 51
	s_addc_u32 s41, s41, s1
	s_cmpk_gt_i32 s29, 0xff
	v_lshl_add_u64 v[40:41], v[40:41], 0, s[12:13]
	v_lshl_add_u64 v[42:43], v[42:43], 0, s[12:13]
	v_lshl_add_u64 v[44:45], v[44:45], 0, s[12:13]
	v_lshl_add_u64 v[46:47], v[46:47], 0, s[12:13]
	v_lshl_add_u64 v[48:49], v[48:49], 0, s[12:13]
	s_cbranch_scc0 .LBB0_149

; #define PG8_STAGE(bufoff, gbase, voff) do { _Pragma("unroll") for (int _i = 0; _i < 2; ++_i) \
;         __builtin_amdgcn_global_load_lds((const unsigned*)((const char*)(gbase) + (voff)[_i]), (LAS unsigned*)(lds + (bufoff) + ldsw + _i * 8192), 16, 0, 0); } while (0)
; #define PG8_LDA(dst, b, h) do { _Pragma("unroll") for (int m = 0; m < 4; ++m) _Pragma("unroll") for (int k = 0; k < 2; ++k) dst[m][k] = *(const LAS bf16x8*)(lds + PG8_SA(b, h) + aoff + m * 2048 + k * 1024); } while (0)
; #define PG8_LDB(dst, b, h) do { _Pragma("unroll") for (int n = 0; n < 2; ++n) _Pragma("unroll") for (int k = 0; k < 2; ++k) dst[n][k] = *(const LAS bf16x8*)(lds + PG8_SB(b, h) + boff + n * 2048 + k * 1024); } while (0)
; #define PG8_MMA(ai, bj, At, Bt) do { __builtin_amdgcn_s_setprio(1); _Pragma("unroll") for (int m = 0; m < 4; ++m) _Pragma("unroll") for (int n = 0; n < 2; ++n) _Pragma("unroll") for (int k = 0; k < 2; ++k) \
;         acc[ai][bj][m][n] = __builtin_amdgcn_mfma_f32_16x16x32_bf16(Bt[n][k], At[m][k], acc[ai][bj][m][n], 0, 0, 0); __builtin_amdgcn_s_setprio(0); } while (0)
; #define PG8_WAIT_V(n) asm volatile("s_waitcnt vmcnt(" #n ")" ::: "memory")
; #define PG8_WAIT_L(n) asm volatile("s_waitcnt lgkmcnt(" #n ")" ::: "memory")
; #define PG8_BAR __builtin_amdgcn_s_barrier()
; #define PG8_SCHED __builtin_amdgcn_sched_barrier(0)
; template <class Epi, bool SP2 = true, bool ALIGN_EPI = true>
; __device__ __forceinline__ void gemm_phase(LAS unsigned char* lds, const Gemm g, const StaticOrder& S, const Epi& E, const int tid) {
;     ...
;             PG8_LDB(B0, 0, 0); PG8_LDB(B1, 0, 1); PG8_SCHED; PG8_LDA(At, 0, 0); PG8_STAGE(PG8_SA(1, 1), a1 + hstep, voffA);
;             PG8_WAIT_V(8); PG8_WAIT_L(0); PG8_BAR; PG8_MMA(0, 0, At, B0); PG8_MMA(0, 1, At, B1); PG8_BAR; PG8_SCHED;
;             PG8_LDA(At, 0, 1); PG8_STAGE(PG8_SB(0, 0), b2, voffB); PG8_STAGE(PG8_SB(0, 1), b2 + hstep, voffB); PG8_STAGE(PG8_SA(0, 0), a2, voffA);
;             PG8_WAIT_V(8); PG8_WAIT_L(0); PG8_BAR; PG8_MMA(1, 0, At, B0); PG8_MMA(1, 1, At, B1); PG8_BAR; PG8_SCHED;
.LBB0_167:
	s_add_u32 s12, s24, 0xfffc0080
	s_addc_u32 s13, s25, -1
	s_add_i32 s56, 0, 0x10000
	s_cmp_eq_u32 s55, 12
	s_cselect_b32 s29, s45, s13
	s_cselect_b32 s28, s46, s12
	v_add_u32_e32 v148, s56, v152
	s_cselect_b32 s19, s47, s54
	s_cselect_b32 s18, s48, s49
	s_add_i32 s12, 0, 0x14000
	ds_read_b128 v[140:143], v148
	ds_read_b128 v[144:147], v148 offset:1024
	ds_read_b128 v[154:157], v148 offset:2048
	ds_read_b128 v[158:161], v148 offset:3072
	v_add_u32_e32 v148, s12, v152
	ds_read_b128 v[162:165], v148
	ds_read_b128 v[166:169], v148 offset:1024
	ds_read_b128 v[170:173], v148 offset:2048
	ds_read_b128 v[174:177], v148 offset:3072
	s_add_i32 m0, s39, 0xc000
	ds_read_b128 v[178:181], v153
	ds_read_b128 v[182:185], v153 offset:1024
	ds_read_b128 v[186:189], v153 offset:2048
	ds_read_b128 v[206:209], v153 offset:3072
	ds_read_b128 v[210:213], v153 offset:4096
	ds_read_b128 v[214:217], v153 offset:5120
	ds_read_b128 v[218:221], v153 offset:6144
	ds_read_b128 v[232:235], v153 offset:7168
	global_load_lds_dwordx4 v136, s[24:25]
	s_add_i32 m0, s39, 0xe000
	s_nop 0
	global_load_lds_dwordx4 v138, s[24:25]
	s_waitcnt vmcnt(8)
	s_waitcnt lgkmcnt(0)
	s_barrier
	s_setprio 1
	s_waitcnt lgkmcnt(0)
	v_mfma_f32_16x16x32_bf16 v[124:127], v[140:143], v[178:181], v[124:127]
	v_mfma_f32_16x16x32_bf16 v[120:123], v[154:157], v[178:181], v[120:123]
	v_mfma_f32_16x16x32_bf16 v[108:111], v[140:143], v[186:189], v[108:111]
	v_mfma_f32_16x16x32_bf16 v[104:107], v[154:157], v[186:189], v[104:107]
	v_mfma_f32_16x16x32_bf16 v[92:95], v[140:143], v[210:213], v[92:95]
	v_mfma_f32_16x16x32_bf16 v[88:91], v[154:157], v[210:213], v[88:91]
	v_mfma_f32_16x16x32_bf16 v[76:79], v[140:143], v[218:221], v[76:79]
	v_mfma_f32_16x16x32_bf16 v[72:75], v[154:157], v[218:221], v[72:75]
	v_mfma_f32_16x16x32_bf16 v[124:127], v[144:147], v[182:185], v[124:127]
	v_mfma_f32_16x16x32_bf16 v[120:123], v[158:161], v[182:185], v[120:123]
	v_mfma_f32_16x16x32_bf16 v[108:111], v[144:147], v[206:209], v[108:111]
	v_mfma_f32_16x16x32_bf16 v[104:107], v[158:161], v[206:209], v[104:107]
	v_mfma_f32_16x16x32_bf16 v[92:95], v[144:147], v[214:217], v[92:95]
	v_mfma_f32_16x16x32_bf16 v[88:91], v[158:161], v[214:217], v[88:91]
	v_mfma_f32_16x16x32_bf16 v[76:79], v[144:147], v[232:235], v[76:79]
	v_mfma_f32_16x16x32_bf16 v[72:75], v[158:161], v[232:235], v[72:75]
	s_setprio 0
	s_setprio 1
	v_mfma_f32_16x16x32_bf16 v[116:119], v[162:165], v[178:181], v[116:119]
	v_mfma_f32_16x16x32_bf16 v[112:115], v[170:173], v[178:181], v[112:115]
	v_mfma_f32_16x16x32_bf16 v[100:103], v[162:165], v[186:189], v[100:103]
	v_mfma_f32_16x16x32_bf16 v[96:99], v[170:173], v[186:189], v[96:99]
	v_mfma_f32_16x16x32_bf16 v[84:87], v[162:165], v[210:213], v[84:87]
	v_mfma_f32_16x16x32_bf16 v[80:83], v[170:173], v[210:213], v[80:83]
	v_mfma_f32_16x16x32_bf16 v[68:71], v[162:165], v[218:221], v[68:71]
	v_mfma_f32_16x16x32_bf16 v[64:67], v[170:173], v[218:221], v[64:67]
	v_mfma_f32_16x16x32_bf16 v[116:119], v[166:169], v[182:185], v[116:119]
	v_mfma_f32_16x16x32_bf16 v[112:115], v[174:177], v[182:185], v[112:115]
	v_mfma_f32_16x16x32_bf16 v[100:103], v[166:169], v[206:209], v[100:103]
	v_mfma_f32_16x16x32_bf16 v[96:99], v[174:177], v[206:209], v[96:99]
	v_mfma_f32_16x16x32_bf16 v[84:87], v[166:169], v[214:217], v[84:87]
	v_mfma_f32_16x16x32_bf16 v[80:83], v[174:177], v[214:217], v[80:83]
	v_mfma_f32_16x16x32_bf16 v[68:71], v[166:169], v[232:235], v[68:71]
	v_mfma_f32_16x16x32_bf16 v[64:67], v[174:177], v[232:235], v[64:67]
	s_setprio 0
	s_barrier
	s_add_i32 s13, s56, s36
	s_mov_b32 m0, s13
	ds_read_b128 v[178:181], v153 offset:16384
	ds_read_b128 v[182:185], v153 offset:17408
	ds_read_b128 v[186:189], v153 offset:18432
	ds_read_b128 v[206:209], v153 offset:19456
	ds_read_b128 v[210:213], v153 offset:20480
	ds_read_b128 v[214:217], v153 offset:21504
	ds_read_b128 v[218:221], v153 offset:22528
	ds_read_b128 v[232:235], v153 offset:23552
	global_load_lds_dwordx4 v132, s[18:19]
	s_add_i32 m0, s13, 0x2000
	s_add_u32 s56, s18, 0x40000
	s_addc_u32 s57, s19, 0
	s_add_i32 s12, s12, s36
	global_load_lds_dwordx4 v128, s[18:19]
	s_mov_b32 m0, s12
	s_nop 0
	global_load_lds_dwordx4 v132, s[56:57]
	s_add_i32 m0, s12, 0x2000
	s_nop 0
	global_load_lds_dwordx4 v128, s[56:57]
	s_mov_b32 m0, s39
	s_nop 0
	global_load_lds_dwordx4 v134, s[28:29]
	s_mov_b32 m0, s66
	s_nop 0
	global_load_lds_dwordx4 v130, s[28:29]
	s_waitcnt vmcnt(8)
	s_waitcnt lgkmcnt(0)
	s_barrier
	s_setprio 1
	s_waitcnt lgkmcnt(0)
	v_mfma_f32_16x16x32_bf16 v[60:63], v[140:143], v[178:181], v[60:63]
	v_mfma_f32_16x16x32_bf16 v[56:59], v[154:157], v[178:181], v[56:59]
	v_mfma_f32_16x16x32_bf16 v[44:47], v[140:143], v[186:189], v[44:47]
	v_mfma_f32_16x16x32_bf16 v[40:43], v[154:157], v[186:189], v[40:43]
	v_mfma_f32_16x16x32_bf16 v[28:31], v[140:143], v[210:213], v[28:31]
	v_mfma_f32_16x16x32_bf16 v[24:27], v[154:157], v[210:213], v[24:27]
	v_mfma_f32_16x16x32_bf16 v[12:15], v[140:143], v[218:221], v[12:15]
	v_mfma_f32_16x16x32_bf16 v[8:11], v[154:157], v[218:221], v[8:11]
	v_mfma_f32_16x16x32_bf16 v[60:63], v[144:147], v[182:185], v[60:63]
	v_mfma_f32_16x16x32_bf16 v[56:59], v[158:161], v[182:185], v[56:59]
	v_mfma_f32_16x16x32_bf16 v[44:47], v[144:147], v[206:209], v[44:47]
	v_mfma_f32_16x16x32_bf16 v[40:43], v[158:161], v[206:209], v[40:43]
	v_mfma_f32_16x16x32_bf16 v[28:31], v[144:147], v[214:217], v[28:31]
	v_mfma_f32_16x16x32_bf16 v[24:27], v[158:161], v[214:217], v[24:27]
	v_mfma_f32_16x16x32_bf16 v[12:15], v[144:147], v[232:235], v[12:15]
	v_mfma_f32_16x16x32_bf16 v[8:11], v[158:161], v[232:235], v[8:11]
	s_setprio 0
	s_setprio 1
	v_mfma_f32_16x16x32_bf16 v[52:55], v[162:165], v[178:181], v[52:55]
	v_mfma_f32_16x16x32_bf16 v[48:51], v[170:173], v[178:181], v[48:51]
	v_mfma_f32_16x16x32_bf16 v[36:39], v[162:165], v[186:189], v[36:39]
	v_mfma_f32_16x16x32_bf16 v[32:35], v[170:173], v[186:189], v[32:35]
	v_mfma_f32_16x16x32_bf16 v[20:23], v[162:165], v[210:213], v[20:23]
	v_mfma_f32_16x16x32_bf16 v[16:19], v[170:173], v[210:213], v[16:19]
	v_mfma_f32_16x16x32_bf16 v[4:7], v[162:165], v[218:221], v[4:7]
	v_mfma_f32_16x16x32_bf16 v[0:3], v[170:173], v[218:221], v[0:3]
	v_mfma_f32_16x16x32_bf16 v[52:55], v[166:169], v[182:185], v[52:55]
	v_mfma_f32_16x16x32_bf16 v[48:51], v[174:177], v[182:185], v[48:51]
	v_mfma_f32_16x16x32_bf16 v[36:39], v[166:169], v[206:209], v[36:39]
	v_mfma_f32_16x16x32_bf16 v[32:35], v[174:177], v[206:209], v[32:35]
	v_mfma_f32_16x16x32_bf16 v[20:23], v[166:169], v[214:217], v[20:23]
	v_mfma_f32_16x16x32_bf16 v[16:19], v[174:177], v[214:217], v[16:19]
	v_mfma_f32_16x16x32_bf16 v[4:7], v[166:169], v[232:235], v[4:7]
	v_mfma_f32_16x16x32_bf16 v[0:3], v[174:177], v[232:235], v[0:3]
	s_setprio 0
	s_barrier
; #define PG8_STAGE(bufoff, gbase, voff) do { _Pragma("unroll") for (int _i = 0; _i < 2; ++_i) \
;         __builtin_amdgcn_global_load_lds((const unsigned*)((const char*)(gbase) + (voff)[_i]), (LAS unsigned*)(lds + (bufoff) + ldsw + _i * 8192), 16, 0, 0); } while (0)
; #define PG8_LDA(dst, b, h) do { _Pragma("unroll") for (int m = 0; m < 4; ++m) _Pragma("unroll") for (int k = 0; k < 2; ++k) dst[m][k] = *(const LAS bf16x8*)(lds + PG8_SA(b, h) + aoff + m * 2048 + k * 1024); } while (0)
; #define PG8_LDB(dst, b, h) do { _Pragma("unroll") for (int n = 0; n < 2; ++n) _Pragma("unroll") for (int k = 0; k < 2; ++k) dst[n][k] = *(const LAS bf16x8*)(lds + PG8_SB(b, h) + boff + n * 2048 + k * 1024); } while (0)
; #define PG8_BAR __builtin_amdgcn_s_barrier()
; template <class Epi, bool SP2 = true, bool ALIGN_EPI = true>
; __device__ __forceinline__ void gemm_phase(LAS unsigned char* lds, const Gemm g, const StaticOrder& S, const Epi& E, const int tid) {
;     ...
;         for (int t = hh * tper; t < (hh + 1) * tper; t += 2) {
;             const bool last = (t == nt - 2);
;             const char* a1 = cA + (size_t)(t + 1) * kstep;
;             const char* a2 = last ? nA : cA + (size_t)(t + 2) * kstep; const char* b2 = last ? nB : cB + (size_t)(t + 2) * kstep;
;             const char* a3 = a2 + kstep; const char* b3 = b2 + kstep;
;             if constexpr (SP2) {
;             PG8_LDB(B0, 0, 0); PG8_LDB(B1, 0, 1); PG8_SCHED; PG8_LDA(At, 0, 0); PG8_STAGE(PG8_SA(1, 1), a1 + hstep, voffA);
;             PG8_WAIT_V(8); PG8_WAIT_L(0); PG8_BAR; PG8_MMA(0, 0, At, B0); PG8_MMA(0, 1, At, B1); PG8_BAR; PG8_SCHED;
;             PG8_LDA(At, 0, 1); PG8_STAGE(PG8_SB(0, 0), b2, voffB); PG8_STAGE(PG8_SB(0, 1), b2 + hstep, voffB); PG8_STAGE(PG8_SA(0, 0), a2, voffA);
;             PG8_WAIT_V(8); PG8_WAIT_L(0); PG8_BAR; PG8_MMA(1, 0, At, B0); PG8_MMA(1, 1, At, B1); PG8_BAR; PG8_SCHED;
;             PG8_LDB(B0, 1, 0); PG8_LDB(B1, 1, 1); PG8_SCHED; PG8_LDA(At, 1, 0); PG8_STAGE(PG8_SA(0, 1), a2 + hstep, voffA);
;             PG8_WAIT_V(8); PG8_WAIT_L(0); PG8_BAR; PG8_MMA(0, 0, At, B0); PG8_MMA(0, 1, At, B1); PG8_BAR; PG8_SCHED;
;             PG8_LDA(At, 1, 1); PG8_STAGE(PG8_SB(1, 0), b3, voffB); PG8_STAGE(PG8_SB(1, 1), b3 + hstep, voffB); PG8_STAGE(PG8_SA(1, 0), a3, voffA);
;             PG8_WAIT_V(8); PG8_WAIT_L(0); PG8_BAR; PG8_MMA(1, 0, At, B0); PG8_MMA(1, 1, At, B1); PG8_BAR; PG8_SCHED;
	s_add_i32 s12, 0, 0x18000
	s_add_i32 s13, 0, 0x1c000
	v_add_u32_e32 v158, s12, v152
	v_add_u32_e32 v174, s13, v152
	ds_read_b128 v[140:143], v158
	ds_read_b128 v[144:147], v158 offset:1024
	ds_read_b128 v[154:157], v158 offset:2048
	ds_read_b128 v[158:161], v158 offset:3072
	ds_read_b128 v[162:165], v174
	ds_read_b128 v[166:169], v174 offset:1024
	ds_read_b128 v[170:173], v174 offset:2048
	ds_read_b128 v[174:177], v174 offset:3072
	s_add_u32 s28, s28, 0x40000
	s_addc_u32 s29, s29, 0
	s_mov_b32 m0, s95
	ds_read_b128 v[178:181], v153 offset:32768
	ds_read_b128 v[182:185], v153 offset:33792
	ds_read_b128 v[186:189], v153 offset:34816
	ds_read_b128 v[206:209], v153 offset:35840
	ds_read_b128 v[210:213], v153 offset:36864
	ds_read_b128 v[214:217], v153 offset:37888
	ds_read_b128 v[218:221], v153 offset:38912
	ds_read_b128 v[232:235], v153 offset:39936
	global_load_lds_dwordx4 v134, s[28:29]
	s_mov_b32 m0, s75
	s_nop 0
	global_load_lds_dwordx4 v130, s[28:29]
	s_waitcnt vmcnt(8)
	s_waitcnt lgkmcnt(0)
	s_barrier
	s_setprio 1
	s_waitcnt lgkmcnt(0)
	v_mfma_f32_16x16x32_bf16 v[124:127], v[140:143], v[178:181], v[124:127]
	v_mfma_f32_16x16x32_bf16 v[120:123], v[154:157], v[178:181], v[120:123]
	v_mfma_f32_16x16x32_bf16 v[108:111], v[140:143], v[186:189], v[108:111]
	v_mfma_f32_16x16x32_bf16 v[104:107], v[154:157], v[186:189], v[104:107]
	v_mfma_f32_16x16x32_bf16 v[92:95], v[140:143], v[210:213], v[92:95]
	v_mfma_f32_16x16x32_bf16 v[88:91], v[154:157], v[210:213], v[88:91]
	v_mfma_f32_16x16x32_bf16 v[76:79], v[140:143], v[218:221], v[76:79]
	v_mfma_f32_16x16x32_bf16 v[72:75], v[154:157], v[218:221], v[72:75]
	v_mfma_f32_16x16x32_bf16 v[124:127], v[144:147], v[182:185], v[124:127]
	v_mfma_f32_16x16x32_bf16 v[120:123], v[158:161], v[182:185], v[120:123]
	v_mfma_f32_16x16x32_bf16 v[108:111], v[144:147], v[206:209], v[108:111]
	v_mfma_f32_16x16x32_bf16 v[104:107], v[158:161], v[206:209], v[104:107]
	v_mfma_f32_16x16x32_bf16 v[92:95], v[144:147], v[214:217], v[92:95]
	v_mfma_f32_16x16x32_bf16 v[88:91], v[158:161], v[214:217], v[88:91]
	v_mfma_f32_16x16x32_bf16 v[76:79], v[144:147], v[232:235], v[76:79]
	v_mfma_f32_16x16x32_bf16 v[72:75], v[158:161], v[232:235], v[72:75]
	s_setprio 0
	s_setprio 1
	v_mfma_f32_16x16x32_bf16 v[116:119], v[162:165], v[178:181], v[116:119]
	v_mfma_f32_16x16x32_bf16 v[112:115], v[170:173], v[178:181], v[112:115]
	v_mfma_f32_16x16x32_bf16 v[100:103], v[162:165], v[186:189], v[100:103]
	v_mfma_f32_16x16x32_bf16 v[96:99], v[170:173], v[186:189], v[96:99]
	v_mfma_f32_16x16x32_bf16 v[84:87], v[162:165], v[210:213], v[84:87]
	v_mfma_f32_16x16x32_bf16 v[80:83], v[170:173], v[210:213], v[80:83]
	v_mfma_f32_16x16x32_bf16 v[68:71], v[162:165], v[218:221], v[68:71]
	v_mfma_f32_16x16x32_bf16 v[64:67], v[170:173], v[218:221], v[64:67]
	v_mfma_f32_16x16x32_bf16 v[116:119], v[166:169], v[182:185], v[116:119]
	v_mfma_f32_16x16x32_bf16 v[112:115], v[174:177], v[182:185], v[112:115]
	v_mfma_f32_16x16x32_bf16 v[100:103], v[166:169], v[206:209], v[100:103]
	v_mfma_f32_16x16x32_bf16 v[96:99], v[174:177], v[206:209], v[96:99]
	v_mfma_f32_16x16x32_bf16 v[84:87], v[166:169], v[214:217], v[84:87]
	v_mfma_f32_16x16x32_bf16 v[80:83], v[174:177], v[214:217], v[80:83]
	v_mfma_f32_16x16x32_bf16 v[68:71], v[166:169], v[232:235], v[68:71]
	v_mfma_f32_16x16x32_bf16 v[64:67], v[174:177], v[232:235], v[64:67]
	s_setprio 0
	s_barrier
	s_add_i32 s12, s12, s36
	s_add_u32 s98, s18, 0x80
	s_addc_u32 s99, s19, 0
	s_add_u32 s100, s28, 0xfffc0080
	s_addc_u32 s101, s29, -1
	s_mov_b32 m0, s12
	ds_read_b128 v[178:181], v153 offset:49152
	ds_read_b128 v[182:185], v153 offset:50176
	ds_read_b128 v[186:189], v153 offset:51200
	ds_read_b128 v[206:209], v153 offset:52224
	ds_read_b128 v[210:213], v153 offset:53248
	ds_read_b128 v[214:217], v153 offset:54272
	ds_read_b128 v[218:221], v153 offset:55296
	ds_read_b128 v[232:235], v153 offset:56320
	global_load_lds_dwordx4 v132, s[98:99]
	s_add_i32 m0, s12, 0x2000
	s_add_u32 s18, s18, 0x40080
	s_addc_u32 s19, s19, 0
	s_add_i32 s12, s13, s36
	global_load_lds_dwordx4 v128, s[98:99]
	s_mov_b32 m0, s12
	s_nop 0
	global_load_lds_dwordx4 v132, s[18:19]
	s_add_i32 m0, s12, 0x2000
	s_nop 0
	global_load_lds_dwordx4 v128, s[18:19]
	s_mov_b32 m0, s76
	s_nop 0
	global_load_lds_dwordx4 v134, s[100:101]
	s_mov_b32 m0, s70
	s_nop 0
	global_load_lds_dwordx4 v130, s[100:101]
	s_waitcnt vmcnt(8)
	s_waitcnt lgkmcnt(0)
	s_barrier
	s_setprio 1
	s_waitcnt lgkmcnt(0)
	v_mfma_f32_16x16x32_bf16 v[60:63], v[140:143], v[178:181], v[60:63]
	v_mfma_f32_16x16x32_bf16 v[56:59], v[154:157], v[178:181], v[56:59]
	v_mfma_f32_16x16x32_bf16 v[44:47], v[140:143], v[186:189], v[44:47]
	v_mfma_f32_16x16x32_bf16 v[40:43], v[154:157], v[186:189], v[40:43]
	v_mfma_f32_16x16x32_bf16 v[28:31], v[140:143], v[210:213], v[28:31]
	v_mfma_f32_16x16x32_bf16 v[24:27], v[154:157], v[210:213], v[24:27]
	v_mfma_f32_16x16x32_bf16 v[12:15], v[140:143], v[218:221], v[12:15]
	v_mfma_f32_16x16x32_bf16 v[8:11], v[154:157], v[218:221], v[8:11]
	v_mfma_f32_16x16x32_bf16 v[60:63], v[144:147], v[182:185], v[60:63]
	v_mfma_f32_16x16x32_bf16 v[56:59], v[158:161], v[182:185], v[56:59]
	v_mfma_f32_16x16x32_bf16 v[44:47], v[144:147], v[206:209], v[44:47]
	v_mfma_f32_16x16x32_bf16 v[40:43], v[158:161], v[206:209], v[40:43]
	v_mfma_f32_16x16x32_bf16 v[28:31], v[144:147], v[214:217], v[28:31]
	v_mfma_f32_16x16x32_bf16 v[24:27], v[158:161], v[214:217], v[24:27]
	v_mfma_f32_16x16x32_bf16 v[12:15], v[144:147], v[232:235], v[12:15]
	v_mfma_f32_16x16x32_bf16 v[8:11], v[158:161], v[232:235], v[8:11]
	s_setprio 0
	s_setprio 1
	v_mfma_f32_16x16x32_bf16 v[52:55], v[162:165], v[178:181], v[52:55]
	v_mfma_f32_16x16x32_bf16 v[48:51], v[170:173], v[178:181], v[48:51]
	v_mfma_f32_16x16x32_bf16 v[36:39], v[162:165], v[186:189], v[36:39]
	v_mfma_f32_16x16x32_bf16 v[32:35], v[170:173], v[186:189], v[32:35]
	v_mfma_f32_16x16x32_bf16 v[20:23], v[162:165], v[210:213], v[20:23]
	v_mfma_f32_16x16x32_bf16 v[16:19], v[170:173], v[210:213], v[16:19]
	v_mfma_f32_16x16x32_bf16 v[4:7], v[162:165], v[218:221], v[4:7]
	v_mfma_f32_16x16x32_bf16 v[0:3], v[170:173], v[218:221], v[0:3]
	v_mfma_f32_16x16x32_bf16 v[52:55], v[166:169], v[182:185], v[52:55]
	v_mfma_f32_16x16x32_bf16 v[48:51], v[174:177], v[182:185], v[48:51]
	v_mfma_f32_16x16x32_bf16 v[36:39], v[166:169], v[206:209], v[36:39]
	v_mfma_f32_16x16x32_bf16 v[32:35], v[174:177], v[206:209], v[32:35]
	v_mfma_f32_16x16x32_bf16 v[20:23], v[166:169], v[214:217], v[20:23]
	v_mfma_f32_16x16x32_bf16 v[16:19], v[174:177], v[214:217], v[16:19]
	v_mfma_f32_16x16x32_bf16 v[4:7], v[166:169], v[232:235], v[4:7]
	v_mfma_f32_16x16x32_bf16 v[0:3], v[174:177], v[232:235], v[0:3]
	s_setprio 0
	s_barrier
	s_add_i32 s55, s55, 2
	s_add_u32 s24, s24, 0x100
	s_addc_u32 s25, s25, 0
	s_add_u32 s49, s49, 0x100
	s_addc_u32 s54, s54, 0
	s_cmp_gt_u32 s55, 13
	s_cbranch_scc0 .LBB0_167
	v_readlane_b32 s0, v248, 58
	v_readlane_b32 s1, v248, 59
	s_and_b64 vcc, exec, s[0:1]
	s_cbranch_vccz .LBB0_170
	s_barrier

;     __device__ __forceinline__ void operator()(const Acc& acc, const Unit& u, int wr, int wc, int fr, int fq) const {
;     ...
;                 for (int mm = 0; mm < 2; ++mm) { const int row = row0 + ai * HALF + (2 * mh + mm) * 16; const size_t off = (size_t)row * D + col0;
;                     sv[mm] = st ? st[row] : (f32x2){0.f, 1.f};
; #pragma unroll
;                     for (int bj = 0; bj < 2; ++bj)
; #pragma unroll
;                         for (int n = 0; n < 2; ++n) pre[mm][bj][n] = *(const f32x4*)(base + off + bj * HALF + n * 16); }
;                 asm volatile("" ::: "memory");
; #pragma unroll
;                 for (int bj = 0; bj < 2; ++bj)
; #pragma unroll
;                     for (int n = 0; n < 2; ++n) { f32x4 gv = (f32x4){ALPHA, ALPHA, ALPHA, ALPHA}, bv = (f32x4){0.f, 0.f, 0.f, 0.f};
;                         if (st) { gv = *(const f32x4*)(g + col0 + bj * HALF + n * 16) * ALPHA; bv = *(const f32x4*)(b + col0 + bj * HALF + n * 16) * ALPHA; }
; #pragma unroll
;                         for (int mm = 0; mm < 2; ++mm) { const int m = 2 * mh + mm; const size_t off = (size_t)(row0 + ai * HALF + m * 16) * D + col0;
;                             *(f32x4*)(out + off + bj * HALF + n * 16) = ((pre[mm][bj][n] - sv[mm].x) * sv[mm].y) * gv + bv + acc[ai][bj][m][n] * scale; } }
.LBB0_328:
	s_lshl_b32 s12, s76, 8
	v_mov_b32_e32 v129, v215
	v_mov_b32_e32 v128, v214
	s_add_i32 s12, s12, s70
	v_mov_b32_e32 v176, 1.0
	v_add_u32_e32 v172, s12, v129
	v_readlane_b32 s12, v249, 9
	v_readlane_b32 s13, v249, 10
	v_ashrrev_i32_e32 v173, 31, v172
	v_mov_b32_e32 v178, 0
	v_cndmask_b32_e64 v129, 0, 1, s[12:13]
	v_cmp_ne_u32_e64 s[44:45], 1, v129
	s_andn2_b64 vcc, exec, s[12:13]
	v_mov_b32_e32 v182, 0
	v_mov_b32_e32 v180, 1.0
	s_mov_b64 s[94:95], 0x8000
	v_mov_b32_e32 v183, 1.0
	s_cbranch_vccnz .LBB0_330
	v_lshl_add_u64 v[130:131], v[172:173], 3, s[4:5]
	global_load_dwordx2 v[182:183], v[130:131], off
.LBB0_330:
	s_lshl_b32 s12, s75, 8
	s_or_b32 s12, s12, s71
	v_lshl_add_u32 v166, v128, 2, s12
	v_ashrrev_i32_e32 v167, 31, v166
	v_lshl_add_u64 v[174:175], v[166:167], 2, s[84:85]
	v_lshlrev_b64 v[188:189], 12, v[172:173]
	v_lshl_add_u64 v[128:129], v[174:175], 0, v[188:189]
	global_load_dwordx4 v[156:159], v[128:129], off
	global_load_dwordx4 v[148:151], v[128:129], off offset:64
	global_load_dwordx4 v[140:143], v[128:129], off offset:512
	global_load_dwordx4 v[132:135], v[128:129], off offset:576
	v_add_u32_e32 v128, 16, v172
	s_and_b64 vcc, exec, s[44:45]
	v_ashrrev_i32_e32 v129, 31, v128
	v_mov_b32_e32 v179, 1.0
	s_cbranch_vccnz .LBB0_332
	v_lshl_add_u64 v[130:131], v[128:129], 3, s[4:5]
	global_load_dwordx2 v[178:179], v[130:131], off
.LBB0_332:
	v_lshlrev_b64 v[190:191], 12, v[128:129]
	v_lshl_add_u64 v[128:129], v[174:175], 0, v[190:191]
	global_load_dwordx4 v[152:155], v[128:129], off
	global_load_dwordx4 v[144:147], v[128:129], off offset:64
	global_load_dwordx4 v[136:139], v[128:129], off offset:512
	s_nop 0
	global_load_dwordx4 v[128:131], v[128:129], off offset:576
	v_lshlrev_b64 v[170:171], 2, v[166:167]
	v_mov_b32_e32 v186, 0
	v_mov_b32_e32 v184, 0x3fd744fd
	s_and_b64 vcc, exec, s[44:45]
	v_lshl_add_u64 v[166:167], s[48:49], 0, v[170:171]
	v_lshl_add_u64 v[168:169], s[46:47], 0, v[170:171]
	v_mov_b32_e32 v208, 0x3fd744fd
	v_mov_b32_e32 v209, 0x3fd744fd
	v_mov_b32_e32 v206, 0x3fd744fd
	v_mov_b32_e32 v207, 0x3fd744fd
	v_mov_b32_e32 v212, 0
	v_mov_b32_e32 v213, 0
	v_mov_b32_e32 v210, 0
	v_mov_b32_e32 v211, 0
	s_cbranch_vccnz .LBB0_334
	v_and_b32_e32 v240, 15, v230
	v_and_b32_e32 v238, 3, v240
	v_lshlrev_b32_e32 v238, 2, v238
	v_and_b32_e32 v241, 4, v240
	v_lshlrev_b32_e32 v241, 4, v241
	v_or_b32_e32 v238, v238, v241
	v_and_b32_e32 v241, 8, v240
	v_lshlrev_b32_e32 v241, 6, v241
	v_or_b32_e32 v238, v238, v241
	v_mov_b32_e32 v239, 0
	v_lshl_add_u64 v[242:243], v[168:169], 0, v[238:239]
	v_lshl_add_u64 v[244:245], v[166:167], 0, v[238:239]
	global_load_dword v236, v[242:243], off
	global_load_dword v237, v[244:245], off
	s_waitcnt vmcnt(0)
	v_mul_f32_e32 v236, s64, v236
	v_mul_f32_e32 v237, s64, v237
	s_nop 1
	v_mov_b32_dpp v206, v236 row_newbcast:2 row_mask:0xf bank_mask:0xf
	v_mov_b32_dpp v207, v236 row_newbcast:3 row_mask:0xf bank_mask:0xf
	v_mov_b32_dpp v208, v236 row_newbcast:0 row_mask:0xf bank_mask:0xf
	v_mov_b32_dpp v209, v236 row_newbcast:1 row_mask:0xf bank_mask:0xf
	v_mov_b32_dpp v210, v237 row_newbcast:2 row_mask:0xf bank_mask:0xf
	v_mov_b32_dpp v211, v237 row_newbcast:3 row_mask:0xf bank_mask:0xf
	v_mov_b32_dpp v212, v237 row_newbcast:0 row_mask:0xf bank_mask:0xf
	v_mov_b32_dpp v213, v237 row_newbcast:1 row_mask:0xf bank_mask:0xf
.LBB0_334:
	s_waitcnt vmcnt(0)
	v_mov_b32_e32 v180, v183
	v_mov_b32_e32 v176, v179
	v_sub_f32_e32 v159, v159, v182
	v_sub_f32_e32 v158, v158, v182
	v_pk_mul_f32 v[158:159], v[180:181], v[158:159] op_sel_hi:[0,1]
	v_pk_fma_f32 v[158:159], v[158:159], v[206:207], v[210:211]
	v_sub_f32_e32 v157, v157, v182
	v_sub_f32_e32 v156, v156, v182
	v_pk_add_f32 v[158:159], v[158:159], v[126:127]
	v_sub_f32_e32 v127, v153, v178
	v_sub_f32_e32 v126, v152, v178
	v_sub_f32_e32 v153, v155, v178
	v_sub_f32_e32 v152, v154, v178
	v_pk_mul_f32 v[156:157], v[180:181], v[156:157] op_sel_hi:[0,1]
	v_pk_mul_f32 v[152:153], v[176:177], v[152:153] op_sel_hi:[0,1]
	v_pk_mul_f32 v[126:127], v[176:177], v[126:127] op_sel_hi:[0,1]
	v_pk_fma_f32 v[156:157], v[156:157], v[208:209], v[212:213]
	v_pk_fma_f32 v[126:127], v[126:127], v[208:209], v[212:213]
	v_pk_fma_f32 v[152:153], v[152:153], v[206:207], v[210:211]
	v_pk_add_f32 v[156:157], v[156:157], v[124:125]
	v_lshl_add_u64 v[124:125], s[84:85], 0, v[188:189]
	v_pk_add_f32 v[154:155], v[152:153], v[122:123]
	v_pk_add_f32 v[152:153], v[126:127], v[120:121]
	v_lshl_add_u64 v[120:121], s[84:85], 0, v[190:191]
	v_lshl_add_u64 v[124:125], v[124:125], 0, v[170:171]
	v_lshl_add_u64 v[120:121], v[120:121], 0, v[170:171]
	global_store_dwordx4 v[124:125], v[156:159], off
	global_store_dwordx4 v[120:121], v[152:155], off
	s_and_b64 vcc, exec, s[44:45]
	v_mov_b32_e32 v185, 0x3fd744fd
	v_mov_b32_e32 v126, 0x3fd744fd
	v_mov_b32_e32 v127, 0x3fd744fd
	v_mov_b32_e32 v187, 0
	v_mov_b32_e32 v152, 0
	v_mov_b32_e32 v153, 0
	s_cbranch_vccnz .LBB0_336
	v_mov_b32_dpp v126, v236 row_newbcast:6 row_mask:0xf bank_mask:0xf
	v_mov_b32_dpp v127, v236 row_newbcast:7 row_mask:0xf bank_mask:0xf
	v_mov_b32_dpp v184, v236 row_newbcast:4 row_mask:0xf bank_mask:0xf
	v_mov_b32_dpp v185, v236 row_newbcast:5 row_mask:0xf bank_mask:0xf
	v_mov_b32_dpp v152, v237 row_newbcast:6 row_mask:0xf bank_mask:0xf
	v_mov_b32_dpp v153, v237 row_newbcast:7 row_mask:0xf bank_mask:0xf
	v_mov_b32_dpp v186, v237 row_newbcast:4 row_mask:0xf bank_mask:0xf
	v_mov_b32_dpp v187, v237 row_newbcast:5 row_mask:0xf bank_mask:0xf
;     __device__ __forceinline__ void operator()(const Acc& acc, const Unit& u, int wr, int wc, int fr, int fq) const {
;     ...
;                 for (int mm = 0; mm < 2; ++mm) { const int row = row0 + ai * HALF + (2 * mh + mm) * 16; const size_t off = (size_t)row * D + col0;
;                     sv[mm] = st ? st[row] : (f32x2){0.f, 1.f};
; #pragma unroll
;                     for (int bj = 0; bj < 2; ++bj)
; #pragma unroll
;                         for (int n = 0; n < 2; ++n) pre[mm][bj][n] = *(const f32x4*)(base + off + bj * HALF + n * 16); }
;                 asm volatile("" ::: "memory");
; #pragma unroll
;                 for (int bj = 0; bj < 2; ++bj)
; #pragma unroll
;                     for (int n = 0; n < 2; ++n) { f32x4 gv = (f32x4){ALPHA, ALPHA, ALPHA, ALPHA}, bv = (f32x4){0.f, 0.f, 0.f, 0.f};
;                         if (st) { gv = *(const f32x4*)(g + col0 + bj * HALF + n * 16) * ALPHA; bv = *(const f32x4*)(b + col0 + bj * HALF + n * 16) * ALPHA; }
; #pragma unroll
;                         for (int mm = 0; mm < 2; ++mm) { const int m = 2 * mh + mm; const size_t off = (size_t)(row0 + ai * HALF + m * 16) * D + col0;
;                             *(f32x4*)(out + off + bj * HALF + n * 16) = ((pre[mm][bj][n] - sv[mm].x) * sv[mm].y) * gv + bv + acc[ai][bj][m][n] * scale; } }
.LBB0_336:
	v_mov_b32_e32 v181, v180
	v_sub_f32_e32 v149, v149, v182
	v_sub_f32_e32 v148, v148, v182
	v_sub_f32_e32 v151, v151, v182
	v_sub_f32_e32 v150, v150, v182
	v_mov_b32_e32 v122, v180
	v_mov_b32_e32 v123, v180
	v_pk_mul_f32 v[150:151], v[122:123], v[150:151]
	v_pk_mul_f32 v[148:149], v[180:181], v[148:149]
	v_pk_fma_f32 v[150:151], v[150:151], v[126:127], v[152:153]
	v_pk_fma_f32 v[148:149], v[148:149], v[184:185], v[186:187]
	v_pk_add_f32 v[118:119], v[118:119], v[150:151]
	v_pk_add_f32 v[116:117], v[116:117], v[148:149]
	v_mov_b32_e32 v177, v176
	global_store_dwordx4 v[124:125], v[116:119], off offset:64
	s_and_b64 vcc, exec, s[44:45]
	s_nop 0
	v_sub_f32_e32 v119, v145, v178
	v_sub_f32_e32 v118, v144, v178
	v_sub_f32_e32 v145, v147, v178
	v_sub_f32_e32 v144, v146, v178
	v_mov_b32_e32 v116, v176
	v_mov_b32_e32 v117, v176
	v_pk_mul_f32 v[144:145], v[116:117], v[144:145]
	v_pk_mul_f32 v[118:119], v[176:177], v[118:119]
	v_pk_fma_f32 v[126:127], v[144:145], v[126:127], v[152:153]
	v_pk_fma_f32 v[118:119], v[118:119], v[184:185], v[186:187]
	v_pk_add_f32 v[114:115], v[114:115], v[126:127]
	v_pk_add_f32 v[112:113], v[112:113], v[118:119]
	global_store_dwordx4 v[120:121], v[112:115], off offset:64
	v_mov_b32_e32 v126, 0x3fd744fd
	v_mov_b32_e32 v127, 0x3fd744fd
	v_mov_b32_e32 v114, 0
	v_mov_b32_e32 v112, 0x3fd744fd
	v_mov_b32_e32 v118, 0x3fd744fd
	v_mov_b32_e32 v119, 0x3fd744fd
	v_mov_b32_e32 v146, 0
	v_mov_b32_e32 v147, 0
	v_mov_b32_e32 v144, 0
	v_mov_b32_e32 v145, 0
	s_cbranch_vccnz .LBB0_338
	v_mov_b32_dpp v118, v236 row_newbcast:10 row_mask:0xf bank_mask:0xf
	v_mov_b32_dpp v119, v236 row_newbcast:11 row_mask:0xf bank_mask:0xf
	v_mov_b32_dpp v126, v236 row_newbcast:8 row_mask:0xf bank_mask:0xf
	v_mov_b32_dpp v127, v236 row_newbcast:9 row_mask:0xf bank_mask:0xf
	v_mov_b32_dpp v144, v237 row_newbcast:10 row_mask:0xf bank_mask:0xf
	v_mov_b32_dpp v145, v237 row_newbcast:11 row_mask:0xf bank_mask:0xf
	v_mov_b32_dpp v146, v237 row_newbcast:8 row_mask:0xf bank_mask:0xf
	v_mov_b32_dpp v147, v237 row_newbcast:9 row_mask:0xf bank_mask:0xf
.LBB0_338:
	v_sub_f32_e32 v141, v141, v182
	v_sub_f32_e32 v140, v140, v182
	v_sub_f32_e32 v143, v143, v182
	v_sub_f32_e32 v142, v142, v182
	v_pk_mul_f32 v[122:123], v[122:123], v[142:143]
	v_pk_mul_f32 v[140:141], v[180:181], v[140:141]
	v_pk_fma_f32 v[122:123], v[122:123], v[118:119], v[144:145]
	v_pk_fma_f32 v[140:141], v[140:141], v[126:127], v[146:147]
	v_pk_add_f32 v[110:111], v[110:111], v[122:123]
	v_pk_add_f32 v[108:109], v[108:109], v[140:141]
	global_store_dwordx4 v[124:125], v[108:111], off offset:512
	s_and_b64 vcc, exec, s[44:45]
	v_mov_b32_e32 v113, 0x3fd744fd
	v_sub_f32_e32 v109, v137, v178
	v_sub_f32_e32 v108, v136, v178
	v_sub_f32_e32 v111, v139, v178
	v_sub_f32_e32 v110, v138, v178
	v_pk_mul_f32 v[110:111], v[116:117], v[110:111]
	v_pk_mul_f32 v[108:109], v[176:177], v[108:109]
	v_pk_fma_f32 v[110:111], v[110:111], v[118:119], v[144:145]
	v_pk_fma_f32 v[108:109], v[108:109], v[126:127], v[146:147]
	v_pk_add_f32 v[106:107], v[106:107], v[110:111]
	v_pk_add_f32 v[104:105], v[104:105], v[108:109]
	global_store_dwordx4 v[120:121], v[104:107], off offset:512
	v_mov_b32_e32 v115, 0
	s_nop 0
	v_mov_b32_e32 v104, 0x3fd744fd
	v_mov_b32_e32 v105, 0x3fd744fd
	v_mov_b32_e32 v106, 0
	v_mov_b32_e32 v107, 0
	s_cbranch_vccnz .LBB0_340
	v_mov_b32_dpp v104, v236 row_newbcast:14 row_mask:0xf bank_mask:0xf
	v_mov_b32_dpp v105, v236 row_newbcast:15 row_mask:0xf bank_mask:0xf
	v_mov_b32_dpp v112, v236 row_newbcast:12 row_mask:0xf bank_mask:0xf
	v_mov_b32_dpp v113, v236 row_newbcast:13 row_mask:0xf bank_mask:0xf
	v_mov_b32_dpp v106, v237 row_newbcast:14 row_mask:0xf bank_mask:0xf
	v_mov_b32_dpp v107, v237 row_newbcast:15 row_mask:0xf bank_mask:0xf
	v_mov_b32_dpp v114, v237 row_newbcast:12 row_mask:0xf bank_mask:0xf
	v_mov_b32_dpp v115, v237 row_newbcast:13 row_mask:0xf bank_mask:0xf
.LBB0_340:
	v_sub_f32_e32 v109, v133, v182
	v_sub_f32_e32 v108, v132, v182
	v_sub_f32_e32 v111, v135, v182
	v_sub_f32_e32 v110, v134, v182
	v_mov_b32_e32 v116, v180
	v_mov_b32_e32 v117, v180
	v_pk_mul_f32 v[110:111], v[116:117], v[110:111]
	v_pk_mul_f32 v[108:109], v[180:181], v[108:109]
	v_pk_fma_f32 v[110:111], v[110:111], v[104:105], v[106:107]
	v_pk_fma_f32 v[108:109], v[108:109], v[112:113], v[114:115]
	v_pk_add_f32 v[102:103], v[102:103], v[110:111]
	v_pk_add_f32 v[100:101], v[100:101], v[108:109]
	global_store_dwordx4 v[124:125], v[100:103], off offset:576
	v_mov_b32_e32 v108, v176
	v_mov_b32_e32 v109, v176
	v_sub_f32_e32 v101, v129, v178
	v_sub_f32_e32 v100, v128, v178
	v_sub_f32_e32 v103, v131, v178
	v_sub_f32_e32 v102, v130, v178
	v_pk_mul_f32 v[102:103], v[108:109], v[102:103]
	v_pk_mul_f32 v[100:101], v[176:177], v[100:101]
	v_pk_fma_f32 v[102:103], v[102:103], v[104:105], v[106:107]
	v_pk_fma_f32 v[100:101], v[100:101], v[112:113], v[114:115]
	v_pk_add_f32 v[98:99], v[98:99], v[102:103]
	v_pk_add_f32 v[96:97], v[96:97], v[100:101]
	global_store_dwordx4 v[120:121], v[96:99], off offset:576
	v_mov_b32_e32 v128, 1.0
	v_mov_b32_e32 v130, 0
	v_add_u32_e32 v96, 32, v172
	v_ashrrev_i32_e32 v97, 31, v96
	s_and_b64 vcc, exec, s[44:45]
	v_mov_b32_e32 v134, 0
	v_mov_b32_e32 v132, 1.0
	v_mov_b32_e32 v135, 1.0
	s_cbranch_vccnz .LBB0_342
	v_lshl_add_u64 v[98:99], v[96:97], 3, s[4:5]
	global_load_dwordx2 v[134:135], v[98:99], off
.LBB0_342:
	v_lshlrev_b64 v[140:141], 12, v[96:97]
	v_lshl_add_u64 v[96:97], v[174:175], 0, v[140:141]
	global_load_dwordx4 v[124:127], v[96:97], off
	global_load_dwordx4 v[116:119], v[96:97], off offset:64
	global_load_dwordx4 v[108:111], v[96:97], off offset:512
	global_load_dwordx4 v[100:103], v[96:97], off offset:576
	v_add_u32_e32 v96, 48, v172
	s_and_b64 vcc, exec, s[44:45]
	v_ashrrev_i32_e32 v97, 31, v96
	v_mov_b32_e32 v131, 1.0
	s_cbranch_vccnz .LBB0_344
	v_lshl_add_u64 v[98:99], v[96:97], 3, s[4:5]
	global_load_dwordx2 v[130:131], v[98:99], off
;     __device__ __forceinline__ void operator()(const Acc& acc, const Unit& u, int wr, int wc, int fr, int fq) const {
;     ...
;                 for (int mm = 0; mm < 2; ++mm) { const int row = row0 + ai * HALF + (2 * mh + mm) * 16; const size_t off = (size_t)row * D + col0;
;                     sv[mm] = st ? st[row] : (f32x2){0.f, 1.f};
; #pragma unroll
;                     for (int bj = 0; bj < 2; ++bj)
; #pragma unroll
;                         for (int n = 0; n < 2; ++n) pre[mm][bj][n] = *(const f32x4*)(base + off + bj * HALF + n * 16); }
;                 asm volatile("" ::: "memory");
; #pragma unroll
;                 for (int bj = 0; bj < 2; ++bj)
; #pragma unroll
;                     for (int n = 0; n < 2; ++n) { f32x4 gv = (f32x4){ALPHA, ALPHA, ALPHA, ALPHA}, bv = (f32x4){0.f, 0.f, 0.f, 0.f};
;                         if (st) { gv = *(const f32x4*)(g + col0 + bj * HALF + n * 16) * ALPHA; bv = *(const f32x4*)(b + col0 + bj * HALF + n * 16) * ALPHA; }
; #pragma unroll
;                         for (int mm = 0; mm < 2; ++mm) { const int m = 2 * mh + mm; const size_t off = (size_t)(row0 + ai * HALF + m * 16) * D + col0;
;                             *(f32x4*)(out + off + bj * HALF + n * 16) = ((pre[mm][bj][n] - sv[mm].x) * sv[mm].y) * gv + bv + acc[ai][bj][m][n] * scale; } }
.LBB0_344:
	v_lshlrev_b64 v[142:143], 12, v[96:97]
	v_lshl_add_u64 v[96:97], v[174:175], 0, v[142:143]
	global_load_dwordx4 v[120:123], v[96:97], off
	global_load_dwordx4 v[112:115], v[96:97], off offset:64
	global_load_dwordx4 v[104:107], v[96:97], off offset:512
	s_nop 0
	global_load_dwordx4 v[96:99], v[96:97], off offset:576
	v_mov_b32_e32 v138, 0
	v_mov_b32_e32 v136, 0x3fd744fd
	s_and_b64 vcc, exec, s[44:45]
	v_mov_b32_e32 v146, 0x3fd744fd
	v_mov_b32_e32 v147, 0x3fd744fd
	v_mov_b32_e32 v144, 0x3fd744fd
	v_mov_b32_e32 v145, 0x3fd744fd
	v_mov_b32_e32 v150, 0
	v_mov_b32_e32 v151, 0
	v_mov_b32_e32 v148, 0
	v_mov_b32_e32 v149, 0
	s_cbranch_vccnz .LBB0_346
	v_mov_b32_dpp v144, v236 row_newbcast:2 row_mask:0xf bank_mask:0xf
	v_mov_b32_dpp v145, v236 row_newbcast:3 row_mask:0xf bank_mask:0xf
	v_mov_b32_dpp v146, v236 row_newbcast:0 row_mask:0xf bank_mask:0xf
	v_mov_b32_dpp v147, v236 row_newbcast:1 row_mask:0xf bank_mask:0xf
	v_mov_b32_dpp v148, v237 row_newbcast:2 row_mask:0xf bank_mask:0xf
	v_mov_b32_dpp v149, v237 row_newbcast:3 row_mask:0xf bank_mask:0xf
	v_mov_b32_dpp v150, v237 row_newbcast:0 row_mask:0xf bank_mask:0xf
	v_mov_b32_dpp v151, v237 row_newbcast:1 row_mask:0xf bank_mask:0xf
.LBB0_346:
	s_waitcnt vmcnt(7)
	v_mov_b32_e32 v132, v135
	v_sub_f32_e32 v127, v127, v134
	v_sub_f32_e32 v126, v126, v134
	v_pk_mul_f32 v[126:127], v[132:133], v[126:127] op_sel_hi:[0,1]
	v_pk_fma_f32 v[126:127], v[126:127], v[144:145], v[148:149]
	v_sub_f32_e32 v125, v125, v134
	v_sub_f32_e32 v124, v124, v134
	v_pk_add_f32 v[126:127], v[94:95], v[126:127]
	s_waitcnt vmcnt(3)
	v_mov_b32_e32 v128, v131
	v_sub_f32_e32 v95, v121, v130
	v_sub_f32_e32 v94, v120, v130
	v_sub_f32_e32 v121, v123, v130
	v_sub_f32_e32 v120, v122, v130
	v_pk_mul_f32 v[124:125], v[132:133], v[124:125] op_sel_hi:[0,1]
	v_pk_mul_f32 v[120:121], v[128:129], v[120:121] op_sel_hi:[0,1]
	v_pk_mul_f32 v[94:95], v[128:129], v[94:95] op_sel_hi:[0,1]
	v_pk_fma_f32 v[124:125], v[124:125], v[146:147], v[150:151]
	v_pk_fma_f32 v[94:95], v[94:95], v[146:147], v[150:151]
	v_pk_fma_f32 v[120:121], v[120:121], v[144:145], v[148:149]
	v_pk_add_f32 v[124:125], v[92:93], v[124:125]
	v_lshl_add_u64 v[92:93], s[84:85], 0, v[140:141]
	v_pk_add_f32 v[122:123], v[90:91], v[120:121]
	v_pk_add_f32 v[120:121], v[88:89], v[94:95]
	v_lshl_add_u64 v[88:89], s[84:85], 0, v[142:143]
	v_lshl_add_u64 v[92:93], v[92:93], 0, v[170:171]
	v_lshl_add_u64 v[88:89], v[88:89], 0, v[170:171]
	global_store_dwordx4 v[92:93], v[124:127], off
	global_store_dwordx4 v[88:89], v[120:123], off
	s_and_b64 vcc, exec, s[44:45]
	v_mov_b32_e32 v137, 0x3fd744fd
	v_mov_b32_e32 v94, 0x3fd744fd
	v_mov_b32_e32 v95, 0x3fd744fd
	v_mov_b32_e32 v139, 0
	v_mov_b32_e32 v120, 0
	v_mov_b32_e32 v121, 0
	s_cbranch_vccnz .LBB0_348
	v_mov_b32_dpp v94, v236 row_newbcast:6 row_mask:0xf bank_mask:0xf
	v_mov_b32_dpp v95, v236 row_newbcast:7 row_mask:0xf bank_mask:0xf
	v_mov_b32_dpp v136, v236 row_newbcast:4 row_mask:0xf bank_mask:0xf
	v_mov_b32_dpp v137, v236 row_newbcast:5 row_mask:0xf bank_mask:0xf
	v_mov_b32_dpp v120, v237 row_newbcast:6 row_mask:0xf bank_mask:0xf
	v_mov_b32_dpp v121, v237 row_newbcast:7 row_mask:0xf bank_mask:0xf
	v_mov_b32_dpp v138, v237 row_newbcast:4 row_mask:0xf bank_mask:0xf
	v_mov_b32_dpp v139, v237 row_newbcast:5 row_mask:0xf bank_mask:0xf
.LBB0_348:
	v_mov_b32_e32 v133, v132
	v_sub_f32_e32 v117, v117, v134
	v_sub_f32_e32 v116, v116, v134
	v_sub_f32_e32 v119, v119, v134
	v_sub_f32_e32 v118, v118, v134
	v_mov_b32_e32 v90, v132
	v_mov_b32_e32 v91, v132
	v_pk_mul_f32 v[118:119], v[90:91], v[118:119]
	v_pk_mul_f32 v[116:117], v[132:133], v[116:117]
	v_pk_fma_f32 v[118:119], v[118:119], v[94:95], v[120:121]
	v_pk_fma_f32 v[116:117], v[116:117], v[136:137], v[138:139]
	v_pk_add_f32 v[86:87], v[86:87], v[118:119]
	v_pk_add_f32 v[84:85], v[84:85], v[116:117]
	v_mov_b32_e32 v129, v128
	global_store_dwordx4 v[92:93], v[84:87], off offset:64
	s_and_b64 vcc, exec, s[44:45]
	s_waitcnt vmcnt(5)
	v_sub_f32_e32 v87, v113, v130
	v_sub_f32_e32 v86, v112, v130
	v_sub_f32_e32 v113, v115, v130
	v_sub_f32_e32 v112, v114, v130
	v_mov_b32_e32 v84, v128
	v_mov_b32_e32 v85, v128
	v_pk_mul_f32 v[112:113], v[84:85], v[112:113]
	v_pk_mul_f32 v[86:87], v[128:129], v[86:87]
	v_pk_fma_f32 v[94:95], v[112:113], v[94:95], v[120:121]
	v_pk_fma_f32 v[86:87], v[86:87], v[136:137], v[138:139]
	v_pk_add_f32 v[82:83], v[82:83], v[94:95]
	v_pk_add_f32 v[80:81], v[80:81], v[86:87]
	global_store_dwordx4 v[88:89], v[80:83], off offset:64
	v_mov_b32_e32 v94, 0x3fd744fd
	v_mov_b32_e32 v95, 0x3fd744fd
	v_mov_b32_e32 v82, 0
	v_mov_b32_e32 v80, 0x3fd744fd
	v_mov_b32_e32 v86, 0x3fd744fd
	v_mov_b32_e32 v87, 0x3fd744fd
	v_mov_b32_e32 v114, 0
	v_mov_b32_e32 v115, 0
	v_mov_b32_e32 v112, 0
	v_mov_b32_e32 v113, 0
	s_cbranch_vccnz .LBB0_350
	v_mov_b32_dpp v86, v236 row_newbcast:10 row_mask:0xf bank_mask:0xf
	v_mov_b32_dpp v87, v236 row_newbcast:11 row_mask:0xf bank_mask:0xf
	v_mov_b32_dpp v94, v236 row_newbcast:8 row_mask:0xf bank_mask:0xf
	v_mov_b32_dpp v95, v236 row_newbcast:9 row_mask:0xf bank_mask:0xf
	v_mov_b32_dpp v112, v237 row_newbcast:10 row_mask:0xf bank_mask:0xf
	v_mov_b32_dpp v113, v237 row_newbcast:11 row_mask:0xf bank_mask:0xf
	v_mov_b32_dpp v114, v237 row_newbcast:8 row_mask:0xf bank_mask:0xf
	v_mov_b32_dpp v115, v237 row_newbcast:9 row_mask:0xf bank_mask:0xf
;     __device__ __forceinline__ void operator()(const Acc& acc, const Unit& u, int wr, int wc, int fr, int fq) const {
;     ...
;                 for (int mm = 0; mm < 2; ++mm) { const int row = row0 + ai * HALF + (2 * mh + mm) * 16; const size_t off = (size_t)row * D + col0;
;                     sv[mm] = st ? st[row] : (f32x2){0.f, 1.f};
; #pragma unroll
;                     for (int bj = 0; bj < 2; ++bj)
; #pragma unroll
;                         for (int n = 0; n < 2; ++n) pre[mm][bj][n] = *(const f32x4*)(base + off + bj * HALF + n * 16); }
;                 asm volatile("" ::: "memory");
; #pragma unroll
;                 for (int bj = 0; bj < 2; ++bj)
; #pragma unroll
;                     for (int n = 0; n < 2; ++n) { f32x4 gv = (f32x4){ALPHA, ALPHA, ALPHA, ALPHA}, bv = (f32x4){0.f, 0.f, 0.f, 0.f};
;                         if (st) { gv = *(const f32x4*)(g + col0 + bj * HALF + n * 16) * ALPHA; bv = *(const f32x4*)(b + col0 + bj * HALF + n * 16) * ALPHA; }
; #pragma unroll
;                         for (int mm = 0; mm < 2; ++mm) { const int m = 2 * mh + mm; const size_t off = (size_t)(row0 + ai * HALF + m * 16) * D + col0;
;                             *(f32x4*)(out + off + bj * HALF + n * 16) = ((pre[mm][bj][n] - sv[mm].x) * sv[mm].y) * gv + bv + acc[ai][bj][m][n] * scale; } }
.LBB0_350:
	v_sub_f32_e32 v109, v109, v134
	v_sub_f32_e32 v108, v108, v134
	v_sub_f32_e32 v111, v111, v134
	v_sub_f32_e32 v110, v110, v134
	v_pk_mul_f32 v[90:91], v[90:91], v[110:111]
	v_pk_mul_f32 v[108:109], v[132:133], v[108:109]
	v_pk_fma_f32 v[90:91], v[90:91], v[86:87], v[112:113]
	v_pk_fma_f32 v[108:109], v[108:109], v[94:95], v[114:115]
	v_pk_add_f32 v[78:79], v[78:79], v[90:91]
	v_pk_add_f32 v[76:77], v[76:77], v[108:109]
	global_store_dwordx4 v[92:93], v[76:79], off offset:512
	s_and_b64 vcc, exec, s[44:45]
	v_mov_b32_e32 v81, 0x3fd744fd
	s_waitcnt vmcnt(6)
	v_sub_f32_e32 v77, v105, v130
	v_sub_f32_e32 v76, v104, v130
	v_sub_f32_e32 v79, v107, v130
	v_sub_f32_e32 v78, v106, v130
	v_pk_mul_f32 v[78:79], v[84:85], v[78:79]
	v_pk_mul_f32 v[76:77], v[128:129], v[76:77]
	v_pk_fma_f32 v[78:79], v[78:79], v[86:87], v[112:113]
	v_pk_fma_f32 v[76:77], v[76:77], v[94:95], v[114:115]
	v_pk_add_f32 v[74:75], v[74:75], v[78:79]
	v_pk_add_f32 v[72:73], v[72:73], v[76:77]
	global_store_dwordx4 v[88:89], v[72:75], off offset:512
	v_mov_b32_e32 v83, 0
	s_nop 0
	v_mov_b32_e32 v72, 0x3fd744fd
	v_mov_b32_e32 v73, 0x3fd744fd
	v_mov_b32_e32 v74, 0
	v_mov_b32_e32 v75, 0
	s_cbranch_vccnz .LBB0_352
	v_mov_b32_dpp v72, v236 row_newbcast:14 row_mask:0xf bank_mask:0xf
	v_mov_b32_dpp v73, v236 row_newbcast:15 row_mask:0xf bank_mask:0xf
	v_mov_b32_dpp v80, v236 row_newbcast:12 row_mask:0xf bank_mask:0xf
	v_mov_b32_dpp v81, v236 row_newbcast:13 row_mask:0xf bank_mask:0xf
	v_mov_b32_dpp v74, v237 row_newbcast:14 row_mask:0xf bank_mask:0xf
	v_mov_b32_dpp v75, v237 row_newbcast:15 row_mask:0xf bank_mask:0xf
	v_mov_b32_dpp v82, v237 row_newbcast:12 row_mask:0xf bank_mask:0xf
	v_mov_b32_dpp v83, v237 row_newbcast:13 row_mask:0xf bank_mask:0xf
.LBB0_352:
	v_sub_f32_e32 v77, v101, v134
	v_sub_f32_e32 v76, v100, v134
	v_sub_f32_e32 v79, v103, v134
	v_sub_f32_e32 v78, v102, v134
	v_mov_b32_e32 v84, v132
	v_mov_b32_e32 v85, v132
	v_pk_mul_f32 v[78:79], v[84:85], v[78:79]
	v_pk_mul_f32 v[76:77], v[132:133], v[76:77]
	v_pk_fma_f32 v[78:79], v[78:79], v[72:73], v[74:75]
	v_pk_fma_f32 v[76:77], v[76:77], v[80:81], v[82:83]
	v_pk_add_f32 v[70:71], v[70:71], v[78:79]
	v_pk_add_f32 v[68:69], v[68:69], v[76:77]
	global_store_dwordx4 v[92:93], v[68:71], off offset:576
	v_mov_b32_e32 v76, v128
	v_mov_b32_e32 v77, v128
	s_waitcnt vmcnt(7)
	v_sub_f32_e32 v69, v97, v130
	v_sub_f32_e32 v68, v96, v130
	v_sub_f32_e32 v71, v99, v130
	v_sub_f32_e32 v70, v98, v130
	v_pk_mul_f32 v[70:71], v[76:77], v[70:71]
	v_pk_mul_f32 v[68:69], v[128:129], v[68:69]
	v_pk_fma_f32 v[70:71], v[70:71], v[72:73], v[74:75]
	v_pk_fma_f32 v[68:69], v[68:69], v[80:81], v[82:83]
	v_pk_add_f32 v[66:67], v[66:67], v[70:71]
	v_pk_add_f32 v[64:65], v[64:65], v[68:69]
	global_store_dwordx4 v[88:89], v[64:67], off offset:576
	v_mov_b32_e32 v96, 1.0
	v_mov_b32_e32 v98, 0
	v_add_u32_e32 v64, 0x80, v172
	v_ashrrev_i32_e32 v65, 31, v64
	s_and_b64 vcc, exec, s[44:45]
	v_mov_b32_e32 v102, 0
	v_mov_b32_e32 v100, 1.0
	v_mov_b32_e32 v103, 1.0
	s_cbranch_vccnz .LBB0_354
	v_lshl_add_u64 v[66:67], v[64:65], 3, s[4:5]
	global_load_dwordx2 v[102:103], v[66:67], off
.LBB0_354:
	v_lshlrev_b64 v[108:109], 12, v[64:65]
	v_lshl_add_u64 v[64:65], v[174:175], 0, v[108:109]
	global_load_dwordx4 v[92:95], v[64:65], off
	global_load_dwordx4 v[84:87], v[64:65], off offset:64
	global_load_dwordx4 v[76:79], v[64:65], off offset:512
	global_load_dwordx4 v[68:71], v[64:65], off offset:576
	v_add_u32_e32 v64, 0x90, v172
	s_and_b64 vcc, exec, s[44:45]
	v_ashrrev_i32_e32 v65, 31, v64
	v_mov_b32_e32 v99, 1.0
	s_cbranch_vccnz .LBB0_356
	v_lshl_add_u64 v[66:67], v[64:65], 3, s[4:5]
	global_load_dwordx2 v[98:99], v[66:67], off
.LBB0_356:
	v_lshlrev_b64 v[110:111], 12, v[64:65]
	v_lshl_add_u64 v[64:65], v[174:175], 0, v[110:111]
	global_load_dwordx4 v[88:91], v[64:65], off
	global_load_dwordx4 v[80:83], v[64:65], off offset:64
	global_load_dwordx4 v[72:75], v[64:65], off offset:512
	s_nop 0
	global_load_dwordx4 v[64:67], v[64:65], off offset:576
	v_mov_b32_e32 v106, 0
	v_mov_b32_e32 v104, 0x3fd744fd
	s_and_b64 vcc, exec, s[44:45]
	v_mov_b32_e32 v114, 0x3fd744fd
	v_mov_b32_e32 v115, 0x3fd744fd
	v_mov_b32_e32 v112, 0x3fd744fd
	v_mov_b32_e32 v113, 0x3fd744fd
	v_mov_b32_e32 v118, 0
	v_mov_b32_e32 v119, 0
	v_mov_b32_e32 v116, 0
	v_mov_b32_e32 v117, 0
	s_cbranch_vccnz .LBB0_358
	v_mov_b32_dpp v112, v236 row_newbcast:2 row_mask:0xf bank_mask:0xf
	v_mov_b32_dpp v113, v236 row_newbcast:3 row_mask:0xf bank_mask:0xf
	v_mov_b32_dpp v114, v236 row_newbcast:0 row_mask:0xf bank_mask:0xf
	v_mov_b32_dpp v115, v236 row_newbcast:1 row_mask:0xf bank_mask:0xf
	v_mov_b32_dpp v116, v237 row_newbcast:2 row_mask:0xf bank_mask:0xf
	v_mov_b32_dpp v117, v237 row_newbcast:3 row_mask:0xf bank_mask:0xf
	v_mov_b32_dpp v118, v237 row_newbcast:0 row_mask:0xf bank_mask:0xf
	v_mov_b32_dpp v119, v237 row_newbcast:1 row_mask:0xf bank_mask:0xf
;     __device__ __forceinline__ void operator()(const Acc& acc, const Unit& u, int wr, int wc, int fr, int fq) const {
;     ...
;                 for (int mm = 0; mm < 2; ++mm) { const int row = row0 + ai * HALF + (2 * mh + mm) * 16; const size_t off = (size_t)row * D + col0;
;                     sv[mm] = st ? st[row] : (f32x2){0.f, 1.f};
; #pragma unroll
;                     for (int bj = 0; bj < 2; ++bj)
; #pragma unroll
;                         for (int n = 0; n < 2; ++n) pre[mm][bj][n] = *(const f32x4*)(base + off + bj * HALF + n * 16); }
;                 asm volatile("" ::: "memory");
; #pragma unroll
;                 for (int bj = 0; bj < 2; ++bj)
; #pragma unroll
;                     for (int n = 0; n < 2; ++n) { f32x4 gv = (f32x4){ALPHA, ALPHA, ALPHA, ALPHA}, bv = (f32x4){0.f, 0.f, 0.f, 0.f};
;                         if (st) { gv = *(const f32x4*)(g + col0 + bj * HALF + n * 16) * ALPHA; bv = *(const f32x4*)(b + col0 + bj * HALF + n * 16) * ALPHA; }
; #pragma unroll
;                         for (int mm = 0; mm < 2; ++mm) { const int m = 2 * mh + mm; const size_t off = (size_t)(row0 + ai * HALF + m * 16) * D + col0;
;                             *(f32x4*)(out + off + bj * HALF + n * 16) = ((pre[mm][bj][n] - sv[mm].x) * sv[mm].y) * gv + bv + acc[ai][bj][m][n] * scale; } }
.LBB0_358:
	s_waitcnt vmcnt(7)
	v_mov_b32_e32 v100, v103
	v_sub_f32_e32 v95, v95, v102
	v_sub_f32_e32 v94, v94, v102
	v_pk_mul_f32 v[94:95], v[100:101], v[94:95] op_sel_hi:[0,1]
	v_pk_fma_f32 v[94:95], v[94:95], v[112:113], v[116:117]
	v_sub_f32_e32 v93, v93, v102
	v_sub_f32_e32 v92, v92, v102
	v_pk_add_f32 v[94:95], v[62:63], v[94:95]
	s_waitcnt vmcnt(3)
	v_mov_b32_e32 v96, v99
	v_sub_f32_e32 v63, v89, v98
	v_sub_f32_e32 v62, v88, v98
	v_sub_f32_e32 v89, v91, v98
	v_sub_f32_e32 v88, v90, v98
	v_pk_mul_f32 v[92:93], v[100:101], v[92:93] op_sel_hi:[0,1]
	v_pk_mul_f32 v[88:89], v[96:97], v[88:89] op_sel_hi:[0,1]
	v_pk_mul_f32 v[62:63], v[96:97], v[62:63] op_sel_hi:[0,1]
	v_pk_fma_f32 v[92:93], v[92:93], v[114:115], v[118:119]
	v_pk_fma_f32 v[62:63], v[62:63], v[114:115], v[118:119]
	v_pk_fma_f32 v[88:89], v[88:89], v[112:113], v[116:117]
	v_pk_add_f32 v[92:93], v[60:61], v[92:93]
	v_lshl_add_u64 v[60:61], s[84:85], 0, v[108:109]
	v_pk_add_f32 v[90:91], v[58:59], v[88:89]
	v_pk_add_f32 v[88:89], v[56:57], v[62:63]
	v_lshl_add_u64 v[56:57], s[84:85], 0, v[110:111]
	v_lshl_add_u64 v[60:61], v[60:61], 0, v[170:171]
	v_lshl_add_u64 v[56:57], v[56:57], 0, v[170:171]
	global_store_dwordx4 v[60:61], v[92:95], off
	global_store_dwordx4 v[56:57], v[88:91], off
	s_and_b64 vcc, exec, s[44:45]
	v_mov_b32_e32 v105, 0x3fd744fd
	v_mov_b32_e32 v62, 0x3fd744fd
	v_mov_b32_e32 v63, 0x3fd744fd
	v_mov_b32_e32 v107, 0
	v_mov_b32_e32 v88, 0
	v_mov_b32_e32 v89, 0
	s_cbranch_vccnz .LBB0_360
	v_mov_b32_dpp v62, v236 row_newbcast:6 row_mask:0xf bank_mask:0xf
	v_mov_b32_dpp v63, v236 row_newbcast:7 row_mask:0xf bank_mask:0xf
	v_mov_b32_dpp v104, v236 row_newbcast:4 row_mask:0xf bank_mask:0xf
	v_mov_b32_dpp v105, v236 row_newbcast:5 row_mask:0xf bank_mask:0xf
	v_mov_b32_dpp v88, v237 row_newbcast:6 row_mask:0xf bank_mask:0xf
	v_mov_b32_dpp v89, v237 row_newbcast:7 row_mask:0xf bank_mask:0xf
	v_mov_b32_dpp v106, v237 row_newbcast:4 row_mask:0xf bank_mask:0xf
	v_mov_b32_dpp v107, v237 row_newbcast:5 row_mask:0xf bank_mask:0xf
.LBB0_360:
	v_mov_b32_e32 v101, v100
	v_sub_f32_e32 v85, v85, v102
	v_sub_f32_e32 v84, v84, v102
	v_sub_f32_e32 v87, v87, v102
	v_sub_f32_e32 v86, v86, v102
	v_mov_b32_e32 v58, v100
	v_mov_b32_e32 v59, v100
	v_pk_mul_f32 v[86:87], v[58:59], v[86:87]
	v_pk_mul_f32 v[84:85], v[100:101], v[84:85]
	v_pk_fma_f32 v[86:87], v[86:87], v[62:63], v[88:89]
	v_pk_fma_f32 v[84:85], v[84:85], v[104:105], v[106:107]
	v_pk_add_f32 v[54:55], v[54:55], v[86:87]
	v_pk_add_f32 v[52:53], v[52:53], v[84:85]
	v_mov_b32_e32 v97, v96
	global_store_dwordx4 v[60:61], v[52:55], off offset:64
	s_and_b64 vcc, exec, s[44:45]
	s_waitcnt vmcnt(5)
	v_sub_f32_e32 v55, v81, v98
	v_sub_f32_e32 v54, v80, v98
	v_sub_f32_e32 v81, v83, v98
	v_sub_f32_e32 v80, v82, v98
	v_mov_b32_e32 v52, v96
	v_mov_b32_e32 v53, v96
	v_pk_mul_f32 v[80:81], v[52:53], v[80:81]
	v_pk_mul_f32 v[54:55], v[96:97], v[54:55]
	v_pk_fma_f32 v[62:63], v[80:81], v[62:63], v[88:89]
	v_pk_fma_f32 v[54:55], v[54:55], v[104:105], v[106:107]
	v_pk_add_f32 v[50:51], v[50:51], v[62:63]
	v_pk_add_f32 v[48:49], v[48:49], v[54:55]
	global_store_dwordx4 v[56:57], v[48:51], off offset:64
	v_mov_b32_e32 v62, 0x3fd744fd
	v_mov_b32_e32 v63, 0x3fd744fd
	v_mov_b32_e32 v50, 0
	v_mov_b32_e32 v48, 0x3fd744fd
	v_mov_b32_e32 v54, 0x3fd744fd
	v_mov_b32_e32 v55, 0x3fd744fd
	v_mov_b32_e32 v82, 0
	v_mov_b32_e32 v83, 0
	v_mov_b32_e32 v80, 0
	v_mov_b32_e32 v81, 0
	s_cbranch_vccnz .LBB0_362
	v_mov_b32_dpp v54, v236 row_newbcast:10 row_mask:0xf bank_mask:0xf
	v_mov_b32_dpp v55, v236 row_newbcast:11 row_mask:0xf bank_mask:0xf
	v_mov_b32_dpp v62, v236 row_newbcast:8 row_mask:0xf bank_mask:0xf
	v_mov_b32_dpp v63, v236 row_newbcast:9 row_mask:0xf bank_mask:0xf
	v_mov_b32_dpp v80, v237 row_newbcast:10 row_mask:0xf bank_mask:0xf
	v_mov_b32_dpp v81, v237 row_newbcast:11 row_mask:0xf bank_mask:0xf
	v_mov_b32_dpp v82, v237 row_newbcast:8 row_mask:0xf bank_mask:0xf
	v_mov_b32_dpp v83, v237 row_newbcast:9 row_mask:0xf bank_mask:0xf
.LBB0_362:
	v_sub_f32_e32 v77, v77, v102
	v_sub_f32_e32 v76, v76, v102
	v_sub_f32_e32 v79, v79, v102
	v_sub_f32_e32 v78, v78, v102
	v_pk_mul_f32 v[58:59], v[58:59], v[78:79]
	v_pk_mul_f32 v[76:77], v[100:101], v[76:77]
	v_pk_fma_f32 v[58:59], v[58:59], v[54:55], v[80:81]
	v_pk_fma_f32 v[76:77], v[76:77], v[62:63], v[82:83]
	v_pk_add_f32 v[46:47], v[46:47], v[58:59]
	v_pk_add_f32 v[44:45], v[44:45], v[76:77]
	global_store_dwordx4 v[60:61], v[44:47], off offset:512
	s_and_b64 vcc, exec, s[44:45]
	v_mov_b32_e32 v49, 0x3fd744fd
	s_waitcnt vmcnt(6)
	v_sub_f32_e32 v45, v73, v98
	v_sub_f32_e32 v44, v72, v98
	v_sub_f32_e32 v47, v75, v98
	v_sub_f32_e32 v46, v74, v98
	v_pk_mul_f32 v[46:47], v[52:53], v[46:47]
	v_pk_mul_f32 v[44:45], v[96:97], v[44:45]
	v_pk_fma_f32 v[46:47], v[46:47], v[54:55], v[80:81]
	v_pk_fma_f32 v[44:45], v[44:45], v[62:63], v[82:83]
	v_pk_add_f32 v[42:43], v[42:43], v[46:47]
	v_pk_add_f32 v[40:41], v[40:41], v[44:45]
	global_store_dwordx4 v[56:57], v[40:43], off offset:512
	v_mov_b32_e32 v51, 0
	s_nop 0
	v_mov_b32_e32 v40, 0x3fd744fd
	v_mov_b32_e32 v41, 0x3fd744fd
	v_mov_b32_e32 v42, 0
	v_mov_b32_e32 v43, 0
	s_cbranch_vccnz .LBB0_364
	v_mov_b32_dpp v40, v236 row_newbcast:14 row_mask:0xf bank_mask:0xf
	v_mov_b32_dpp v41, v236 row_newbcast:15 row_mask:0xf bank_mask:0xf
	v_mov_b32_dpp v48, v236 row_newbcast:12 row_mask:0xf bank_mask:0xf
	v_mov_b32_dpp v49, v236 row_newbcast:13 row_mask:0xf bank_mask:0xf
	v_mov_b32_dpp v42, v237 row_newbcast:14 row_mask:0xf bank_mask:0xf
	v_mov_b32_dpp v43, v237 row_newbcast:15 row_mask:0xf bank_mask:0xf
	v_mov_b32_dpp v50, v237 row_newbcast:12 row_mask:0xf bank_mask:0xf
	v_mov_b32_dpp v51, v237 row_newbcast:13 row_mask:0xf bank_mask:0xf
;     __device__ __forceinline__ void operator()(const Acc& acc, const Unit& u, int wr, int wc, int fr, int fq) const {
;     ...
;                 for (int mm = 0; mm < 2; ++mm) { const int row = row0 + ai * HALF + (2 * mh + mm) * 16; const size_t off = (size_t)row * D + col0;
;                     sv[mm] = st ? st[row] : (f32x2){0.f, 1.f};
; #pragma unroll
;                     for (int bj = 0; bj < 2; ++bj)
; #pragma unroll
;                         for (int n = 0; n < 2; ++n) pre[mm][bj][n] = *(const f32x4*)(base + off + bj * HALF + n * 16); }
;                 asm volatile("" ::: "memory");
; #pragma unroll
;                 for (int bj = 0; bj < 2; ++bj)
; #pragma unroll
;                     for (int n = 0; n < 2; ++n) { f32x4 gv = (f32x4){ALPHA, ALPHA, ALPHA, ALPHA}, bv = (f32x4){0.f, 0.f, 0.f, 0.f};
;                         if (st) { gv = *(const f32x4*)(g + col0 + bj * HALF + n * 16) * ALPHA; bv = *(const f32x4*)(b + col0 + bj * HALF + n * 16) * ALPHA; }
; #pragma unroll
;                         for (int mm = 0; mm < 2; ++mm) { const int m = 2 * mh + mm; const size_t off = (size_t)(row0 + ai * HALF + m * 16) * D + col0;
;                             *(f32x4*)(out + off + bj * HALF + n * 16) = ((pre[mm][bj][n] - sv[mm].x) * sv[mm].y) * gv + bv + acc[ai][bj][m][n] * scale; } }
.LBB0_364:
	v_sub_f32_e32 v45, v69, v102
	v_sub_f32_e32 v44, v68, v102
	v_sub_f32_e32 v47, v71, v102
	v_sub_f32_e32 v46, v70, v102
	v_mov_b32_e32 v52, v100
	v_mov_b32_e32 v53, v100
	v_pk_mul_f32 v[46:47], v[52:53], v[46:47]
	v_pk_mul_f32 v[44:45], v[100:101], v[44:45]
	v_pk_fma_f32 v[46:47], v[46:47], v[40:41], v[42:43]
	v_pk_fma_f32 v[44:45], v[44:45], v[48:49], v[50:51]
	v_pk_add_f32 v[38:39], v[38:39], v[46:47]
	v_pk_add_f32 v[36:37], v[36:37], v[44:45]
	global_store_dwordx4 v[60:61], v[36:39], off offset:576
	v_mov_b32_e32 v44, v96
	v_mov_b32_e32 v45, v96
	s_waitcnt vmcnt(7)
	v_sub_f32_e32 v37, v65, v98
	v_sub_f32_e32 v36, v64, v98
	v_sub_f32_e32 v39, v67, v98
	v_sub_f32_e32 v38, v66, v98
	v_pk_mul_f32 v[38:39], v[44:45], v[38:39]
	v_pk_mul_f32 v[36:37], v[96:97], v[36:37]
	v_pk_fma_f32 v[38:39], v[38:39], v[40:41], v[42:43]
	v_pk_fma_f32 v[36:37], v[36:37], v[48:49], v[50:51]
	v_pk_add_f32 v[34:35], v[34:35], v[38:39]
	v_pk_add_f32 v[32:33], v[32:33], v[36:37]
	global_store_dwordx4 v[56:57], v[32:35], off offset:576
	v_mov_b32_e32 v64, 1.0
	v_mov_b32_e32 v66, 0
	v_add_u32_e32 v32, 0xa0, v172
	v_ashrrev_i32_e32 v33, 31, v32
	s_and_b64 vcc, exec, s[44:45]
	v_mov_b32_e32 v70, 0
	v_mov_b32_e32 v68, 1.0
	v_mov_b32_e32 v71, 1.0
	s_cbranch_vccnz .LBB0_366
	v_lshl_add_u64 v[34:35], v[32:33], 3, s[4:5]
	global_load_dwordx2 v[70:71], v[34:35], off
.LBB0_366:
	v_lshlrev_b64 v[76:77], 12, v[32:33]
	v_lshl_add_u64 v[32:33], v[174:175], 0, v[76:77]
	global_load_dwordx4 v[60:63], v[32:33], off
	global_load_dwordx4 v[52:55], v[32:33], off offset:64
	global_load_dwordx4 v[44:47], v[32:33], off offset:512
	global_load_dwordx4 v[36:39], v[32:33], off offset:576
	v_add_u32_e32 v32, 0xb0, v172
	s_and_b64 vcc, exec, s[44:45]
	v_ashrrev_i32_e32 v33, 31, v32
	v_mov_b32_e32 v67, 1.0
	s_cbranch_vccnz .LBB0_368
	v_lshl_add_u64 v[34:35], v[32:33], 3, s[4:5]
	global_load_dwordx2 v[66:67], v[34:35], off
.LBB0_368:
	v_lshlrev_b64 v[78:79], 12, v[32:33]
	v_lshl_add_u64 v[32:33], v[174:175], 0, v[78:79]
	global_load_dwordx4 v[56:59], v[32:33], off
	global_load_dwordx4 v[48:51], v[32:33], off offset:64
	global_load_dwordx4 v[40:43], v[32:33], off offset:512
	s_nop 0
	global_load_dwordx4 v[32:35], v[32:33], off offset:576
	v_mov_b32_e32 v74, 0
	v_mov_b32_e32 v72, 0x3fd744fd
	s_and_b64 vcc, exec, s[44:45]
	v_mov_b32_e32 v82, 0x3fd744fd
	v_mov_b32_e32 v83, 0x3fd744fd
	v_mov_b32_e32 v80, 0x3fd744fd
	v_mov_b32_e32 v81, 0x3fd744fd
	v_mov_b32_e32 v86, 0
	v_mov_b32_e32 v87, 0
	v_mov_b32_e32 v84, 0
	v_mov_b32_e32 v85, 0
	s_cbranch_vccnz .LBB0_370
	v_mov_b32_dpp v80, v236 row_newbcast:2 row_mask:0xf bank_mask:0xf
	v_mov_b32_dpp v81, v236 row_newbcast:3 row_mask:0xf bank_mask:0xf
	v_mov_b32_dpp v82, v236 row_newbcast:0 row_mask:0xf bank_mask:0xf
	v_mov_b32_dpp v83, v236 row_newbcast:1 row_mask:0xf bank_mask:0xf
	v_mov_b32_dpp v84, v237 row_newbcast:2 row_mask:0xf bank_mask:0xf
	v_mov_b32_dpp v85, v237 row_newbcast:3 row_mask:0xf bank_mask:0xf
	v_mov_b32_dpp v86, v237 row_newbcast:0 row_mask:0xf bank_mask:0xf
	v_mov_b32_dpp v87, v237 row_newbcast:1 row_mask:0xf bank_mask:0xf
.LBB0_370:
	s_waitcnt vmcnt(7)
	v_mov_b32_e32 v68, v71
	v_sub_f32_e32 v63, v63, v70
	v_sub_f32_e32 v62, v62, v70
	v_pk_mul_f32 v[62:63], v[68:69], v[62:63] op_sel_hi:[0,1]
	v_pk_fma_f32 v[62:63], v[62:63], v[80:81], v[84:85]
	v_sub_f32_e32 v61, v61, v70
	v_sub_f32_e32 v60, v60, v70
	v_pk_add_f32 v[62:63], v[30:31], v[62:63]
	s_waitcnt vmcnt(3)
	v_mov_b32_e32 v64, v67
	v_sub_f32_e32 v31, v57, v66
	v_sub_f32_e32 v30, v56, v66
	v_sub_f32_e32 v57, v59, v66
	v_sub_f32_e32 v56, v58, v66
	v_pk_mul_f32 v[60:61], v[68:69], v[60:61] op_sel_hi:[0,1]
	v_pk_mul_f32 v[56:57], v[64:65], v[56:57] op_sel_hi:[0,1]
	v_pk_mul_f32 v[30:31], v[64:65], v[30:31] op_sel_hi:[0,1]
	v_pk_fma_f32 v[60:61], v[60:61], v[82:83], v[86:87]
	v_pk_fma_f32 v[30:31], v[30:31], v[82:83], v[86:87]
	v_pk_fma_f32 v[56:57], v[56:57], v[80:81], v[84:85]
	v_pk_add_f32 v[60:61], v[28:29], v[60:61]
	v_lshl_add_u64 v[28:29], s[84:85], 0, v[76:77]
	v_pk_add_f32 v[58:59], v[26:27], v[56:57]
	v_pk_add_f32 v[56:57], v[24:25], v[30:31]
	v_lshl_add_u64 v[24:25], s[84:85], 0, v[78:79]
	v_lshl_add_u64 v[28:29], v[28:29], 0, v[170:171]
	v_lshl_add_u64 v[24:25], v[24:25], 0, v[170:171]
	global_store_dwordx4 v[28:29], v[60:63], off
	global_store_dwordx4 v[24:25], v[56:59], off
	s_and_b64 vcc, exec, s[44:45]
	v_mov_b32_e32 v73, 0x3fd744fd
	v_mov_b32_e32 v30, 0x3fd744fd
	v_mov_b32_e32 v31, 0x3fd744fd
	v_mov_b32_e32 v75, 0
	v_mov_b32_e32 v56, 0
	v_mov_b32_e32 v57, 0
	s_cbranch_vccnz .LBB0_372
	v_mov_b32_dpp v30, v236 row_newbcast:6 row_mask:0xf bank_mask:0xf
	v_mov_b32_dpp v31, v236 row_newbcast:7 row_mask:0xf bank_mask:0xf
	v_mov_b32_dpp v72, v236 row_newbcast:4 row_mask:0xf bank_mask:0xf
	v_mov_b32_dpp v73, v236 row_newbcast:5 row_mask:0xf bank_mask:0xf
	v_mov_b32_dpp v56, v237 row_newbcast:6 row_mask:0xf bank_mask:0xf
	v_mov_b32_dpp v57, v237 row_newbcast:7 row_mask:0xf bank_mask:0xf
	v_mov_b32_dpp v74, v237 row_newbcast:4 row_mask:0xf bank_mask:0xf
	v_mov_b32_dpp v75, v237 row_newbcast:5 row_mask:0xf bank_mask:0xf
;     __device__ __forceinline__ void operator()(const Acc& acc, const Unit& u, int wr, int wc, int fr, int fq) const {
;     ...
;                 for (int mm = 0; mm < 2; ++mm) { const int row = row0 + ai * HALF + (2 * mh + mm) * 16; const size_t off = (size_t)row * D + col0;
;                     sv[mm] = st ? st[row] : (f32x2){0.f, 1.f};
; #pragma unroll
;                     for (int bj = 0; bj < 2; ++bj)
; #pragma unroll
;                         for (int n = 0; n < 2; ++n) pre[mm][bj][n] = *(const f32x4*)(base + off + bj * HALF + n * 16); }
;                 asm volatile("" ::: "memory");
; #pragma unroll
;                 for (int bj = 0; bj < 2; ++bj)
; #pragma unroll
;                     for (int n = 0; n < 2; ++n) { f32x4 gv = (f32x4){ALPHA, ALPHA, ALPHA, ALPHA}, bv = (f32x4){0.f, 0.f, 0.f, 0.f};
;                         if (st) { gv = *(const f32x4*)(g + col0 + bj * HALF + n * 16) * ALPHA; bv = *(const f32x4*)(b + col0 + bj * HALF + n * 16) * ALPHA; }
; #pragma unroll
;                         for (int mm = 0; mm < 2; ++mm) { const int m = 2 * mh + mm; const size_t off = (size_t)(row0 + ai * HALF + m * 16) * D + col0;
;                             *(f32x4*)(out + off + bj * HALF + n * 16) = ((pre[mm][bj][n] - sv[mm].x) * sv[mm].y) * gv + bv + acc[ai][bj][m][n] * scale; } }
.LBB0_372:
	v_mov_b32_e32 v69, v68
	v_sub_f32_e32 v53, v53, v70
	v_sub_f32_e32 v52, v52, v70
	v_sub_f32_e32 v55, v55, v70
	v_sub_f32_e32 v54, v54, v70
	v_mov_b32_e32 v26, v68
	v_mov_b32_e32 v27, v68
	v_pk_mul_f32 v[54:55], v[26:27], v[54:55]
	v_pk_mul_f32 v[52:53], v[68:69], v[52:53]
	v_pk_fma_f32 v[54:55], v[54:55], v[30:31], v[56:57]
	v_pk_fma_f32 v[52:53], v[52:53], v[72:73], v[74:75]
	v_pk_add_f32 v[22:23], v[22:23], v[54:55]
	v_pk_add_f32 v[20:21], v[20:21], v[52:53]
	v_mov_b32_e32 v65, v64
	global_store_dwordx4 v[28:29], v[20:23], off offset:64
	s_and_b64 vcc, exec, s[44:45]
	s_waitcnt vmcnt(5)
	v_sub_f32_e32 v23, v49, v66
	v_sub_f32_e32 v22, v48, v66
	v_sub_f32_e32 v49, v51, v66
	v_sub_f32_e32 v48, v50, v66
	v_mov_b32_e32 v20, v64
	v_mov_b32_e32 v21, v64
	v_pk_mul_f32 v[48:49], v[20:21], v[48:49]
	v_pk_mul_f32 v[22:23], v[64:65], v[22:23]
	v_pk_fma_f32 v[30:31], v[48:49], v[30:31], v[56:57]
	v_pk_fma_f32 v[22:23], v[22:23], v[72:73], v[74:75]
	v_pk_add_f32 v[18:19], v[18:19], v[30:31]
	v_pk_add_f32 v[16:17], v[16:17], v[22:23]
	global_store_dwordx4 v[24:25], v[16:19], off offset:64
	v_mov_b32_e32 v30, 0x3fd744fd
	v_mov_b32_e32 v31, 0x3fd744fd
	v_mov_b32_e32 v18, 0
	v_mov_b32_e32 v16, 0x3fd744fd
	v_mov_b32_e32 v22, 0x3fd744fd
	v_mov_b32_e32 v23, 0x3fd744fd
	v_mov_b32_e32 v50, 0
	v_mov_b32_e32 v51, 0
	v_mov_b32_e32 v48, 0
	v_mov_b32_e32 v49, 0
	s_cbranch_vccnz .LBB0_374
	v_mov_b32_dpp v22, v236 row_newbcast:10 row_mask:0xf bank_mask:0xf
	v_mov_b32_dpp v23, v236 row_newbcast:11 row_mask:0xf bank_mask:0xf
	v_mov_b32_dpp v30, v236 row_newbcast:8 row_mask:0xf bank_mask:0xf
	v_mov_b32_dpp v31, v236 row_newbcast:9 row_mask:0xf bank_mask:0xf
	v_mov_b32_dpp v48, v237 row_newbcast:10 row_mask:0xf bank_mask:0xf
	v_mov_b32_dpp v49, v237 row_newbcast:11 row_mask:0xf bank_mask:0xf
	v_mov_b32_dpp v50, v237 row_newbcast:8 row_mask:0xf bank_mask:0xf
	v_mov_b32_dpp v51, v237 row_newbcast:9 row_mask:0xf bank_mask:0xf
.LBB0_374:
	v_sub_f32_e32 v45, v45, v70
	v_sub_f32_e32 v44, v44, v70
	v_sub_f32_e32 v47, v47, v70
	v_sub_f32_e32 v46, v46, v70
	v_pk_mul_f32 v[26:27], v[26:27], v[46:47]
	v_pk_mul_f32 v[44:45], v[68:69], v[44:45]
	v_pk_fma_f32 v[26:27], v[26:27], v[22:23], v[48:49]
	v_pk_fma_f32 v[44:45], v[44:45], v[30:31], v[50:51]
	v_pk_add_f32 v[14:15], v[14:15], v[26:27]
	v_pk_add_f32 v[12:13], v[12:13], v[44:45]
	global_store_dwordx4 v[28:29], v[12:15], off offset:512
	s_and_b64 vcc, exec, s[44:45]
	v_mov_b32_e32 v17, 0x3fd744fd
	s_waitcnt vmcnt(6)
	v_sub_f32_e32 v13, v41, v66
	v_sub_f32_e32 v12, v40, v66
	v_sub_f32_e32 v15, v43, v66
	v_sub_f32_e32 v14, v42, v66
	v_pk_mul_f32 v[14:15], v[20:21], v[14:15]
	v_pk_mul_f32 v[12:13], v[64:65], v[12:13]
	v_pk_fma_f32 v[14:15], v[14:15], v[22:23], v[48:49]
	v_pk_fma_f32 v[12:13], v[12:13], v[30:31], v[50:51]
	v_pk_add_f32 v[10:11], v[10:11], v[14:15]
	v_pk_add_f32 v[8:9], v[8:9], v[12:13]
	global_store_dwordx4 v[24:25], v[8:11], off offset:512
	v_mov_b32_e32 v19, 0
	s_nop 0
	v_mov_b32_e32 v8, 0x3fd744fd
	v_mov_b32_e32 v9, 0x3fd744fd
	v_mov_b32_e32 v10, 0
	v_mov_b32_e32 v11, 0
	s_cbranch_vccnz .LBB0_376
	v_mov_b32_dpp v8, v236 row_newbcast:14 row_mask:0xf bank_mask:0xf
	v_mov_b32_dpp v9, v236 row_newbcast:15 row_mask:0xf bank_mask:0xf
	v_mov_b32_dpp v16, v236 row_newbcast:12 row_mask:0xf bank_mask:0xf
	v_mov_b32_dpp v17, v236 row_newbcast:13 row_mask:0xf bank_mask:0xf
	v_mov_b32_dpp v10, v237 row_newbcast:14 row_mask:0xf bank_mask:0xf
	v_mov_b32_dpp v11, v237 row_newbcast:15 row_mask:0xf bank_mask:0xf
	v_mov_b32_dpp v18, v237 row_newbcast:12 row_mask:0xf bank_mask:0xf
	v_mov_b32_dpp v19, v237 row_newbcast:13 row_mask:0xf bank_mask:0xf

;     __device__ __forceinline__ void operator()(const Acc& acc, const Unit& u, int wr, int wc, int fr, int fq) const {
;     ...
;                 for (int mm = 0; mm < 2; ++mm) { const int row = row0 + ai * HALF + (2 * mh + mm) * 16; const size_t off = (size_t)row * D + col0;
;                     sv[mm] = st ? st[row] : (f32x2){0.f, 1.f};
; #pragma unroll
;                     for (int bj = 0; bj < 2; ++bj)
; #pragma unroll
;                         for (int n = 0; n < 2; ++n) pre[mm][bj][n] = *(const f32x4*)(base + off + bj * HALF + n * 16); }
;                 asm volatile("" ::: "memory");
; #pragma unroll
;                 for (int bj = 0; bj < 2; ++bj)
; #pragma unroll
;                     for (int n = 0; n < 2; ++n) { f32x4 gv = (f32x4){ALPHA, ALPHA, ALPHA, ALPHA}, bv = (f32x4){0.f, 0.f, 0.f, 0.f};
;                         if (st) { gv = *(const f32x4*)(g + col0 + bj * HALF + n * 16) * ALPHA; bv = *(const f32x4*)(b + col0 + bj * HALF + n * 16) * ALPHA; }
; #pragma unroll
;                         for (int mm = 0; mm < 2; ++mm) { const int m = 2 * mh + mm; const size_t off = (size_t)(row0 + ai * HALF + m * 16) * D + col0;
;                             *(f32x4*)(out + off + bj * HALF + n * 16) = ((pre[mm][bj][n] - sv[mm].x) * sv[mm].y) * gv + bv + acc[ai][bj][m][n] * scale; } }
.LBB0_452:
	v_mov_b32_e32 v129, v211
	v_mov_b32_e32 v128, v210
	s_lshl_b32 s12, s78, 8
	s_add_i32 s12, s12, s70
	v_add_u32_e32 v168, s12, v129
	v_cndmask_b32_e64 v129, 0, 1, s[58:59]
	v_ashrrev_i32_e32 v169, 31, v168
	v_mov_b32_e32 v172, 1.0
	v_mov_b32_e32 v174, 0
	v_cmp_ne_u32_e64 s[44:45], 1, v129
	s_andn2_b64 vcc, exec, s[58:59]
	v_mov_b32_e32 v178, 0
	v_mov_b32_e32 v176, 1.0
	s_mov_b64 s[94:95], 0x8000
	v_mov_b32_e32 v179, 1.0
	s_cbranch_vccnz .LBB0_454
	v_lshl_add_u64 v[130:131], v[168:169], 3, s[4:5]
	global_load_dwordx2 v[178:179], v[130:131], off
.LBB0_454:
	s_lshl_b32 s12, s76, 8
	s_or_b32 s12, s12, s71
	v_lshl_add_u32 v166, v128, 2, s12
	v_ashrrev_i32_e32 v167, 31, v166
	v_lshl_add_u64 v[170:171], v[166:167], 2, s[40:41]
	v_lshlrev_b64 v[184:185], 12, v[168:169]
	v_lshl_add_u64 v[128:129], v[170:171], 0, v[184:185]
	global_load_dwordx4 v[156:159], v[128:129], off
	global_load_dwordx4 v[148:151], v[128:129], off offset:64
	global_load_dwordx4 v[140:143], v[128:129], off offset:512
	global_load_dwordx4 v[132:135], v[128:129], off offset:576
	v_add_u32_e32 v128, 16, v168
	s_and_b64 vcc, exec, s[44:45]
	v_ashrrev_i32_e32 v129, 31, v128
	v_mov_b32_e32 v175, 1.0
	s_cbranch_vccnz .LBB0_456
	v_lshl_add_u64 v[130:131], v[128:129], 3, s[4:5]
	global_load_dwordx2 v[174:175], v[130:131], off
.LBB0_456:
	v_lshlrev_b64 v[186:187], 12, v[128:129]
	v_lshl_add_u64 v[128:129], v[170:171], 0, v[186:187]
	global_load_dwordx4 v[152:155], v[128:129], off
	global_load_dwordx4 v[144:147], v[128:129], off offset:64
	global_load_dwordx4 v[136:139], v[128:129], off offset:512
	s_nop 0
	global_load_dwordx4 v[128:131], v[128:129], off offset:576
	v_mov_b32_e32 v182, 0
	v_mov_b32_e32 v180, 0x3fd744fd
	s_and_b64 vcc, exec, s[44:45]
	v_lshlrev_b64 v[166:167], 2, v[166:167]
	v_mov_b32_e32 v190, 0x3fd744fd
	v_mov_b32_e32 v191, 0x3fd744fd
	v_mov_b32_e32 v188, 0x3fd744fd
	v_mov_b32_e32 v189, 0x3fd744fd
	v_mov_b32_e32 v208, 0
	v_mov_b32_e32 v209, 0
	v_mov_b32_e32 v206, 0
	v_mov_b32_e32 v207, 0
	s_cbranch_vccnz .LBB0_458
	v_and_b32_e32 v240, 15, v230
	v_and_b32_e32 v238, 3, v240
	v_lshlrev_b32_e32 v238, 2, v238
	v_and_b32_e32 v241, 4, v240
	v_lshlrev_b32_e32 v241, 4, v241
	v_or_b32_e32 v238, v238, v241
	v_and_b32_e32 v241, 8, v240
	v_lshlrev_b32_e32 v241, 6, v241
	v_or_b32_e32 v238, v238, v241
	v_mov_b32_e32 v239, 0
	v_lshl_add_u64 v[242:243], s[48:49], 0, v[166:167]
	v_lshl_add_u64 v[244:245], s[52:53], 0, v[166:167]
	v_lshl_add_u64 v[242:243], v[242:243], 0, v[238:239]
	v_lshl_add_u64 v[244:245], v[244:245], 0, v[238:239]
	global_load_dword v236, v[242:243], off
	global_load_dword v237, v[244:245], off
	s_waitcnt vmcnt(0)
	v_mul_f32_e32 v236, s64, v236
	v_mul_f32_e32 v237, s64, v237
	s_nop 1
	v_mov_b32_dpp v188, v236 row_newbcast:2 row_mask:0xf bank_mask:0xf
	v_mov_b32_dpp v189, v236 row_newbcast:3 row_mask:0xf bank_mask:0xf
	v_mov_b32_dpp v190, v236 row_newbcast:0 row_mask:0xf bank_mask:0xf
	v_mov_b32_dpp v191, v236 row_newbcast:1 row_mask:0xf bank_mask:0xf
	v_mov_b32_dpp v206, v237 row_newbcast:2 row_mask:0xf bank_mask:0xf
	v_mov_b32_dpp v207, v237 row_newbcast:3 row_mask:0xf bank_mask:0xf
	v_mov_b32_dpp v208, v237 row_newbcast:0 row_mask:0xf bank_mask:0xf
	v_mov_b32_dpp v209, v237 row_newbcast:1 row_mask:0xf bank_mask:0xf
.LBB0_458:
	s_waitcnt vmcnt(0)
	v_mov_b32_e32 v176, v179
	v_mov_b32_e32 v172, v175
	v_sub_f32_e32 v159, v159, v178
	v_sub_f32_e32 v158, v158, v178
	v_pk_mul_f32 v[158:159], v[176:177], v[158:159] op_sel_hi:[0,1]
	v_pk_fma_f32 v[158:159], v[158:159], v[188:189], v[206:207]
	v_sub_f32_e32 v157, v157, v178
	v_sub_f32_e32 v156, v156, v178
	v_pk_fma_f32 v[158:159], v[126:127], 0.5, v[158:159] op_sel_hi:[1,0,1]
	v_sub_f32_e32 v127, v153, v174
	v_sub_f32_e32 v126, v152, v174
	v_sub_f32_e32 v153, v155, v174
	v_sub_f32_e32 v152, v154, v174
	v_pk_mul_f32 v[156:157], v[176:177], v[156:157] op_sel_hi:[0,1]
	v_pk_mul_f32 v[152:153], v[172:173], v[152:153] op_sel_hi:[0,1]
	v_pk_mul_f32 v[126:127], v[172:173], v[126:127] op_sel_hi:[0,1]
	v_pk_fma_f32 v[156:157], v[156:157], v[190:191], v[208:209]
	v_pk_fma_f32 v[126:127], v[126:127], v[190:191], v[208:209]
	v_pk_fma_f32 v[152:153], v[152:153], v[188:189], v[206:207]
	v_pk_fma_f32 v[156:157], v[124:125], 0.5, v[156:157] op_sel_hi:[1,0,1]
	v_lshl_add_u64 v[124:125], s[84:85], 0, v[184:185]
	v_pk_fma_f32 v[154:155], v[122:123], 0.5, v[152:153] op_sel_hi:[1,0,1]
	v_pk_fma_f32 v[152:153], v[120:121], 0.5, v[126:127] op_sel_hi:[1,0,1]
	v_lshl_add_u64 v[120:121], s[84:85], 0, v[186:187]
	v_lshl_add_u64 v[124:125], v[124:125], 0, v[166:167]
	v_lshl_add_u64 v[120:121], v[120:121], 0, v[166:167]
	global_store_dwordx4 v[124:125], v[156:159], off
	global_store_dwordx4 v[120:121], v[152:155], off
	s_and_b64 vcc, exec, s[44:45]
	v_mov_b32_e32 v181, 0x3fd744fd
	v_mov_b32_e32 v126, 0x3fd744fd
	v_mov_b32_e32 v127, 0x3fd744fd
	v_mov_b32_e32 v183, 0
	v_mov_b32_e32 v152, 0
	v_mov_b32_e32 v153, 0
	s_cbranch_vccnz .LBB0_460
	v_mov_b32_dpp v126, v236 row_newbcast:6 row_mask:0xf bank_mask:0xf
	v_mov_b32_dpp v127, v236 row_newbcast:7 row_mask:0xf bank_mask:0xf
	v_mov_b32_dpp v180, v236 row_newbcast:4 row_mask:0xf bank_mask:0xf
	v_mov_b32_dpp v181, v236 row_newbcast:5 row_mask:0xf bank_mask:0xf
	v_mov_b32_dpp v152, v237 row_newbcast:6 row_mask:0xf bank_mask:0xf
	v_mov_b32_dpp v153, v237 row_newbcast:7 row_mask:0xf bank_mask:0xf
	v_mov_b32_dpp v182, v237 row_newbcast:4 row_mask:0xf bank_mask:0xf
	v_mov_b32_dpp v183, v237 row_newbcast:5 row_mask:0xf bank_mask:0xf
;     __device__ __forceinline__ void operator()(const Acc& acc, const Unit& u, int wr, int wc, int fr, int fq) const {
;     ...
;                 for (int mm = 0; mm < 2; ++mm) { const int row = row0 + ai * HALF + (2 * mh + mm) * 16; const size_t off = (size_t)row * D + col0;
;                     sv[mm] = st ? st[row] : (f32x2){0.f, 1.f};
; #pragma unroll
;                     for (int bj = 0; bj < 2; ++bj)
; #pragma unroll
;                         for (int n = 0; n < 2; ++n) pre[mm][bj][n] = *(const f32x4*)(base + off + bj * HALF + n * 16); }
;                 asm volatile("" ::: "memory");
; #pragma unroll
;                 for (int bj = 0; bj < 2; ++bj)
; #pragma unroll
;                     for (int n = 0; n < 2; ++n) { f32x4 gv = (f32x4){ALPHA, ALPHA, ALPHA, ALPHA}, bv = (f32x4){0.f, 0.f, 0.f, 0.f};
;                         if (st) { gv = *(const f32x4*)(g + col0 + bj * HALF + n * 16) * ALPHA; bv = *(const f32x4*)(b + col0 + bj * HALF + n * 16) * ALPHA; }
; #pragma unroll
;                         for (int mm = 0; mm < 2; ++mm) { const int m = 2 * mh + mm; const size_t off = (size_t)(row0 + ai * HALF + m * 16) * D + col0;
;                             *(f32x4*)(out + off + bj * HALF + n * 16) = ((pre[mm][bj][n] - sv[mm].x) * sv[mm].y) * gv + bv + acc[ai][bj][m][n] * scale; } }
.LBB0_460:
	v_mov_b32_e32 v177, v176
	v_sub_f32_e32 v149, v149, v178
	v_sub_f32_e32 v148, v148, v178
	v_sub_f32_e32 v151, v151, v178
	v_sub_f32_e32 v150, v150, v178
	v_mov_b32_e32 v122, v176
	v_mov_b32_e32 v123, v176
	v_pk_mul_f32 v[150:151], v[122:123], v[150:151]
	v_pk_mul_f32 v[148:149], v[176:177], v[148:149]
	v_pk_fma_f32 v[150:151], v[150:151], v[126:127], v[152:153]
	v_pk_fma_f32 v[148:149], v[148:149], v[180:181], v[182:183]
	v_pk_fma_f32 v[118:119], v[118:119], 0.5, v[150:151] op_sel_hi:[1,0,1]
	v_pk_fma_f32 v[116:117], v[116:117], 0.5, v[148:149] op_sel_hi:[1,0,1]
	v_mov_b32_e32 v173, v172
	global_store_dwordx4 v[124:125], v[116:119], off offset:64
	s_and_b64 vcc, exec, s[44:45]
	s_nop 0
	v_sub_f32_e32 v119, v145, v174
	v_sub_f32_e32 v118, v144, v174
	v_sub_f32_e32 v145, v147, v174
	v_sub_f32_e32 v144, v146, v174
	v_mov_b32_e32 v116, v172
	v_mov_b32_e32 v117, v172
	v_pk_mul_f32 v[144:145], v[116:117], v[144:145]
	v_pk_mul_f32 v[118:119], v[172:173], v[118:119]
	v_pk_fma_f32 v[126:127], v[144:145], v[126:127], v[152:153]
	v_pk_fma_f32 v[118:119], v[118:119], v[180:181], v[182:183]
	v_pk_fma_f32 v[114:115], v[114:115], 0.5, v[126:127] op_sel_hi:[1,0,1]
	v_pk_fma_f32 v[112:113], v[112:113], 0.5, v[118:119] op_sel_hi:[1,0,1]
	global_store_dwordx4 v[120:121], v[112:115], off offset:64
	v_mov_b32_e32 v126, 0x3fd744fd
	v_mov_b32_e32 v127, 0x3fd744fd
	v_mov_b32_e32 v114, 0
	v_mov_b32_e32 v112, 0x3fd744fd
	v_mov_b32_e32 v118, 0x3fd744fd
	v_mov_b32_e32 v119, 0x3fd744fd
	v_mov_b32_e32 v146, 0
	v_mov_b32_e32 v147, 0
	v_mov_b32_e32 v144, 0
	v_mov_b32_e32 v145, 0
	s_cbranch_vccnz .LBB0_462
	v_mov_b32_dpp v118, v236 row_newbcast:10 row_mask:0xf bank_mask:0xf
	v_mov_b32_dpp v119, v236 row_newbcast:11 row_mask:0xf bank_mask:0xf
	v_mov_b32_dpp v126, v236 row_newbcast:8 row_mask:0xf bank_mask:0xf
	v_mov_b32_dpp v127, v236 row_newbcast:9 row_mask:0xf bank_mask:0xf
	v_mov_b32_dpp v144, v237 row_newbcast:10 row_mask:0xf bank_mask:0xf
	v_mov_b32_dpp v145, v237 row_newbcast:11 row_mask:0xf bank_mask:0xf
	v_mov_b32_dpp v146, v237 row_newbcast:8 row_mask:0xf bank_mask:0xf
	v_mov_b32_dpp v147, v237 row_newbcast:9 row_mask:0xf bank_mask:0xf
.LBB0_462:
	v_sub_f32_e32 v141, v141, v178
	v_sub_f32_e32 v140, v140, v178
	v_sub_f32_e32 v143, v143, v178
	v_sub_f32_e32 v142, v142, v178
	v_pk_mul_f32 v[122:123], v[122:123], v[142:143]
	v_pk_mul_f32 v[140:141], v[176:177], v[140:141]
	v_pk_fma_f32 v[122:123], v[122:123], v[118:119], v[144:145]
	v_pk_fma_f32 v[140:141], v[140:141], v[126:127], v[146:147]
	v_pk_fma_f32 v[110:111], v[110:111], 0.5, v[122:123] op_sel_hi:[1,0,1]
	v_pk_fma_f32 v[108:109], v[108:109], 0.5, v[140:141] op_sel_hi:[1,0,1]
	global_store_dwordx4 v[124:125], v[108:111], off offset:512
	s_and_b64 vcc, exec, s[44:45]
	v_mov_b32_e32 v113, 0x3fd744fd
	v_sub_f32_e32 v109, v137, v174
	v_sub_f32_e32 v108, v136, v174
	v_sub_f32_e32 v111, v139, v174
	v_sub_f32_e32 v110, v138, v174
	v_pk_mul_f32 v[110:111], v[116:117], v[110:111]
	v_pk_mul_f32 v[108:109], v[172:173], v[108:109]
	v_pk_fma_f32 v[110:111], v[110:111], v[118:119], v[144:145]
	v_pk_fma_f32 v[108:109], v[108:109], v[126:127], v[146:147]
	v_pk_fma_f32 v[106:107], v[106:107], 0.5, v[110:111] op_sel_hi:[1,0,1]
	v_pk_fma_f32 v[104:105], v[104:105], 0.5, v[108:109] op_sel_hi:[1,0,1]
	global_store_dwordx4 v[120:121], v[104:107], off offset:512
	v_mov_b32_e32 v115, 0
	s_nop 0
	v_mov_b32_e32 v104, 0x3fd744fd
	v_mov_b32_e32 v105, 0x3fd744fd
	v_mov_b32_e32 v106, 0
	v_mov_b32_e32 v107, 0
	s_cbranch_vccnz .LBB0_464
	v_mov_b32_dpp v104, v236 row_newbcast:14 row_mask:0xf bank_mask:0xf
	v_mov_b32_dpp v105, v236 row_newbcast:15 row_mask:0xf bank_mask:0xf
	v_mov_b32_dpp v112, v236 row_newbcast:12 row_mask:0xf bank_mask:0xf
	v_mov_b32_dpp v113, v236 row_newbcast:13 row_mask:0xf bank_mask:0xf
	v_mov_b32_dpp v106, v237 row_newbcast:14 row_mask:0xf bank_mask:0xf
	v_mov_b32_dpp v107, v237 row_newbcast:15 row_mask:0xf bank_mask:0xf
	v_mov_b32_dpp v114, v237 row_newbcast:12 row_mask:0xf bank_mask:0xf
	v_mov_b32_dpp v115, v237 row_newbcast:13 row_mask:0xf bank_mask:0xf
.LBB0_464:
	v_sub_f32_e32 v109, v133, v178
	v_sub_f32_e32 v108, v132, v178
	v_sub_f32_e32 v111, v135, v178
	v_sub_f32_e32 v110, v134, v178
	v_mov_b32_e32 v116, v176
	v_mov_b32_e32 v117, v176
	v_pk_mul_f32 v[110:111], v[116:117], v[110:111]
	v_pk_mul_f32 v[108:109], v[176:177], v[108:109]
	v_pk_fma_f32 v[110:111], v[110:111], v[104:105], v[106:107]
	v_pk_fma_f32 v[108:109], v[108:109], v[112:113], v[114:115]
	v_pk_fma_f32 v[102:103], v[102:103], 0.5, v[110:111] op_sel_hi:[1,0,1]
	v_pk_fma_f32 v[100:101], v[100:101], 0.5, v[108:109] op_sel_hi:[1,0,1]
	global_store_dwordx4 v[124:125], v[100:103], off offset:576
	v_mov_b32_e32 v108, v172
	v_mov_b32_e32 v109, v172
	v_sub_f32_e32 v101, v129, v174
	v_sub_f32_e32 v100, v128, v174
	v_sub_f32_e32 v103, v131, v174
	v_sub_f32_e32 v102, v130, v174
	v_pk_mul_f32 v[102:103], v[108:109], v[102:103]
	v_pk_mul_f32 v[100:101], v[172:173], v[100:101]
	v_pk_fma_f32 v[102:103], v[102:103], v[104:105], v[106:107]
	v_pk_fma_f32 v[100:101], v[100:101], v[112:113], v[114:115]
	v_pk_fma_f32 v[98:99], v[98:99], 0.5, v[102:103] op_sel_hi:[1,0,1]
	v_pk_fma_f32 v[96:97], v[96:97], 0.5, v[100:101] op_sel_hi:[1,0,1]
	global_store_dwordx4 v[120:121], v[96:99], off offset:576
	v_mov_b32_e32 v128, 1.0
	v_mov_b32_e32 v130, 0
	v_add_u32_e32 v96, 32, v168
	v_ashrrev_i32_e32 v97, 31, v96
	s_and_b64 vcc, exec, s[44:45]
	v_mov_b32_e32 v134, 0
	v_mov_b32_e32 v132, 1.0
	v_mov_b32_e32 v135, 1.0
	s_cbranch_vccnz .LBB0_466
	v_lshl_add_u64 v[98:99], v[96:97], 3, s[4:5]
	global_load_dwordx2 v[134:135], v[98:99], off
;     __device__ __forceinline__ void operator()(const Acc& acc, const Unit& u, int wr, int wc, int fr, int fq) const {
;     ...
;                 for (int mm = 0; mm < 2; ++mm) { const int row = row0 + ai * HALF + (2 * mh + mm) * 16; const size_t off = (size_t)row * D + col0;
;                     sv[mm] = st ? st[row] : (f32x2){0.f, 1.f};
; #pragma unroll
;                     for (int bj = 0; bj < 2; ++bj)
; #pragma unroll
;                         for (int n = 0; n < 2; ++n) pre[mm][bj][n] = *(const f32x4*)(base + off + bj * HALF + n * 16); }
;                 asm volatile("" ::: "memory");
; #pragma unroll
;                 for (int bj = 0; bj < 2; ++bj)
; #pragma unroll
;                     for (int n = 0; n < 2; ++n) { f32x4 gv = (f32x4){ALPHA, ALPHA, ALPHA, ALPHA}, bv = (f32x4){0.f, 0.f, 0.f, 0.f};
;                         if (st) { gv = *(const f32x4*)(g + col0 + bj * HALF + n * 16) * ALPHA; bv = *(const f32x4*)(b + col0 + bj * HALF + n * 16) * ALPHA; }
; #pragma unroll
;                         for (int mm = 0; mm < 2; ++mm) { const int m = 2 * mh + mm; const size_t off = (size_t)(row0 + ai * HALF + m * 16) * D + col0;
;                             *(f32x4*)(out + off + bj * HALF + n * 16) = ((pre[mm][bj][n] - sv[mm].x) * sv[mm].y) * gv + bv + acc[ai][bj][m][n] * scale; } }
.LBB0_466:
	v_lshlrev_b64 v[140:141], 12, v[96:97]
	v_lshl_add_u64 v[96:97], v[170:171], 0, v[140:141]
	global_load_dwordx4 v[124:127], v[96:97], off
	global_load_dwordx4 v[116:119], v[96:97], off offset:64
	global_load_dwordx4 v[108:111], v[96:97], off offset:512
	global_load_dwordx4 v[100:103], v[96:97], off offset:576
	v_add_u32_e32 v96, 48, v168
	s_and_b64 vcc, exec, s[44:45]
	v_ashrrev_i32_e32 v97, 31, v96
	v_mov_b32_e32 v131, 1.0
	s_cbranch_vccnz .LBB0_468
	v_lshl_add_u64 v[98:99], v[96:97], 3, s[4:5]
	global_load_dwordx2 v[130:131], v[98:99], off
.LBB0_468:
	v_lshlrev_b64 v[142:143], 12, v[96:97]
	v_lshl_add_u64 v[96:97], v[170:171], 0, v[142:143]
	global_load_dwordx4 v[120:123], v[96:97], off
	global_load_dwordx4 v[112:115], v[96:97], off offset:64
	global_load_dwordx4 v[104:107], v[96:97], off offset:512
	s_nop 0
	global_load_dwordx4 v[96:99], v[96:97], off offset:576
	v_mov_b32_e32 v138, 0
	v_mov_b32_e32 v136, 0x3fd744fd
	s_and_b64 vcc, exec, s[44:45]
	v_mov_b32_e32 v146, 0x3fd744fd
	v_mov_b32_e32 v147, 0x3fd744fd
	v_mov_b32_e32 v144, 0x3fd744fd
	v_mov_b32_e32 v145, 0x3fd744fd
	v_mov_b32_e32 v150, 0
	v_mov_b32_e32 v151, 0
	v_mov_b32_e32 v148, 0
	v_mov_b32_e32 v149, 0
	s_cbranch_vccnz .LBB0_470
	v_mov_b32_dpp v144, v236 row_newbcast:2 row_mask:0xf bank_mask:0xf
	v_mov_b32_dpp v145, v236 row_newbcast:3 row_mask:0xf bank_mask:0xf
	v_mov_b32_dpp v146, v236 row_newbcast:0 row_mask:0xf bank_mask:0xf
	v_mov_b32_dpp v147, v236 row_newbcast:1 row_mask:0xf bank_mask:0xf
	v_mov_b32_dpp v148, v237 row_newbcast:2 row_mask:0xf bank_mask:0xf
	v_mov_b32_dpp v149, v237 row_newbcast:3 row_mask:0xf bank_mask:0xf
	v_mov_b32_dpp v150, v237 row_newbcast:0 row_mask:0xf bank_mask:0xf
	v_mov_b32_dpp v151, v237 row_newbcast:1 row_mask:0xf bank_mask:0xf
.LBB0_470:
	s_waitcnt vmcnt(7)
	v_mov_b32_e32 v132, v135
	v_sub_f32_e32 v127, v127, v134
	v_sub_f32_e32 v126, v126, v134
	v_pk_mul_f32 v[126:127], v[132:133], v[126:127] op_sel_hi:[0,1]
	v_pk_fma_f32 v[126:127], v[126:127], v[144:145], v[148:149]
	v_sub_f32_e32 v125, v125, v134
	v_sub_f32_e32 v124, v124, v134
	v_pk_fma_f32 v[126:127], v[94:95], 0.5, v[126:127] op_sel_hi:[1,0,1]
	s_waitcnt vmcnt(3)
	v_mov_b32_e32 v128, v131
	v_sub_f32_e32 v95, v121, v130
	v_sub_f32_e32 v94, v120, v130
	v_sub_f32_e32 v121, v123, v130
	v_sub_f32_e32 v120, v122, v130
	v_pk_mul_f32 v[124:125], v[132:133], v[124:125] op_sel_hi:[0,1]
	v_pk_mul_f32 v[120:121], v[128:129], v[120:121] op_sel_hi:[0,1]
	v_pk_mul_f32 v[94:95], v[128:129], v[94:95] op_sel_hi:[0,1]
	v_pk_fma_f32 v[124:125], v[124:125], v[146:147], v[150:151]
	v_pk_fma_f32 v[94:95], v[94:95], v[146:147], v[150:151]
	v_pk_fma_f32 v[120:121], v[120:121], v[144:145], v[148:149]
	v_pk_fma_f32 v[124:125], v[92:93], 0.5, v[124:125] op_sel_hi:[1,0,1]
	v_lshl_add_u64 v[92:93], s[84:85], 0, v[140:141]
	v_pk_fma_f32 v[122:123], v[90:91], 0.5, v[120:121] op_sel_hi:[1,0,1]
	v_pk_fma_f32 v[120:121], v[88:89], 0.5, v[94:95] op_sel_hi:[1,0,1]
	v_lshl_add_u64 v[88:89], s[84:85], 0, v[142:143]
	v_lshl_add_u64 v[92:93], v[92:93], 0, v[166:167]
	v_lshl_add_u64 v[88:89], v[88:89], 0, v[166:167]
	global_store_dwordx4 v[92:93], v[124:127], off
	global_store_dwordx4 v[88:89], v[120:123], off
	s_and_b64 vcc, exec, s[44:45]
	v_mov_b32_e32 v137, 0x3fd744fd
	v_mov_b32_e32 v94, 0x3fd744fd
	v_mov_b32_e32 v95, 0x3fd744fd
	v_mov_b32_e32 v139, 0
	v_mov_b32_e32 v120, 0
	v_mov_b32_e32 v121, 0
	s_cbranch_vccnz .LBB0_472
	v_mov_b32_dpp v94, v236 row_newbcast:6 row_mask:0xf bank_mask:0xf
	v_mov_b32_dpp v95, v236 row_newbcast:7 row_mask:0xf bank_mask:0xf
	v_mov_b32_dpp v136, v236 row_newbcast:4 row_mask:0xf bank_mask:0xf
	v_mov_b32_dpp v137, v236 row_newbcast:5 row_mask:0xf bank_mask:0xf
	v_mov_b32_dpp v120, v237 row_newbcast:6 row_mask:0xf bank_mask:0xf
	v_mov_b32_dpp v121, v237 row_newbcast:7 row_mask:0xf bank_mask:0xf
	v_mov_b32_dpp v138, v237 row_newbcast:4 row_mask:0xf bank_mask:0xf
	v_mov_b32_dpp v139, v237 row_newbcast:5 row_mask:0xf bank_mask:0xf
.LBB0_472:
	v_mov_b32_e32 v133, v132
	v_sub_f32_e32 v117, v117, v134
	v_sub_f32_e32 v116, v116, v134
	v_sub_f32_e32 v119, v119, v134
	v_sub_f32_e32 v118, v118, v134
	v_mov_b32_e32 v90, v132
	v_mov_b32_e32 v91, v132
	v_pk_mul_f32 v[118:119], v[90:91], v[118:119]
	v_pk_mul_f32 v[116:117], v[132:133], v[116:117]
	v_pk_fma_f32 v[118:119], v[118:119], v[94:95], v[120:121]
	v_pk_fma_f32 v[116:117], v[116:117], v[136:137], v[138:139]
	v_pk_fma_f32 v[86:87], v[86:87], 0.5, v[118:119] op_sel_hi:[1,0,1]
	v_pk_fma_f32 v[84:85], v[84:85], 0.5, v[116:117] op_sel_hi:[1,0,1]
	v_mov_b32_e32 v129, v128
	global_store_dwordx4 v[92:93], v[84:87], off offset:64
	s_and_b64 vcc, exec, s[44:45]
	s_waitcnt vmcnt(5)
	v_sub_f32_e32 v87, v113, v130
	v_sub_f32_e32 v86, v112, v130
	v_sub_f32_e32 v113, v115, v130
	v_sub_f32_e32 v112, v114, v130
	v_mov_b32_e32 v84, v128
	v_mov_b32_e32 v85, v128
	v_pk_mul_f32 v[112:113], v[84:85], v[112:113]
	v_pk_mul_f32 v[86:87], v[128:129], v[86:87]
	v_pk_fma_f32 v[94:95], v[112:113], v[94:95], v[120:121]
	v_pk_fma_f32 v[86:87], v[86:87], v[136:137], v[138:139]
	v_pk_fma_f32 v[82:83], v[82:83], 0.5, v[94:95] op_sel_hi:[1,0,1]
	v_pk_fma_f32 v[80:81], v[80:81], 0.5, v[86:87] op_sel_hi:[1,0,1]
	global_store_dwordx4 v[88:89], v[80:83], off offset:64
	v_mov_b32_e32 v94, 0x3fd744fd
	v_mov_b32_e32 v95, 0x3fd744fd
	v_mov_b32_e32 v82, 0
	v_mov_b32_e32 v80, 0x3fd744fd
	v_mov_b32_e32 v86, 0x3fd744fd
	v_mov_b32_e32 v87, 0x3fd744fd
	v_mov_b32_e32 v114, 0
	v_mov_b32_e32 v115, 0
	v_mov_b32_e32 v112, 0
	v_mov_b32_e32 v113, 0
	s_cbranch_vccnz .LBB0_474
	v_mov_b32_dpp v86, v236 row_newbcast:10 row_mask:0xf bank_mask:0xf
	v_mov_b32_dpp v87, v236 row_newbcast:11 row_mask:0xf bank_mask:0xf
	v_mov_b32_dpp v94, v236 row_newbcast:8 row_mask:0xf bank_mask:0xf
	v_mov_b32_dpp v95, v236 row_newbcast:9 row_mask:0xf bank_mask:0xf
	v_mov_b32_dpp v112, v237 row_newbcast:10 row_mask:0xf bank_mask:0xf
	v_mov_b32_dpp v113, v237 row_newbcast:11 row_mask:0xf bank_mask:0xf
	v_mov_b32_dpp v114, v237 row_newbcast:8 row_mask:0xf bank_mask:0xf
	v_mov_b32_dpp v115, v237 row_newbcast:9 row_mask:0xf bank_mask:0xf
;     __device__ __forceinline__ void operator()(const Acc& acc, const Unit& u, int wr, int wc, int fr, int fq) const {
;     ...
;                 for (int mm = 0; mm < 2; ++mm) { const int row = row0 + ai * HALF + (2 * mh + mm) * 16; const size_t off = (size_t)row * D + col0;
;                     sv[mm] = st ? st[row] : (f32x2){0.f, 1.f};
; #pragma unroll
;                     for (int bj = 0; bj < 2; ++bj)
; #pragma unroll
;                         for (int n = 0; n < 2; ++n) pre[mm][bj][n] = *(const f32x4*)(base + off + bj * HALF + n * 16); }
;                 asm volatile("" ::: "memory");
; #pragma unroll
;                 for (int bj = 0; bj < 2; ++bj)
; #pragma unroll
;                     for (int n = 0; n < 2; ++n) { f32x4 gv = (f32x4){ALPHA, ALPHA, ALPHA, ALPHA}, bv = (f32x4){0.f, 0.f, 0.f, 0.f};
;                         if (st) { gv = *(const f32x4*)(g + col0 + bj * HALF + n * 16) * ALPHA; bv = *(const f32x4*)(b + col0 + bj * HALF + n * 16) * ALPHA; }
; #pragma unroll
;                         for (int mm = 0; mm < 2; ++mm) { const int m = 2 * mh + mm; const size_t off = (size_t)(row0 + ai * HALF + m * 16) * D + col0;
;                             *(f32x4*)(out + off + bj * HALF + n * 16) = ((pre[mm][bj][n] - sv[mm].x) * sv[mm].y) * gv + bv + acc[ai][bj][m][n] * scale; } }
.LBB0_474:
	v_sub_f32_e32 v109, v109, v134
	v_sub_f32_e32 v108, v108, v134
	v_sub_f32_e32 v111, v111, v134
	v_sub_f32_e32 v110, v110, v134
	v_pk_mul_f32 v[90:91], v[90:91], v[110:111]
	v_pk_mul_f32 v[108:109], v[132:133], v[108:109]
	v_pk_fma_f32 v[90:91], v[90:91], v[86:87], v[112:113]
	v_pk_fma_f32 v[108:109], v[108:109], v[94:95], v[114:115]
	v_pk_fma_f32 v[78:79], v[78:79], 0.5, v[90:91] op_sel_hi:[1,0,1]
	v_pk_fma_f32 v[76:77], v[76:77], 0.5, v[108:109] op_sel_hi:[1,0,1]
	global_store_dwordx4 v[92:93], v[76:79], off offset:512
	s_and_b64 vcc, exec, s[44:45]
	v_mov_b32_e32 v81, 0x3fd744fd
	s_waitcnt vmcnt(6)
	v_sub_f32_e32 v77, v105, v130
	v_sub_f32_e32 v76, v104, v130
	v_sub_f32_e32 v79, v107, v130
	v_sub_f32_e32 v78, v106, v130
	v_pk_mul_f32 v[78:79], v[84:85], v[78:79]
	v_pk_mul_f32 v[76:77], v[128:129], v[76:77]
	v_pk_fma_f32 v[78:79], v[78:79], v[86:87], v[112:113]
	v_pk_fma_f32 v[76:77], v[76:77], v[94:95], v[114:115]
	v_pk_fma_f32 v[74:75], v[74:75], 0.5, v[78:79] op_sel_hi:[1,0,1]
	v_pk_fma_f32 v[72:73], v[72:73], 0.5, v[76:77] op_sel_hi:[1,0,1]
	global_store_dwordx4 v[88:89], v[72:75], off offset:512
	v_mov_b32_e32 v83, 0
	s_nop 0
	v_mov_b32_e32 v72, 0x3fd744fd
	v_mov_b32_e32 v73, 0x3fd744fd
	v_mov_b32_e32 v74, 0
	v_mov_b32_e32 v75, 0
	s_cbranch_vccnz .LBB0_476
	v_mov_b32_dpp v72, v236 row_newbcast:14 row_mask:0xf bank_mask:0xf
	v_mov_b32_dpp v73, v236 row_newbcast:15 row_mask:0xf bank_mask:0xf
	v_mov_b32_dpp v80, v236 row_newbcast:12 row_mask:0xf bank_mask:0xf
	v_mov_b32_dpp v81, v236 row_newbcast:13 row_mask:0xf bank_mask:0xf
	v_mov_b32_dpp v74, v237 row_newbcast:14 row_mask:0xf bank_mask:0xf
	v_mov_b32_dpp v75, v237 row_newbcast:15 row_mask:0xf bank_mask:0xf
	v_mov_b32_dpp v82, v237 row_newbcast:12 row_mask:0xf bank_mask:0xf
	v_mov_b32_dpp v83, v237 row_newbcast:13 row_mask:0xf bank_mask:0xf
.LBB0_476:
	v_sub_f32_e32 v77, v101, v134
	v_sub_f32_e32 v76, v100, v134
	v_sub_f32_e32 v79, v103, v134
	v_sub_f32_e32 v78, v102, v134
	v_mov_b32_e32 v84, v132
	v_mov_b32_e32 v85, v132
	v_pk_mul_f32 v[78:79], v[84:85], v[78:79]
	v_pk_mul_f32 v[76:77], v[132:133], v[76:77]
	v_pk_fma_f32 v[78:79], v[78:79], v[72:73], v[74:75]
	v_pk_fma_f32 v[76:77], v[76:77], v[80:81], v[82:83]
	v_pk_fma_f32 v[70:71], v[70:71], 0.5, v[78:79] op_sel_hi:[1,0,1]
	v_pk_fma_f32 v[68:69], v[68:69], 0.5, v[76:77] op_sel_hi:[1,0,1]
	global_store_dwordx4 v[92:93], v[68:71], off offset:576
	v_mov_b32_e32 v76, v128
	v_mov_b32_e32 v77, v128
	s_waitcnt vmcnt(7)
	v_sub_f32_e32 v69, v97, v130
	v_sub_f32_e32 v68, v96, v130
	v_sub_f32_e32 v71, v99, v130
	v_sub_f32_e32 v70, v98, v130
	v_pk_mul_f32 v[70:71], v[76:77], v[70:71]
	v_pk_mul_f32 v[68:69], v[128:129], v[68:69]
	v_pk_fma_f32 v[70:71], v[70:71], v[72:73], v[74:75]
	v_pk_fma_f32 v[68:69], v[68:69], v[80:81], v[82:83]
	v_pk_fma_f32 v[66:67], v[66:67], 0.5, v[70:71] op_sel_hi:[1,0,1]
	v_pk_fma_f32 v[64:65], v[64:65], 0.5, v[68:69] op_sel_hi:[1,0,1]
	global_store_dwordx4 v[88:89], v[64:67], off offset:576
	v_mov_b32_e32 v96, 1.0
	v_mov_b32_e32 v98, 0
	v_add_u32_e32 v64, 0x80, v168
	v_ashrrev_i32_e32 v65, 31, v64
	s_and_b64 vcc, exec, s[44:45]
	v_mov_b32_e32 v102, 0
	v_mov_b32_e32 v100, 1.0
	v_mov_b32_e32 v103, 1.0
	s_cbranch_vccnz .LBB0_478
	v_lshl_add_u64 v[66:67], v[64:65], 3, s[4:5]
	global_load_dwordx2 v[102:103], v[66:67], off
.LBB0_478:
	v_lshlrev_b64 v[108:109], 12, v[64:65]
	v_lshl_add_u64 v[64:65], v[170:171], 0, v[108:109]
	global_load_dwordx4 v[92:95], v[64:65], off
	global_load_dwordx4 v[84:87], v[64:65], off offset:64
	global_load_dwordx4 v[76:79], v[64:65], off offset:512
	global_load_dwordx4 v[68:71], v[64:65], off offset:576
	v_add_u32_e32 v64, 0x90, v168
	s_and_b64 vcc, exec, s[44:45]
	v_ashrrev_i32_e32 v65, 31, v64
	v_mov_b32_e32 v99, 1.0
	s_cbranch_vccnz .LBB0_480
	v_lshl_add_u64 v[66:67], v[64:65], 3, s[4:5]
	global_load_dwordx2 v[98:99], v[66:67], off
.LBB0_480:
	v_lshlrev_b64 v[110:111], 12, v[64:65]
	v_lshl_add_u64 v[64:65], v[170:171], 0, v[110:111]
	global_load_dwordx4 v[88:91], v[64:65], off
	global_load_dwordx4 v[80:83], v[64:65], off offset:64
	global_load_dwordx4 v[72:75], v[64:65], off offset:512
	s_nop 0
	global_load_dwordx4 v[64:67], v[64:65], off offset:576
	v_mov_b32_e32 v106, 0
	v_mov_b32_e32 v104, 0x3fd744fd
	s_and_b64 vcc, exec, s[44:45]
	v_mov_b32_e32 v114, 0x3fd744fd
	v_mov_b32_e32 v115, 0x3fd744fd
	v_mov_b32_e32 v112, 0x3fd744fd
	v_mov_b32_e32 v113, 0x3fd744fd
	v_mov_b32_e32 v118, 0
	v_mov_b32_e32 v119, 0
	v_mov_b32_e32 v116, 0
	v_mov_b32_e32 v117, 0
	s_cbranch_vccnz .LBB0_482
	v_mov_b32_dpp v112, v236 row_newbcast:2 row_mask:0xf bank_mask:0xf
	v_mov_b32_dpp v113, v236 row_newbcast:3 row_mask:0xf bank_mask:0xf
	v_mov_b32_dpp v114, v236 row_newbcast:0 row_mask:0xf bank_mask:0xf
	v_mov_b32_dpp v115, v236 row_newbcast:1 row_mask:0xf bank_mask:0xf
	v_mov_b32_dpp v116, v237 row_newbcast:2 row_mask:0xf bank_mask:0xf
	v_mov_b32_dpp v117, v237 row_newbcast:3 row_mask:0xf bank_mask:0xf
	v_mov_b32_dpp v118, v237 row_newbcast:0 row_mask:0xf bank_mask:0xf
	v_mov_b32_dpp v119, v237 row_newbcast:1 row_mask:0xf bank_mask:0xf
;     __device__ __forceinline__ void operator()(const Acc& acc, const Unit& u, int wr, int wc, int fr, int fq) const {
;     ...
;                 for (int mm = 0; mm < 2; ++mm) { const int row = row0 + ai * HALF + (2 * mh + mm) * 16; const size_t off = (size_t)row * D + col0;
;                     sv[mm] = st ? st[row] : (f32x2){0.f, 1.f};
; #pragma unroll
;                     for (int bj = 0; bj < 2; ++bj)
; #pragma unroll
;                         for (int n = 0; n < 2; ++n) pre[mm][bj][n] = *(const f32x4*)(base + off + bj * HALF + n * 16); }
;                 asm volatile("" ::: "memory");
; #pragma unroll
;                 for (int bj = 0; bj < 2; ++bj)
; #pragma unroll
;                     for (int n = 0; n < 2; ++n) { f32x4 gv = (f32x4){ALPHA, ALPHA, ALPHA, ALPHA}, bv = (f32x4){0.f, 0.f, 0.f, 0.f};
;                         if (st) { gv = *(const f32x4*)(g + col0 + bj * HALF + n * 16) * ALPHA; bv = *(const f32x4*)(b + col0 + bj * HALF + n * 16) * ALPHA; }
; #pragma unroll
;                         for (int mm = 0; mm < 2; ++mm) { const int m = 2 * mh + mm; const size_t off = (size_t)(row0 + ai * HALF + m * 16) * D + col0;
;                             *(f32x4*)(out + off + bj * HALF + n * 16) = ((pre[mm][bj][n] - sv[mm].x) * sv[mm].y) * gv + bv + acc[ai][bj][m][n] * scale; } }
.LBB0_482:
	s_waitcnt vmcnt(7)
	v_mov_b32_e32 v100, v103
	v_sub_f32_e32 v95, v95, v102
	v_sub_f32_e32 v94, v94, v102
	v_pk_mul_f32 v[94:95], v[100:101], v[94:95] op_sel_hi:[0,1]
	v_pk_fma_f32 v[94:95], v[94:95], v[112:113], v[116:117]
	v_sub_f32_e32 v93, v93, v102
	v_sub_f32_e32 v92, v92, v102
	v_pk_fma_f32 v[94:95], v[62:63], 0.5, v[94:95] op_sel_hi:[1,0,1]
	s_waitcnt vmcnt(3)
	v_mov_b32_e32 v96, v99
	v_sub_f32_e32 v63, v89, v98
	v_sub_f32_e32 v62, v88, v98
	v_sub_f32_e32 v89, v91, v98
	v_sub_f32_e32 v88, v90, v98
	v_pk_mul_f32 v[92:93], v[100:101], v[92:93] op_sel_hi:[0,1]
	v_pk_mul_f32 v[88:89], v[96:97], v[88:89] op_sel_hi:[0,1]
	v_pk_mul_f32 v[62:63], v[96:97], v[62:63] op_sel_hi:[0,1]
	v_pk_fma_f32 v[92:93], v[92:93], v[114:115], v[118:119]
	v_pk_fma_f32 v[62:63], v[62:63], v[114:115], v[118:119]
	v_pk_fma_f32 v[88:89], v[88:89], v[112:113], v[116:117]
	v_pk_fma_f32 v[92:93], v[60:61], 0.5, v[92:93] op_sel_hi:[1,0,1]
	v_lshl_add_u64 v[60:61], s[84:85], 0, v[108:109]
	v_pk_fma_f32 v[90:91], v[58:59], 0.5, v[88:89] op_sel_hi:[1,0,1]
	v_pk_fma_f32 v[88:89], v[56:57], 0.5, v[62:63] op_sel_hi:[1,0,1]
	v_lshl_add_u64 v[56:57], s[84:85], 0, v[110:111]
	v_lshl_add_u64 v[60:61], v[60:61], 0, v[166:167]
	v_lshl_add_u64 v[56:57], v[56:57], 0, v[166:167]
	global_store_dwordx4 v[60:61], v[92:95], off
	global_store_dwordx4 v[56:57], v[88:91], off
	s_and_b64 vcc, exec, s[44:45]
	v_mov_b32_e32 v105, 0x3fd744fd
	v_mov_b32_e32 v62, 0x3fd744fd
	v_mov_b32_e32 v63, 0x3fd744fd
	v_mov_b32_e32 v107, 0
	v_mov_b32_e32 v88, 0
	v_mov_b32_e32 v89, 0
	s_cbranch_vccnz .LBB0_484
	v_mov_b32_dpp v62, v236 row_newbcast:6 row_mask:0xf bank_mask:0xf
	v_mov_b32_dpp v63, v236 row_newbcast:7 row_mask:0xf bank_mask:0xf
	v_mov_b32_dpp v104, v236 row_newbcast:4 row_mask:0xf bank_mask:0xf
	v_mov_b32_dpp v105, v236 row_newbcast:5 row_mask:0xf bank_mask:0xf
	v_mov_b32_dpp v88, v237 row_newbcast:6 row_mask:0xf bank_mask:0xf
	v_mov_b32_dpp v89, v237 row_newbcast:7 row_mask:0xf bank_mask:0xf
	v_mov_b32_dpp v106, v237 row_newbcast:4 row_mask:0xf bank_mask:0xf
	v_mov_b32_dpp v107, v237 row_newbcast:5 row_mask:0xf bank_mask:0xf
.LBB0_484:
	v_mov_b32_e32 v101, v100
	v_sub_f32_e32 v85, v85, v102
	v_sub_f32_e32 v84, v84, v102
	v_sub_f32_e32 v87, v87, v102
	v_sub_f32_e32 v86, v86, v102
	v_mov_b32_e32 v58, v100
	v_mov_b32_e32 v59, v100
	v_pk_mul_f32 v[86:87], v[58:59], v[86:87]
	v_pk_mul_f32 v[84:85], v[100:101], v[84:85]
	v_pk_fma_f32 v[86:87], v[86:87], v[62:63], v[88:89]
	v_pk_fma_f32 v[84:85], v[84:85], v[104:105], v[106:107]
	v_pk_fma_f32 v[54:55], v[54:55], 0.5, v[86:87] op_sel_hi:[1,0,1]
	v_pk_fma_f32 v[52:53], v[52:53], 0.5, v[84:85] op_sel_hi:[1,0,1]
	v_mov_b32_e32 v97, v96
	global_store_dwordx4 v[60:61], v[52:55], off offset:64
	s_and_b64 vcc, exec, s[44:45]
	s_waitcnt vmcnt(5)
	v_sub_f32_e32 v55, v81, v98
	v_sub_f32_e32 v54, v80, v98
	v_sub_f32_e32 v81, v83, v98
	v_sub_f32_e32 v80, v82, v98
	v_mov_b32_e32 v52, v96
	v_mov_b32_e32 v53, v96
	v_pk_mul_f32 v[80:81], v[52:53], v[80:81]
	v_pk_mul_f32 v[54:55], v[96:97], v[54:55]
	v_pk_fma_f32 v[62:63], v[80:81], v[62:63], v[88:89]
	v_pk_fma_f32 v[54:55], v[54:55], v[104:105], v[106:107]
	v_pk_fma_f32 v[50:51], v[50:51], 0.5, v[62:63] op_sel_hi:[1,0,1]
	v_pk_fma_f32 v[48:49], v[48:49], 0.5, v[54:55] op_sel_hi:[1,0,1]
	global_store_dwordx4 v[56:57], v[48:51], off offset:64
	v_mov_b32_e32 v62, 0x3fd744fd
	v_mov_b32_e32 v63, 0x3fd744fd
	v_mov_b32_e32 v50, 0
	v_mov_b32_e32 v48, 0x3fd744fd
	v_mov_b32_e32 v54, 0x3fd744fd
	v_mov_b32_e32 v55, 0x3fd744fd
	v_mov_b32_e32 v82, 0
	v_mov_b32_e32 v83, 0
	v_mov_b32_e32 v80, 0
	v_mov_b32_e32 v81, 0
	s_cbranch_vccnz .LBB0_486
	v_mov_b32_dpp v54, v236 row_newbcast:10 row_mask:0xf bank_mask:0xf
	v_mov_b32_dpp v55, v236 row_newbcast:11 row_mask:0xf bank_mask:0xf
	v_mov_b32_dpp v62, v236 row_newbcast:8 row_mask:0xf bank_mask:0xf
	v_mov_b32_dpp v63, v236 row_newbcast:9 row_mask:0xf bank_mask:0xf
	v_mov_b32_dpp v80, v237 row_newbcast:10 row_mask:0xf bank_mask:0xf
	v_mov_b32_dpp v81, v237 row_newbcast:11 row_mask:0xf bank_mask:0xf
	v_mov_b32_dpp v82, v237 row_newbcast:8 row_mask:0xf bank_mask:0xf
	v_mov_b32_dpp v83, v237 row_newbcast:9 row_mask:0xf bank_mask:0xf
.LBB0_486:
	v_sub_f32_e32 v77, v77, v102
	v_sub_f32_e32 v76, v76, v102
	v_sub_f32_e32 v79, v79, v102
	v_sub_f32_e32 v78, v78, v102
	v_pk_mul_f32 v[58:59], v[58:59], v[78:79]
	v_pk_mul_f32 v[76:77], v[100:101], v[76:77]
	v_pk_fma_f32 v[58:59], v[58:59], v[54:55], v[80:81]
	v_pk_fma_f32 v[76:77], v[76:77], v[62:63], v[82:83]
	v_pk_fma_f32 v[46:47], v[46:47], 0.5, v[58:59] op_sel_hi:[1,0,1]
	v_pk_fma_f32 v[44:45], v[44:45], 0.5, v[76:77] op_sel_hi:[1,0,1]
	global_store_dwordx4 v[60:61], v[44:47], off offset:512
	s_and_b64 vcc, exec, s[44:45]
	v_mov_b32_e32 v49, 0x3fd744fd
	s_waitcnt vmcnt(6)
	v_sub_f32_e32 v45, v73, v98
	v_sub_f32_e32 v44, v72, v98
	v_sub_f32_e32 v47, v75, v98
	v_sub_f32_e32 v46, v74, v98
	v_pk_mul_f32 v[46:47], v[52:53], v[46:47]
	v_pk_mul_f32 v[44:45], v[96:97], v[44:45]
	v_pk_fma_f32 v[46:47], v[46:47], v[54:55], v[80:81]
	v_pk_fma_f32 v[44:45], v[44:45], v[62:63], v[82:83]
	v_pk_fma_f32 v[42:43], v[42:43], 0.5, v[46:47] op_sel_hi:[1,0,1]
	v_pk_fma_f32 v[40:41], v[40:41], 0.5, v[44:45] op_sel_hi:[1,0,1]
	global_store_dwordx4 v[56:57], v[40:43], off offset:512
	v_mov_b32_e32 v51, 0
	s_nop 0
	v_mov_b32_e32 v40, 0x3fd744fd
	v_mov_b32_e32 v41, 0x3fd744fd
	v_mov_b32_e32 v42, 0
	v_mov_b32_e32 v43, 0
	s_cbranch_vccnz .LBB0_488
	v_mov_b32_dpp v40, v236 row_newbcast:14 row_mask:0xf bank_mask:0xf
	v_mov_b32_dpp v41, v236 row_newbcast:15 row_mask:0xf bank_mask:0xf
	v_mov_b32_dpp v48, v236 row_newbcast:12 row_mask:0xf bank_mask:0xf
	v_mov_b32_dpp v49, v236 row_newbcast:13 row_mask:0xf bank_mask:0xf
	v_mov_b32_dpp v42, v237 row_newbcast:14 row_mask:0xf bank_mask:0xf
	v_mov_b32_dpp v43, v237 row_newbcast:15 row_mask:0xf bank_mask:0xf
	v_mov_b32_dpp v50, v237 row_newbcast:12 row_mask:0xf bank_mask:0xf
	v_mov_b32_dpp v51, v237 row_newbcast:13 row_mask:0xf bank_mask:0xf
;     __device__ __forceinline__ void operator()(const Acc& acc, const Unit& u, int wr, int wc, int fr, int fq) const {
;     ...
;                 for (int mm = 0; mm < 2; ++mm) { const int row = row0 + ai * HALF + (2 * mh + mm) * 16; const size_t off = (size_t)row * D + col0;
;                     sv[mm] = st ? st[row] : (f32x2){0.f, 1.f};
; #pragma unroll
;                     for (int bj = 0; bj < 2; ++bj)
; #pragma unroll
;                         for (int n = 0; n < 2; ++n) pre[mm][bj][n] = *(const f32x4*)(base + off + bj * HALF + n * 16); }
;                 asm volatile("" ::: "memory");
; #pragma unroll
;                 for (int bj = 0; bj < 2; ++bj)
; #pragma unroll
;                     for (int n = 0; n < 2; ++n) { f32x4 gv = (f32x4){ALPHA, ALPHA, ALPHA, ALPHA}, bv = (f32x4){0.f, 0.f, 0.f, 0.f};
;                         if (st) { gv = *(const f32x4*)(g + col0 + bj * HALF + n * 16) * ALPHA; bv = *(const f32x4*)(b + col0 + bj * HALF + n * 16) * ALPHA; }
; #pragma unroll
;                         for (int mm = 0; mm < 2; ++mm) { const int m = 2 * mh + mm; const size_t off = (size_t)(row0 + ai * HALF + m * 16) * D + col0;
;                             *(f32x4*)(out + off + bj * HALF + n * 16) = ((pre[mm][bj][n] - sv[mm].x) * sv[mm].y) * gv + bv + acc[ai][bj][m][n] * scale; } }
.LBB0_488:
	v_sub_f32_e32 v45, v69, v102
	v_sub_f32_e32 v44, v68, v102
	v_sub_f32_e32 v47, v71, v102
	v_sub_f32_e32 v46, v70, v102
	v_mov_b32_e32 v52, v100
	v_mov_b32_e32 v53, v100
	v_pk_mul_f32 v[46:47], v[52:53], v[46:47]
	v_pk_mul_f32 v[44:45], v[100:101], v[44:45]
	v_pk_fma_f32 v[46:47], v[46:47], v[40:41], v[42:43]
	v_pk_fma_f32 v[44:45], v[44:45], v[48:49], v[50:51]
	v_pk_fma_f32 v[38:39], v[38:39], 0.5, v[46:47] op_sel_hi:[1,0,1]
	v_pk_fma_f32 v[36:37], v[36:37], 0.5, v[44:45] op_sel_hi:[1,0,1]
	global_store_dwordx4 v[60:61], v[36:39], off offset:576
	v_mov_b32_e32 v44, v96
	v_mov_b32_e32 v45, v96
	s_waitcnt vmcnt(7)
	v_sub_f32_e32 v37, v65, v98
	v_sub_f32_e32 v36, v64, v98
	v_sub_f32_e32 v39, v67, v98
	v_sub_f32_e32 v38, v66, v98
	v_pk_mul_f32 v[38:39], v[44:45], v[38:39]
	v_pk_mul_f32 v[36:37], v[96:97], v[36:37]
	v_pk_fma_f32 v[38:39], v[38:39], v[40:41], v[42:43]
	v_pk_fma_f32 v[36:37], v[36:37], v[48:49], v[50:51]
	v_pk_fma_f32 v[34:35], v[34:35], 0.5, v[38:39] op_sel_hi:[1,0,1]
	v_pk_fma_f32 v[32:33], v[32:33], 0.5, v[36:37] op_sel_hi:[1,0,1]
	global_store_dwordx4 v[56:57], v[32:35], off offset:576
	v_mov_b32_e32 v64, 1.0
	v_mov_b32_e32 v66, 0
	v_add_u32_e32 v32, 0xa0, v168
	v_ashrrev_i32_e32 v33, 31, v32
	s_and_b64 vcc, exec, s[44:45]
	v_mov_b32_e32 v70, 0
	v_mov_b32_e32 v68, 1.0
	v_mov_b32_e32 v71, 1.0
	s_cbranch_vccnz .LBB0_490
	v_lshl_add_u64 v[34:35], v[32:33], 3, s[4:5]
	global_load_dwordx2 v[70:71], v[34:35], off
.LBB0_490:
	v_lshlrev_b64 v[76:77], 12, v[32:33]
	v_lshl_add_u64 v[32:33], v[170:171], 0, v[76:77]
	global_load_dwordx4 v[60:63], v[32:33], off
	global_load_dwordx4 v[52:55], v[32:33], off offset:64
	global_load_dwordx4 v[44:47], v[32:33], off offset:512
	global_load_dwordx4 v[36:39], v[32:33], off offset:576
	v_add_u32_e32 v32, 0xb0, v168
	s_and_b64 vcc, exec, s[44:45]
	v_ashrrev_i32_e32 v33, 31, v32
	v_mov_b32_e32 v67, 1.0
	s_cbranch_vccnz .LBB0_492
	v_lshl_add_u64 v[34:35], v[32:33], 3, s[4:5]
	global_load_dwordx2 v[66:67], v[34:35], off
.LBB0_492:
	v_lshlrev_b64 v[78:79], 12, v[32:33]
	v_lshl_add_u64 v[32:33], v[170:171], 0, v[78:79]
	global_load_dwordx4 v[56:59], v[32:33], off
	global_load_dwordx4 v[48:51], v[32:33], off offset:64
	global_load_dwordx4 v[40:43], v[32:33], off offset:512
	s_nop 0
	global_load_dwordx4 v[32:35], v[32:33], off offset:576
	v_mov_b32_e32 v74, 0
	v_mov_b32_e32 v72, 0x3fd744fd
	s_and_b64 vcc, exec, s[44:45]
	v_mov_b32_e32 v82, 0x3fd744fd
	v_mov_b32_e32 v83, 0x3fd744fd
	v_mov_b32_e32 v80, 0x3fd744fd
	v_mov_b32_e32 v81, 0x3fd744fd
	v_mov_b32_e32 v86, 0
	v_mov_b32_e32 v87, 0
	v_mov_b32_e32 v84, 0
	v_mov_b32_e32 v85, 0
	s_cbranch_vccnz .LBB0_494
	v_mov_b32_dpp v80, v236 row_newbcast:2 row_mask:0xf bank_mask:0xf
	v_mov_b32_dpp v81, v236 row_newbcast:3 row_mask:0xf bank_mask:0xf
	v_mov_b32_dpp v82, v236 row_newbcast:0 row_mask:0xf bank_mask:0xf
	v_mov_b32_dpp v83, v236 row_newbcast:1 row_mask:0xf bank_mask:0xf
	v_mov_b32_dpp v84, v237 row_newbcast:2 row_mask:0xf bank_mask:0xf
	v_mov_b32_dpp v85, v237 row_newbcast:3 row_mask:0xf bank_mask:0xf
	v_mov_b32_dpp v86, v237 row_newbcast:0 row_mask:0xf bank_mask:0xf
	v_mov_b32_dpp v87, v237 row_newbcast:1 row_mask:0xf bank_mask:0xf
.LBB0_494:
	s_waitcnt vmcnt(7)
	v_mov_b32_e32 v68, v71
	v_sub_f32_e32 v63, v63, v70
	v_sub_f32_e32 v62, v62, v70
	v_pk_mul_f32 v[62:63], v[68:69], v[62:63] op_sel_hi:[0,1]
	v_pk_fma_f32 v[62:63], v[62:63], v[80:81], v[84:85]
	v_sub_f32_e32 v61, v61, v70
	v_sub_f32_e32 v60, v60, v70
	v_pk_fma_f32 v[62:63], v[30:31], 0.5, v[62:63] op_sel_hi:[1,0,1]
	s_waitcnt vmcnt(3)
	v_mov_b32_e32 v64, v67
	v_sub_f32_e32 v31, v57, v66
	v_sub_f32_e32 v30, v56, v66
	v_sub_f32_e32 v57, v59, v66
	v_sub_f32_e32 v56, v58, v66
	v_pk_mul_f32 v[60:61], v[68:69], v[60:61] op_sel_hi:[0,1]
	v_pk_mul_f32 v[56:57], v[64:65], v[56:57] op_sel_hi:[0,1]
	v_pk_mul_f32 v[30:31], v[64:65], v[30:31] op_sel_hi:[0,1]
	v_pk_fma_f32 v[60:61], v[60:61], v[82:83], v[86:87]
	v_pk_fma_f32 v[30:31], v[30:31], v[82:83], v[86:87]
	v_pk_fma_f32 v[56:57], v[56:57], v[80:81], v[84:85]
	v_pk_fma_f32 v[60:61], v[28:29], 0.5, v[60:61] op_sel_hi:[1,0,1]
	v_lshl_add_u64 v[28:29], s[84:85], 0, v[76:77]
	v_pk_fma_f32 v[58:59], v[26:27], 0.5, v[56:57] op_sel_hi:[1,0,1]
	v_pk_fma_f32 v[56:57], v[24:25], 0.5, v[30:31] op_sel_hi:[1,0,1]
	v_lshl_add_u64 v[24:25], s[84:85], 0, v[78:79]
	v_lshl_add_u64 v[28:29], v[28:29], 0, v[166:167]
	v_lshl_add_u64 v[24:25], v[24:25], 0, v[166:167]
	global_store_dwordx4 v[28:29], v[60:63], off
	global_store_dwordx4 v[24:25], v[56:59], off
	s_and_b64 vcc, exec, s[44:45]
	v_mov_b32_e32 v73, 0x3fd744fd
	v_mov_b32_e32 v30, 0x3fd744fd
	v_mov_b32_e32 v31, 0x3fd744fd
	v_mov_b32_e32 v75, 0
	v_mov_b32_e32 v56, 0
	v_mov_b32_e32 v57, 0
	s_cbranch_vccnz .LBB0_496
	v_mov_b32_dpp v30, v236 row_newbcast:6 row_mask:0xf bank_mask:0xf
	v_mov_b32_dpp v31, v236 row_newbcast:7 row_mask:0xf bank_mask:0xf
	v_mov_b32_dpp v72, v236 row_newbcast:4 row_mask:0xf bank_mask:0xf
	v_mov_b32_dpp v73, v236 row_newbcast:5 row_mask:0xf bank_mask:0xf
	v_mov_b32_dpp v56, v237 row_newbcast:6 row_mask:0xf bank_mask:0xf
	v_mov_b32_dpp v57, v237 row_newbcast:7 row_mask:0xf bank_mask:0xf
	v_mov_b32_dpp v74, v237 row_newbcast:4 row_mask:0xf bank_mask:0xf
	v_mov_b32_dpp v75, v237 row_newbcast:5 row_mask:0xf bank_mask:0xf
;     __device__ __forceinline__ void operator()(const Acc& acc, const Unit& u, int wr, int wc, int fr, int fq) const {
;     ...
; #pragma unroll
;                 for (int bj = 0; bj < 2; ++bj)
; #pragma unroll
;                     for (int n = 0; n < 2; ++n) { f32x4 gv = (f32x4){ALPHA, ALPHA, ALPHA, ALPHA}, bv = (f32x4){0.f, 0.f, 0.f, 0.f};
;                         if (st) { gv = *(const f32x4*)(g + col0 + bj * HALF + n * 16) * ALPHA; bv = *(const f32x4*)(b + col0 + bj * HALF + n * 16) * ALPHA; }
; #pragma unroll
;                         for (int mm = 0; mm < 2; ++mm) { const int m = 2 * mh + mm; const size_t off = (size_t)(row0 + ai * HALF + m * 16) * D + col0;
;                             *(f32x4*)(out + off + bj * HALF + n * 16) = ((pre[mm][bj][n] - sv[mm].x) * sv[mm].y) * gv + bv + acc[ai][bj][m][n] * scale; } }
;                 asm volatile("" ::: "memory");
.LBB0_496:
	v_mov_b32_e32 v69, v68
	v_sub_f32_e32 v53, v53, v70
	v_sub_f32_e32 v52, v52, v70
	v_sub_f32_e32 v55, v55, v70
	v_sub_f32_e32 v54, v54, v70
	v_mov_b32_e32 v26, v68
	v_mov_b32_e32 v27, v68
	v_pk_mul_f32 v[54:55], v[26:27], v[54:55]
	v_pk_mul_f32 v[52:53], v[68:69], v[52:53]
	v_pk_fma_f32 v[54:55], v[54:55], v[30:31], v[56:57]
	v_pk_fma_f32 v[52:53], v[52:53], v[72:73], v[74:75]
	v_pk_fma_f32 v[22:23], v[22:23], 0.5, v[54:55] op_sel_hi:[1,0,1]
	v_pk_fma_f32 v[20:21], v[20:21], 0.5, v[52:53] op_sel_hi:[1,0,1]
	v_mov_b32_e32 v65, v64
	global_store_dwordx4 v[28:29], v[20:23], off offset:64
	s_and_b64 vcc, exec, s[44:45]
	s_waitcnt vmcnt(5)
	v_sub_f32_e32 v23, v49, v66
	v_sub_f32_e32 v22, v48, v66
	v_sub_f32_e32 v49, v51, v66
	v_sub_f32_e32 v48, v50, v66
	v_mov_b32_e32 v20, v64
	v_mov_b32_e32 v21, v64
	v_pk_mul_f32 v[48:49], v[20:21], v[48:49]
	v_pk_mul_f32 v[22:23], v[64:65], v[22:23]
	v_pk_fma_f32 v[30:31], v[48:49], v[30:31], v[56:57]
	v_pk_fma_f32 v[22:23], v[22:23], v[72:73], v[74:75]
	v_pk_fma_f32 v[18:19], v[18:19], 0.5, v[30:31] op_sel_hi:[1,0,1]
	v_pk_fma_f32 v[16:17], v[16:17], 0.5, v[22:23] op_sel_hi:[1,0,1]
	global_store_dwordx4 v[24:25], v[16:19], off offset:64
	v_mov_b32_e32 v30, 0x3fd744fd
	v_mov_b32_e32 v31, 0x3fd744fd
	v_mov_b32_e32 v18, 0
	v_mov_b32_e32 v16, 0x3fd744fd
	v_mov_b32_e32 v22, 0x3fd744fd
	v_mov_b32_e32 v23, 0x3fd744fd
	v_mov_b32_e32 v50, 0
	v_mov_b32_e32 v51, 0
	v_mov_b32_e32 v48, 0
	v_mov_b32_e32 v49, 0
	s_cbranch_vccnz .LBB0_498
	v_mov_b32_dpp v22, v236 row_newbcast:10 row_mask:0xf bank_mask:0xf
	v_mov_b32_dpp v23, v236 row_newbcast:11 row_mask:0xf bank_mask:0xf
	v_mov_b32_dpp v30, v236 row_newbcast:8 row_mask:0xf bank_mask:0xf
	v_mov_b32_dpp v31, v236 row_newbcast:9 row_mask:0xf bank_mask:0xf
	v_mov_b32_dpp v48, v237 row_newbcast:10 row_mask:0xf bank_mask:0xf
	v_mov_b32_dpp v49, v237 row_newbcast:11 row_mask:0xf bank_mask:0xf
	v_mov_b32_dpp v50, v237 row_newbcast:8 row_mask:0xf bank_mask:0xf
	v_mov_b32_dpp v51, v237 row_newbcast:9 row_mask:0xf bank_mask:0xf
.LBB0_498:
	v_sub_f32_e32 v45, v45, v70
	v_sub_f32_e32 v44, v44, v70
	v_sub_f32_e32 v47, v47, v70
	v_sub_f32_e32 v46, v46, v70
	v_pk_mul_f32 v[26:27], v[26:27], v[46:47]
	v_pk_mul_f32 v[44:45], v[68:69], v[44:45]
	v_pk_fma_f32 v[26:27], v[26:27], v[22:23], v[48:49]
	v_pk_fma_f32 v[44:45], v[44:45], v[30:31], v[50:51]
	v_pk_fma_f32 v[14:15], v[14:15], 0.5, v[26:27] op_sel_hi:[1,0,1]
	v_pk_fma_f32 v[12:13], v[12:13], 0.5, v[44:45] op_sel_hi:[1,0,1]
	global_store_dwordx4 v[28:29], v[12:15], off offset:512
	s_and_b64 vcc, exec, s[44:45]
	v_mov_b32_e32 v17, 0x3fd744fd
	s_waitcnt vmcnt(6)
	v_sub_f32_e32 v13, v41, v66
	v_sub_f32_e32 v12, v40, v66
	v_sub_f32_e32 v15, v43, v66
	v_sub_f32_e32 v14, v42, v66
	v_pk_mul_f32 v[14:15], v[20:21], v[14:15]
	v_pk_mul_f32 v[12:13], v[64:65], v[12:13]
	v_pk_fma_f32 v[14:15], v[14:15], v[22:23], v[48:49]
	v_pk_fma_f32 v[12:13], v[12:13], v[30:31], v[50:51]
	v_pk_fma_f32 v[10:11], v[10:11], 0.5, v[14:15] op_sel_hi:[1,0,1]
	v_pk_fma_f32 v[8:9], v[8:9], 0.5, v[12:13] op_sel_hi:[1,0,1]
	global_store_dwordx4 v[24:25], v[8:11], off offset:512
	v_mov_b32_e32 v19, 0
	s_nop 0
	v_mov_b32_e32 v8, 0x3fd744fd
	v_mov_b32_e32 v9, 0x3fd744fd
	v_mov_b32_e32 v10, 0
	v_mov_b32_e32 v11, 0
	s_cbranch_vccnz .LBB0_500
	v_mov_b32_dpp v8, v236 row_newbcast:14 row_mask:0xf bank_mask:0xf
	v_mov_b32_dpp v9, v236 row_newbcast:15 row_mask:0xf bank_mask:0xf
	v_mov_b32_dpp v16, v236 row_newbcast:12 row_mask:0xf bank_mask:0xf
	v_mov_b32_dpp v17, v236 row_newbcast:13 row_mask:0xf bank_mask:0xf
	v_mov_b32_dpp v10, v237 row_newbcast:14 row_mask:0xf bank_mask:0xf
	v_mov_b32_dpp v11, v237 row_newbcast:15 row_mask:0xf bank_mask:0xf
	v_mov_b32_dpp v18, v237 row_newbcast:12 row_mask:0xf bank_mask:0xf
	v_mov_b32_dpp v19, v237 row_newbcast:13 row_mask:0xf bank_mask:0xf

; #define PG8_STAGE(bufoff, gbase, voff) do { _Pragma("unroll") for (int _i = 0; _i < 2; ++_i) \
;         __builtin_amdgcn_global_load_lds((const unsigned*)((const char*)(gbase) + (voff)[_i]), (LAS unsigned*)(lds + (bufoff) + ldsw + _i * 8192), 16, 0, 0); } while (0)
; #define PG8_LDA(dst, b, h) do { _Pragma("unroll") for (int m = 0; m < 4; ++m) _Pragma("unroll") for (int k = 0; k < 2; ++k) dst[m][k] = *(const LAS bf16x8*)(lds + PG8_SA(b, h) + aoff + m * 2048 + k * 1024); } while (0)
; #define PG8_LDB(dst, b, h) do { _Pragma("unroll") for (int n = 0; n < 2; ++n) _Pragma("unroll") for (int k = 0; k < 2; ++k) dst[n][k] = *(const LAS bf16x8*)(lds + PG8_SB(b, h) + boff + n * 2048 + k * 1024); } while (0)
; #define PG8_MMA(ai, bj, At, Bt) do { __builtin_amdgcn_s_setprio(1); _Pragma("unroll") for (int m = 0; m < 4; ++m) _Pragma("unroll") for (int n = 0; n < 2; ++n) _Pragma("unroll") for (int k = 0; k < 2; ++k) \
;         acc[ai][bj][m][n] = __builtin_amdgcn_mfma_f32_16x16x32_bf16(Bt[n][k], At[m][k], acc[ai][bj][m][n], 0, 0, 0); __builtin_amdgcn_s_setprio(0); } while (0)
; #define PG8_WAIT_V(n) asm volatile("s_waitcnt vmcnt(" #n ")" ::: "memory")
; #define PG8_WAIT_L(n) asm volatile("s_waitcnt lgkmcnt(" #n ")" ::: "memory")
; #define PG8_BAR __builtin_amdgcn_s_barrier()
; #define PG8_SCHED __builtin_amdgcn_sched_barrier(0)
; template <class Epi, bool SP2 = true, bool ALIGN_EPI = true>
; __device__ __forceinline__ void gemm_phase(LAS unsigned char* lds, const Gemm g, const StaticOrder& S, const Epi& E, const int tid) {
;     ...
;             if constexpr (SP2) {
;             PG8_LDB(B0, 0, 0); PG8_LDB(B1, 0, 1); PG8_SCHED; PG8_LDA(At, 0, 0); PG8_STAGE(PG8_SA(1, 1), a1 + hstep, voffA);
;             PG8_WAIT_V(8); PG8_WAIT_L(0); PG8_BAR; PG8_MMA(0, 0, At, B0); PG8_MMA(0, 1, At, B1); PG8_BAR; PG8_SCHED;
;             PG8_LDA(At, 0, 1); PG8_STAGE(PG8_SB(0, 0), b2, voffB); PG8_STAGE(PG8_SB(0, 1), b2 + hstep, voffB); PG8_STAGE(PG8_SA(0, 0), a2, voffA);
;             PG8_WAIT_V(8); PG8_WAIT_L(0); PG8_BAR; PG8_MMA(1, 0, At, B0); PG8_MMA(1, 1, At, B1); PG8_BAR; PG8_SCHED;
.LBB0_514:
	s_add_u32 s12, s24, 0xfffc0080
	s_addc_u32 s13, s25, -1
	s_add_i32 s78, 0, 0x10000
	s_cmp_eq_u32 s76, 12
	s_cselect_b32 s29, s49, s13
	s_cselect_b32 s28, s72, s12
	s_cselect_b32 s19, s47, s75
	s_cselect_b32 s18, s73, s74
	s_add_i32 s12, 0, 0x14000
	v_add_u32_e32 v154, s78, v140
	v_add_u32_e32 v170, s12, v140
	ds_read_b128 v[142:145], v154
	ds_read_b128 v[146:149], v154 offset:1024
	ds_read_b128 v[150:153], v154 offset:2048
	ds_read_b128 v[154:157], v154 offset:3072
	ds_read_b128 v[158:161], v170
	ds_read_b128 v[162:165], v170 offset:1024
	ds_read_b128 v[166:169], v170 offset:2048
	ds_read_b128 v[170:173], v170 offset:3072
	s_add_i32 m0, s22, 0xc000
	ds_read_b128 v[174:177], v141
	ds_read_b128 v[178:181], v141 offset:1024
	ds_read_b128 v[182:185], v141 offset:2048
	ds_read_b128 v[186:189], v141 offset:3072
	ds_read_b128 v[206:209], v141 offset:4096
	ds_read_b128 v[210:213], v141 offset:5120
	ds_read_b128 v[214:217], v141 offset:6144
	ds_read_b128 v[218:221], v141 offset:7168
	global_load_lds_dwordx4 v134, s[24:25]
	s_add_i32 m0, s22, 0xe000
	s_nop 0
	global_load_lds_dwordx4 v136, s[24:25]
	s_waitcnt vmcnt(8)
	s_waitcnt lgkmcnt(0)
	s_barrier
	s_setprio 1
	s_waitcnt lgkmcnt(0)
	v_mfma_f32_16x16x32_bf16 v[124:127], v[142:145], v[174:177], v[124:127]
	v_mfma_f32_16x16x32_bf16 v[116:119], v[150:153], v[174:177], v[116:119]
	v_mfma_f32_16x16x32_bf16 v[108:111], v[142:145], v[182:185], v[108:111]
	v_mfma_f32_16x16x32_bf16 v[100:103], v[150:153], v[182:185], v[100:103]
	v_mfma_f32_16x16x32_bf16 v[92:95], v[142:145], v[206:209], v[92:95]
	v_mfma_f32_16x16x32_bf16 v[84:87], v[150:153], v[206:209], v[84:87]
	v_mfma_f32_16x16x32_bf16 v[76:79], v[142:145], v[214:217], v[76:79]
	v_mfma_f32_16x16x32_bf16 v[68:71], v[150:153], v[214:217], v[68:71]
	v_mfma_f32_16x16x32_bf16 v[124:127], v[146:149], v[178:181], v[124:127]
	v_mfma_f32_16x16x32_bf16 v[116:119], v[154:157], v[178:181], v[116:119]
	v_mfma_f32_16x16x32_bf16 v[108:111], v[146:149], v[186:189], v[108:111]
	v_mfma_f32_16x16x32_bf16 v[100:103], v[154:157], v[186:189], v[100:103]
	v_mfma_f32_16x16x32_bf16 v[92:95], v[146:149], v[210:213], v[92:95]
	v_mfma_f32_16x16x32_bf16 v[84:87], v[154:157], v[210:213], v[84:87]
	v_mfma_f32_16x16x32_bf16 v[76:79], v[146:149], v[218:221], v[76:79]
	v_mfma_f32_16x16x32_bf16 v[68:71], v[154:157], v[218:221], v[68:71]
	s_setprio 0
	s_setprio 1
	v_mfma_f32_16x16x32_bf16 v[120:123], v[158:161], v[174:177], v[120:123]
	v_mfma_f32_16x16x32_bf16 v[112:115], v[166:169], v[174:177], v[112:115]
	v_mfma_f32_16x16x32_bf16 v[104:107], v[158:161], v[182:185], v[104:107]
	v_mfma_f32_16x16x32_bf16 v[96:99], v[166:169], v[182:185], v[96:99]
	v_mfma_f32_16x16x32_bf16 v[88:91], v[158:161], v[206:209], v[88:91]
	v_mfma_f32_16x16x32_bf16 v[80:83], v[166:169], v[206:209], v[80:83]
	v_mfma_f32_16x16x32_bf16 v[72:75], v[158:161], v[214:217], v[72:75]
	v_mfma_f32_16x16x32_bf16 v[64:67], v[166:169], v[214:217], v[64:67]
	v_mfma_f32_16x16x32_bf16 v[120:123], v[162:165], v[178:181], v[120:123]
	v_mfma_f32_16x16x32_bf16 v[112:115], v[170:173], v[178:181], v[112:115]
	v_mfma_f32_16x16x32_bf16 v[104:107], v[162:165], v[186:189], v[104:107]
	v_mfma_f32_16x16x32_bf16 v[96:99], v[170:173], v[186:189], v[96:99]
	v_mfma_f32_16x16x32_bf16 v[88:91], v[162:165], v[210:213], v[88:91]
	v_mfma_f32_16x16x32_bf16 v[80:83], v[170:173], v[210:213], v[80:83]
	v_mfma_f32_16x16x32_bf16 v[72:75], v[162:165], v[218:221], v[72:75]
	v_mfma_f32_16x16x32_bf16 v[64:67], v[170:173], v[218:221], v[64:67]
	s_setprio 0
	s_barrier
	s_add_i32 s13, s78, s20
	s_mov_b32 m0, s13
	ds_read_b128 v[174:177], v141 offset:16384
	ds_read_b128 v[178:181], v141 offset:17408
	ds_read_b128 v[182:185], v141 offset:18432
	ds_read_b128 v[186:189], v141 offset:19456
	ds_read_b128 v[206:209], v141 offset:20480
	ds_read_b128 v[210:213], v141 offset:21504
	ds_read_b128 v[214:217], v141 offset:22528
	ds_read_b128 v[218:221], v141 offset:23552
	global_load_lds_dwordx4 v192, s[18:19]
	s_add_i32 m0, s13, 0x2000
	s_add_u32 s92, s18, 0x40000
	s_addc_u32 s93, s19, 0
	s_add_i32 s12, s12, s20
	global_load_lds_dwordx4 v128, s[18:19]
	s_mov_b32 m0, s12
	s_nop 0
	global_load_lds_dwordx4 v192, s[92:93]
	s_add_i32 m0, s12, 0x2000
	s_nop 0
	global_load_lds_dwordx4 v128, s[92:93]
	s_mov_b32 m0, s22
	s_nop 0
	global_load_lds_dwordx4 v132, s[28:29]
	s_mov_b32 m0, s36
	s_nop 0
	global_load_lds_dwordx4 v130, s[28:29]
	s_waitcnt vmcnt(8)
	s_waitcnt lgkmcnt(0)
	s_barrier
	s_setprio 1
	s_waitcnt lgkmcnt(0)
	v_mfma_f32_16x16x32_bf16 v[60:63], v[142:145], v[174:177], v[60:63]
	v_mfma_f32_16x16x32_bf16 v[52:55], v[150:153], v[174:177], v[52:55]
	v_mfma_f32_16x16x32_bf16 v[44:47], v[142:145], v[182:185], v[44:47]
	v_mfma_f32_16x16x32_bf16 v[36:39], v[150:153], v[182:185], v[36:39]
	v_mfma_f32_16x16x32_bf16 v[28:31], v[142:145], v[206:209], v[28:31]
	v_mfma_f32_16x16x32_bf16 v[20:23], v[150:153], v[206:209], v[20:23]
	v_mfma_f32_16x16x32_bf16 v[12:15], v[142:145], v[214:217], v[12:15]
	v_mfma_f32_16x16x32_bf16 v[4:7], v[150:153], v[214:217], v[4:7]
	v_mfma_f32_16x16x32_bf16 v[60:63], v[146:149], v[178:181], v[60:63]
	v_mfma_f32_16x16x32_bf16 v[52:55], v[154:157], v[178:181], v[52:55]
	v_mfma_f32_16x16x32_bf16 v[44:47], v[146:149], v[186:189], v[44:47]
	v_mfma_f32_16x16x32_bf16 v[36:39], v[154:157], v[186:189], v[36:39]
	v_mfma_f32_16x16x32_bf16 v[28:31], v[146:149], v[210:213], v[28:31]
	v_mfma_f32_16x16x32_bf16 v[20:23], v[154:157], v[210:213], v[20:23]
	v_mfma_f32_16x16x32_bf16 v[12:15], v[146:149], v[218:221], v[12:15]
	v_mfma_f32_16x16x32_bf16 v[4:7], v[154:157], v[218:221], v[4:7]
	s_setprio 0
	s_setprio 1
	v_mfma_f32_16x16x32_bf16 v[56:59], v[158:161], v[174:177], v[56:59]
	v_mfma_f32_16x16x32_bf16 v[48:51], v[166:169], v[174:177], v[48:51]
	v_mfma_f32_16x16x32_bf16 v[40:43], v[158:161], v[182:185], v[40:43]
	v_mfma_f32_16x16x32_bf16 v[32:35], v[166:169], v[182:185], v[32:35]
	v_mfma_f32_16x16x32_bf16 v[24:27], v[158:161], v[206:209], v[24:27]
	v_mfma_f32_16x16x32_bf16 v[16:19], v[166:169], v[206:209], v[16:19]
	v_mfma_f32_16x16x32_bf16 v[8:11], v[158:161], v[214:217], v[8:11]
	v_mfma_f32_16x16x32_bf16 v[0:3], v[166:169], v[214:217], v[0:3]
	v_mfma_f32_16x16x32_bf16 v[56:59], v[162:165], v[178:181], v[56:59]
	v_mfma_f32_16x16x32_bf16 v[48:51], v[170:173], v[178:181], v[48:51]
	v_mfma_f32_16x16x32_bf16 v[40:43], v[162:165], v[186:189], v[40:43]
	v_mfma_f32_16x16x32_bf16 v[32:35], v[170:173], v[186:189], v[32:35]
	v_mfma_f32_16x16x32_bf16 v[24:27], v[162:165], v[210:213], v[24:27]
	v_mfma_f32_16x16x32_bf16 v[16:19], v[170:173], v[210:213], v[16:19]
	v_mfma_f32_16x16x32_bf16 v[8:11], v[162:165], v[218:221], v[8:11]
	v_mfma_f32_16x16x32_bf16 v[0:3], v[170:173], v[218:221], v[0:3]
	s_setprio 0
	s_barrier
; #define PG8_STAGE(bufoff, gbase, voff) do { _Pragma("unroll") for (int _i = 0; _i < 2; ++_i) \
;         __builtin_amdgcn_global_load_lds((const unsigned*)((const char*)(gbase) + (voff)[_i]), (LAS unsigned*)(lds + (bufoff) + ldsw + _i * 8192), 16, 0, 0); } while (0)
; #define PG8_LDA(dst, b, h) do { _Pragma("unroll") for (int m = 0; m < 4; ++m) _Pragma("unroll") for (int k = 0; k < 2; ++k) dst[m][k] = *(const LAS bf16x8*)(lds + PG8_SA(b, h) + aoff + m * 2048 + k * 1024); } while (0)
; #define PG8_LDB(dst, b, h) do { _Pragma("unroll") for (int n = 0; n < 2; ++n) _Pragma("unroll") for (int k = 0; k < 2; ++k) dst[n][k] = *(const LAS bf16x8*)(lds + PG8_SB(b, h) + boff + n * 2048 + k * 1024); } while (0)
; #define PG8_MMA(ai, bj, At, Bt) do { __builtin_amdgcn_s_setprio(1); _Pragma("unroll") for (int m = 0; m < 4; ++m) _Pragma("unroll") for (int n = 0; n < 2; ++n) _Pragma("unroll") for (int k = 0; k < 2; ++k) \
;         acc[ai][bj][m][n] = __builtin_amdgcn_mfma_f32_16x16x32_bf16(Bt[n][k], At[m][k], acc[ai][bj][m][n], 0, 0, 0); __builtin_amdgcn_s_setprio(0); } while (0)
; #define PG8_WAIT_V(n) asm volatile("s_waitcnt vmcnt(" #n ")" ::: "memory")
; #define PG8_WAIT_L(n) asm volatile("s_waitcnt lgkmcnt(" #n ")" ::: "memory")
; #define PG8_BAR __builtin_amdgcn_s_barrier()
; #define PG8_SCHED __builtin_amdgcn_sched_barrier(0)
; template <class Epi, bool SP2 = true, bool ALIGN_EPI = true>
; __device__ __forceinline__ void gemm_phase(LAS unsigned char* lds, const Gemm g, const StaticOrder& S, const Epi& E, const int tid) {
;     ...
;             PG8_LDB(B0, 1, 0); PG8_LDB(B1, 1, 1); PG8_SCHED; PG8_LDA(At, 1, 0); PG8_STAGE(PG8_SA(0, 1), a2 + hstep, voffA);
;             PG8_WAIT_V(8); PG8_WAIT_L(0); PG8_BAR; PG8_MMA(0, 0, At, B0); PG8_MMA(0, 1, At, B1); PG8_BAR; PG8_SCHED;
;             PG8_LDA(At, 1, 1); PG8_STAGE(PG8_SB(1, 0), b3, voffB); PG8_STAGE(PG8_SB(1, 1), b3 + hstep, voffB); PG8_STAGE(PG8_SA(1, 0), a3, voffA);
;             PG8_WAIT_V(8); PG8_WAIT_L(0); PG8_BAR; PG8_MMA(1, 0, At, B0); PG8_MMA(1, 1, At, B1); PG8_BAR; PG8_SCHED;
	s_add_i32 s12, 0, 0x18000
	s_add_i32 s13, 0, 0x1c000
	v_add_u32_e32 v154, s12, v140
	v_add_u32_e32 v170, s13, v140
	ds_read_b128 v[142:145], v154
	ds_read_b128 v[146:149], v154 offset:1024
	ds_read_b128 v[150:153], v154 offset:2048
	ds_read_b128 v[154:157], v154 offset:3072
	ds_read_b128 v[158:161], v170
	ds_read_b128 v[162:165], v170 offset:1024
	ds_read_b128 v[166:169], v170 offset:2048
	ds_read_b128 v[170:173], v170 offset:3072
	s_add_u32 s28, s28, 0x40000
	s_addc_u32 s29, s29, 0
	s_mov_b32 m0, s39
	ds_read_b128 v[174:177], v141 offset:32768
	ds_read_b128 v[178:181], v141 offset:33792
	ds_read_b128 v[182:185], v141 offset:34816
	ds_read_b128 v[186:189], v141 offset:35840
	ds_read_b128 v[206:209], v141 offset:36864
	ds_read_b128 v[210:213], v141 offset:37888
	ds_read_b128 v[214:217], v141 offset:38912
	ds_read_b128 v[218:221], v141 offset:39936
	global_load_lds_dwordx4 v132, s[28:29]
	s_mov_b32 m0, s56
	s_nop 0
	global_load_lds_dwordx4 v130, s[28:29]
	s_waitcnt vmcnt(8)
	s_waitcnt lgkmcnt(0)
	s_barrier
	s_setprio 1
	s_waitcnt lgkmcnt(0)
	v_mfma_f32_16x16x32_bf16 v[124:127], v[142:145], v[174:177], v[124:127]
	v_mfma_f32_16x16x32_bf16 v[116:119], v[150:153], v[174:177], v[116:119]
	v_mfma_f32_16x16x32_bf16 v[108:111], v[142:145], v[182:185], v[108:111]
	v_mfma_f32_16x16x32_bf16 v[100:103], v[150:153], v[182:185], v[100:103]
	v_mfma_f32_16x16x32_bf16 v[92:95], v[142:145], v[206:209], v[92:95]
	v_mfma_f32_16x16x32_bf16 v[84:87], v[150:153], v[206:209], v[84:87]
	v_mfma_f32_16x16x32_bf16 v[76:79], v[142:145], v[214:217], v[76:79]
	v_mfma_f32_16x16x32_bf16 v[68:71], v[150:153], v[214:217], v[68:71]
	v_mfma_f32_16x16x32_bf16 v[124:127], v[146:149], v[178:181], v[124:127]
	v_mfma_f32_16x16x32_bf16 v[116:119], v[154:157], v[178:181], v[116:119]
	v_mfma_f32_16x16x32_bf16 v[108:111], v[146:149], v[186:189], v[108:111]
	v_mfma_f32_16x16x32_bf16 v[100:103], v[154:157], v[186:189], v[100:103]
	v_mfma_f32_16x16x32_bf16 v[92:95], v[146:149], v[210:213], v[92:95]
	v_mfma_f32_16x16x32_bf16 v[84:87], v[154:157], v[210:213], v[84:87]
	v_mfma_f32_16x16x32_bf16 v[76:79], v[146:149], v[218:221], v[76:79]
	v_mfma_f32_16x16x32_bf16 v[68:71], v[154:157], v[218:221], v[68:71]
	s_setprio 0
	s_setprio 1
	v_mfma_f32_16x16x32_bf16 v[120:123], v[158:161], v[174:177], v[120:123]
	v_mfma_f32_16x16x32_bf16 v[112:115], v[166:169], v[174:177], v[112:115]
	v_mfma_f32_16x16x32_bf16 v[104:107], v[158:161], v[182:185], v[104:107]
	v_mfma_f32_16x16x32_bf16 v[96:99], v[166:169], v[182:185], v[96:99]
	v_mfma_f32_16x16x32_bf16 v[88:91], v[158:161], v[206:209], v[88:91]
	v_mfma_f32_16x16x32_bf16 v[80:83], v[166:169], v[206:209], v[80:83]
	v_mfma_f32_16x16x32_bf16 v[72:75], v[158:161], v[214:217], v[72:75]
	v_mfma_f32_16x16x32_bf16 v[64:67], v[166:169], v[214:217], v[64:67]
	v_mfma_f32_16x16x32_bf16 v[120:123], v[162:165], v[178:181], v[120:123]
	v_mfma_f32_16x16x32_bf16 v[112:115], v[170:173], v[178:181], v[112:115]
	v_mfma_f32_16x16x32_bf16 v[104:107], v[162:165], v[186:189], v[104:107]
	v_mfma_f32_16x16x32_bf16 v[96:99], v[170:173], v[186:189], v[96:99]
	v_mfma_f32_16x16x32_bf16 v[88:91], v[162:165], v[210:213], v[88:91]
	v_mfma_f32_16x16x32_bf16 v[80:83], v[170:173], v[210:213], v[80:83]
	v_mfma_f32_16x16x32_bf16 v[72:75], v[162:165], v[218:221], v[72:75]
	v_mfma_f32_16x16x32_bf16 v[64:67], v[170:173], v[218:221], v[64:67]
	s_setprio 0
	s_barrier
	s_add_i32 s12, s12, s20
	s_add_u32 s98, s18, 0x80
	s_addc_u32 s99, s19, 0
	s_add_u32 s100, s28, 0xfffc0080
	s_addc_u32 s101, s29, -1
	s_mov_b32 m0, s12
	ds_read_b128 v[174:177], v141 offset:49152
	ds_read_b128 v[178:181], v141 offset:50176
	ds_read_b128 v[182:185], v141 offset:51200
	ds_read_b128 v[186:189], v141 offset:52224
	ds_read_b128 v[206:209], v141 offset:53248
	ds_read_b128 v[210:213], v141 offset:54272
	ds_read_b128 v[214:217], v141 offset:55296
	ds_read_b128 v[218:221], v141 offset:56320
	global_load_lds_dwordx4 v192, s[98:99]
	s_add_i32 m0, s12, 0x2000
	s_add_u32 s18, s18, 0x40080
	s_addc_u32 s19, s19, 0
	s_add_i32 s12, s13, s20
	global_load_lds_dwordx4 v128, s[98:99]
	s_mov_b32 m0, s12
	s_nop 0
	global_load_lds_dwordx4 v192, s[18:19]
	s_add_i32 m0, s12, 0x2000
	s_nop 0
	global_load_lds_dwordx4 v128, s[18:19]
	s_mov_b32 m0, s57
	s_nop 0
	global_load_lds_dwordx4 v132, s[100:101]
	s_mov_b32 m0, s58
	s_nop 0
	global_load_lds_dwordx4 v130, s[100:101]
	s_waitcnt vmcnt(8)
	s_waitcnt lgkmcnt(0)
	s_barrier
	s_setprio 1
	s_waitcnt lgkmcnt(0)
	v_mfma_f32_16x16x32_bf16 v[60:63], v[142:145], v[174:177], v[60:63]
	v_mfma_f32_16x16x32_bf16 v[52:55], v[150:153], v[174:177], v[52:55]
	v_mfma_f32_16x16x32_bf16 v[44:47], v[142:145], v[182:185], v[44:47]
	v_mfma_f32_16x16x32_bf16 v[36:39], v[150:153], v[182:185], v[36:39]
	v_mfma_f32_16x16x32_bf16 v[28:31], v[142:145], v[206:209], v[28:31]
	v_mfma_f32_16x16x32_bf16 v[20:23], v[150:153], v[206:209], v[20:23]
	v_mfma_f32_16x16x32_bf16 v[12:15], v[142:145], v[214:217], v[12:15]
	v_mfma_f32_16x16x32_bf16 v[4:7], v[150:153], v[214:217], v[4:7]
	v_mfma_f32_16x16x32_bf16 v[60:63], v[146:149], v[178:181], v[60:63]
	v_mfma_f32_16x16x32_bf16 v[52:55], v[154:157], v[178:181], v[52:55]
	v_mfma_f32_16x16x32_bf16 v[44:47], v[146:149], v[186:189], v[44:47]
	v_mfma_f32_16x16x32_bf16 v[36:39], v[154:157], v[186:189], v[36:39]
	v_mfma_f32_16x16x32_bf16 v[28:31], v[146:149], v[210:213], v[28:31]
	v_mfma_f32_16x16x32_bf16 v[20:23], v[154:157], v[210:213], v[20:23]
	v_mfma_f32_16x16x32_bf16 v[12:15], v[146:149], v[218:221], v[12:15]
	v_mfma_f32_16x16x32_bf16 v[4:7], v[154:157], v[218:221], v[4:7]
	s_setprio 0
	s_setprio 1
	v_mfma_f32_16x16x32_bf16 v[56:59], v[158:161], v[174:177], v[56:59]
	v_mfma_f32_16x16x32_bf16 v[48:51], v[166:169], v[174:177], v[48:51]
	v_mfma_f32_16x16x32_bf16 v[40:43], v[158:161], v[182:185], v[40:43]
	v_mfma_f32_16x16x32_bf16 v[32:35], v[166:169], v[182:185], v[32:35]
	v_mfma_f32_16x16x32_bf16 v[24:27], v[158:161], v[206:209], v[24:27]
	v_mfma_f32_16x16x32_bf16 v[16:19], v[166:169], v[206:209], v[16:19]
	v_mfma_f32_16x16x32_bf16 v[8:11], v[158:161], v[214:217], v[8:11]
	v_mfma_f32_16x16x32_bf16 v[0:3], v[166:169], v[214:217], v[0:3]
	v_mfma_f32_16x16x32_bf16 v[56:59], v[162:165], v[178:181], v[56:59]
	v_mfma_f32_16x16x32_bf16 v[48:51], v[170:173], v[178:181], v[48:51]
	v_mfma_f32_16x16x32_bf16 v[40:43], v[162:165], v[186:189], v[40:43]
	v_mfma_f32_16x16x32_bf16 v[32:35], v[170:173], v[186:189], v[32:35]
	v_mfma_f32_16x16x32_bf16 v[24:27], v[162:165], v[210:213], v[24:27]
	v_mfma_f32_16x16x32_bf16 v[16:19], v[170:173], v[210:213], v[16:19]
	v_mfma_f32_16x16x32_bf16 v[8:11], v[162:165], v[218:221], v[8:11]
	v_mfma_f32_16x16x32_bf16 v[0:3], v[170:173], v[218:221], v[0:3]
	s_setprio 0
	s_barrier
	s_add_i32 s76, s76, 2
	s_add_u32 s24, s24, 0x100
	s_addc_u32 s25, s25, 0
	s_add_u32 s74, s74, 0x100
	s_addc_u32 s75, s75, 0
	s_cmp_gt_u32 s76, 13
	s_cbranch_scc0 .LBB0_514
	s_and_b64 vcc, exec, s[44:45]
	s_cbranch_vccz .LBB0_517
	s_barrier

; __global__ void __launch_bounds__(512, 2) mk_fwd(Args a) {
;     extern __shared__ __attribute__((aligned(16))) unsigned char lds_raw[];
	.amdhsa_kernel _Z6mk_fwd4Args
		.amdhsa_group_segment_fixed_size 0
		.amdhsa_private_segment_fixed_size 0
		.amdhsa_kernarg_size 560
		.amdhsa_user_sgpr_count 2
		.amdhsa_user_sgpr_dispatch_ptr 0
		.amdhsa_user_sgpr_queue_ptr 0
		.amdhsa_user_sgpr_kernarg_segment_ptr 1
		.amdhsa_user_sgpr_dispatch_id 0
		.amdhsa_user_sgpr_kernarg_preload_length 0
		.amdhsa_user_sgpr_kernarg_preload_offset 0
		.amdhsa_user_sgpr_private_segment_size 0
		.amdhsa_uses_dynamic_stack 0
		.amdhsa_enable_private_segment 0
		.amdhsa_system_sgpr_workgroup_id_x 1
		.amdhsa_system_sgpr_workgroup_id_y 0
		.amdhsa_system_sgpr_workgroup_id_z 0
		.amdhsa_system_sgpr_workgroup_info 0
		.amdhsa_system_vgpr_workitem_id 2
		.amdhsa_next_free_vgpr 252
		.amdhsa_next_free_sgpr 102
		.amdhsa_accum_offset 252
		.amdhsa_reserve_vcc 1
		.amdhsa_float_round_mode_32 0
		.amdhsa_float_round_mode_16_64 0
		.amdhsa_float_denorm_mode_32 3
		.amdhsa_float_denorm_mode_16_64 3
		.amdhsa_dx10_clamp 1
		.amdhsa_ieee_mode 1
		.amdhsa_fp16_overflow 0
		.amdhsa_tg_split 0
		.amdhsa_exception_fp_ieee_invalid_op 0
		.amdhsa_exception_fp_denorm_src 0
		.amdhsa_exception_fp_ieee_div_zero 0
		.amdhsa_exception_fp_ieee_overflow 0
		.amdhsa_exception_fp_ieee_underflow 0
		.amdhsa_exception_fp_ieee_inexact 0
		.amdhsa_exception_int_div_zero 0
	.end_amdhsa_kernel

; __global__ void __launch_bounds__(512, 2) mk_fwd(Args a) {
;     extern __shared__ __attribute__((aligned(16))) unsigned char lds_raw[];
amdhsa.kernels:
  - .agpr_count:     0
    .args:
      - .offset:         0
        .size:           304
        .value_kind:     by_value
      - .offset:         304
        .size:           4
        .value_kind:     hidden_block_count_x
      - .offset:         308
        .size:           4
        .value_kind:     hidden_block_count_y
      - .offset:         312
        .size:           4
        .value_kind:     hidden_block_count_z
      - .offset:         316
        .size:           2
        .value_kind:     hidden_group_size_x
      - .offset:         318
        .size:           2
        .value_kind:     hidden_group_size_y
      - .offset:         320
        .size:           2
        .value_kind:     hidden_group_size_z
      - .offset:         322
        .size:           2
        .value_kind:     hidden_remainder_x
      - .offset:         324
        .size:           2
        .value_kind:     hidden_remainder_y
      - .offset:         326
        .size:           2
        .value_kind:     hidden_remainder_z
      - .offset:         344
        .size:           8
        .value_kind:     hidden_global_offset_x
      - .offset:         352
        .size:           8
        .value_kind:     hidden_global_offset_y
      - .offset:         360
        .size:           8
        .value_kind:     hidden_global_offset_z
      - .offset:         368
        .size:           2
        .value_kind:     hidden_grid_dims
      - .offset:         392
        .size:           8
        .value_kind:     hidden_multigrid_sync_arg
      - .offset:         424
        .size:           4
        .value_kind:     hidden_dynamic_lds_size
    .group_segment_fixed_size: 0
    .kernarg_segment_align: 8
    .kernarg_segment_size: 560
    .language:       OpenCL C
    .language_version:
      - 2
      - 0
    .max_flat_workgroup_size: 512
    .name:           _Z6mk_fwd4Args
    .private_segment_fixed_size: 0
    .sgpr_count:     108
    .sgpr_spill_count: 274
    .symbol:         _Z6mk_fwd4Args.kd
    .uniform_work_group_size: 1
    .uses_dynamic_stack: false
    .vgpr_count:     252
    .vgpr_spill_count: 0
    .wavefront_size: 64
